# byte-phase placement: every 32-MFMA segment of the GEMM K-loops starts 8-byte aligned (s_nop pads before the segment barrier); attention code keeps its placement
# baseline (speedup 1.0000x reference)
; #define PG8_STAGE(bufoff, gbase, voff) do { _Pragma("unroll") for (int _i = 0; _i < 2; ++_i) \
;         __builtin_amdgcn_global_load_lds((const unsigned*)((const char*)(gbase) + (voff)[_i]), (LAS unsigned*)(lds + (bufoff) + ldsw + _i * 8192), 16, 0, 0); } while (0)
; #define PG8_LDA(dst, b, h) do { _Pragma("unroll") for (int m = 0; m < 4; ++m) _Pragma("unroll") for (int k = 0; k < 2; ++k) dst[m][k] = *(const LAS bf16x8*)(lds + PG8_SA(b, h) + aoff + m * 2048 + k * 1024); } while (0)
; #define PG8_LDB(dst, b, h) do { _Pragma("unroll") for (int n = 0; n < 2; ++n) _Pragma("unroll") for (int k = 0; k < 2; ++k) dst[n][k] = *(const LAS bf16x8*)(lds + PG8_SB(b, h) + boff + n * 2048 + k * 1024); } while (0)
; #define PG8_MMA(ai, bj, At, Bt) do { __builtin_amdgcn_s_setprio(1); _Pragma("unroll") for (int m = 0; m < 4; ++m) _Pragma("unroll") for (int n = 0; n < 2; ++n) _Pragma("unroll") for (int k = 0; k < 2; ++k) \
;         acc[ai][bj][m][n] = __builtin_amdgcn_mfma_f32_16x16x32_bf16(Bt[n][k], At[m][k], acc[ai][bj][m][n], 0, 0, 0); __builtin_amdgcn_s_setprio(0); } while (0)
; #define PG8_WAIT_V(n) asm volatile("s_waitcnt vmcnt(" #n ")" ::: "memory")
; #define PG8_WAIT_L(n) asm volatile("s_waitcnt lgkmcnt(" #n ")" ::: "memory")
; #define PG8_BAR __builtin_amdgcn_s_barrier()
; #define PG8_SCHED __builtin_amdgcn_sched_barrier(0)
; template <class Epi, class Sched>
; DI void gemm_phase(LAS unsigned char* lds, const Gemm g, const Sched& S, const Epi& E) {
;     ...
;             PG8_LDB(B0, 0, 0); PG8_LDB(B1, 0, 1); PG8_SCHED; PG8_LDA(At, 0, 0); PG8_STAGE(PG8_SA(1, 1), a1 + hstepA, voffA);
;             PG8_WAIT_V(8); PG8_WAIT_L(0); PG8_BAR; PG8_MMA(0, 0, At, B0); PG8_MMA(0, 1, At, B1); PG8_BAR; PG8_SCHED;
;             PG8_LDA(At, 0, 1); PG8_STAGE(PG8_SB(0, 0), b2, voffB); PG8_STAGE(PG8_SB(0, 1), b2 + hstepB, voffB); PG8_STAGE(PG8_SA(0, 0), a2, voffA);
;             PG8_WAIT_V(8); PG8_WAIT_L(0); PG8_BAR; PG8_MMA(1, 0, At, B0); PG8_MMA(1, 1, At, B1); PG8_BAR; PG8_SCHED;
;             PG8_LDB(B0, 1, 0); PG8_LDB(B1, 1, 1); PG8_SCHED; PG8_LDA(At, 1, 0); PG8_STAGE(PG8_SA(0, 1), a2 + hstepA, voffA);
;             PG8_WAIT_V(8); PG8_WAIT_L(0); PG8_BAR; PG8_MMA(0, 0, At, B0); PG8_MMA(0, 1, At, B1); PG8_BAR; PG8_SCHED;
.Lpk0_w2:
	s_mov_b32 s99, 0
	s_waitcnt lgkmcnt(0)
	s_nop 0
	s_barrier
	s_setprio 1
	v_mfma_f32_16x16x32_bf16 v[62:65], v[168:171], v[202:205], 0
	v_mfma_f32_16x16x32_bf16 v[54:57], v[176:179], v[202:205], 0
	v_mfma_f32_16x16x32_bf16 v[46:49], v[168:171], v[210:213], 0
	v_mfma_f32_16x16x32_bf16 v[38:41], v[176:179], v[210:213], 0
	v_mfma_f32_16x16x32_bf16 v[30:33], v[168:171], v[218:221], 0
	v_mfma_f32_16x16x32_bf16 v[22:25], v[176:179], v[218:221], 0
	v_mfma_f32_16x16x32_bf16 v[14:17], v[168:171], v[226:229], 0
	v_mfma_f32_16x16x32_bf16 v[6:9], v[176:179], v[226:229], 0
	v_mfma_f32_16x16x32_bf16 v[62:65], v[172:175], v[206:209], v[62:65]
	v_mfma_f32_16x16x32_bf16 v[54:57], v[180:183], v[206:209], v[54:57]
	v_mfma_f32_16x16x32_bf16 v[46:49], v[172:175], v[214:217], v[46:49]
	v_mfma_f32_16x16x32_bf16 v[38:41], v[180:183], v[214:217], v[38:41]
	v_mfma_f32_16x16x32_bf16 v[30:33], v[172:175], v[222:225], v[30:33]
	v_mfma_f32_16x16x32_bf16 v[22:25], v[180:183], v[222:225], v[22:25]
	v_mfma_f32_16x16x32_bf16 v[14:17], v[172:175], v[230:233], v[14:17]
	v_mfma_f32_16x16x32_bf16 v[6:9], v[180:183], v[230:233], v[6:9]
	v_mfma_f32_16x16x32_bf16 v[58:61], v[186:189], v[202:205], 0
	v_mfma_f32_16x16x32_bf16 v[50:53], v[194:197], v[202:205], 0
	v_mfma_f32_16x16x32_bf16 v[42:45], v[186:189], v[210:213], 0
	v_mfma_f32_16x16x32_bf16 v[34:37], v[194:197], v[210:213], 0
	v_mfma_f32_16x16x32_bf16 v[26:29], v[186:189], v[218:221], 0
	v_mfma_f32_16x16x32_bf16 v[18:21], v[194:197], v[218:221], 0
	v_mfma_f32_16x16x32_bf16 v[10:13], v[186:189], v[226:229], 0
	v_mfma_f32_16x16x32_bf16 v[2:5], v[194:197], v[226:229], 0
	v_mfma_f32_16x16x32_bf16 v[58:61], v[190:193], v[206:209], v[58:61]
	v_mfma_f32_16x16x32_bf16 v[50:53], v[198:201], v[206:209], v[50:53]
	v_mfma_f32_16x16x32_bf16 v[42:45], v[190:193], v[214:217], v[42:45]
	v_mfma_f32_16x16x32_bf16 v[34:37], v[198:201], v[214:217], v[34:37]
	v_mfma_f32_16x16x32_bf16 v[26:29], v[190:193], v[222:225], v[26:29]
	v_mfma_f32_16x16x32_bf16 v[18:21], v[198:201], v[222:225], v[18:21]
	v_mfma_f32_16x16x32_bf16 v[10:13], v[190:193], v[230:233], v[10:13]
	v_mfma_f32_16x16x32_bf16 v[2:5], v[198:201], v[230:233], v[2:5]
	s_setprio 0
	s_barrier
	s_add_i32 s66, 0, 0x18000
	v_add_u32_e32 v167, s66, v158
	s_add_i32 s67, 0, 0x1c000
	ds_read_b128 v[168:171], v167
	ds_read_b128 v[172:175], v167 offset:1024
	ds_read_b128 v[176:179], v167 offset:2048
	ds_read_b128 v[180:183], v167 offset:3072
	v_add_u32_e32 v167, s67, v158
	ds_read_b128 v[186:189], v167
	ds_read_b128 v[190:193], v167 offset:1024
	ds_read_b128 v[194:197], v167 offset:2048
	ds_read_b128 v[198:201], v167 offset:3072
	s_add_u32 s44, s44, 0x40000
	s_addc_u32 s45, s45, 0
	s_mov_b32 m0, s51
	v_lshl_add_u64 v[242:243], s[44:45], 0, v[136:137]
	ds_read_b128 v[202:205], v160 offset:32768
	ds_read_b128 v[206:209], v160 offset:33792
	ds_read_b128 v[210:213], v160 offset:34816
	ds_read_b128 v[214:217], v160 offset:35840
	ds_read_b128 v[218:221], v160 offset:36864
	ds_read_b128 v[222:225], v160 offset:37888
	ds_read_b128 v[226:229], v160 offset:38912
	ds_read_b128 v[230:233], v160 offset:39936
	global_load_lds_dwordx4 v[242:243], off
	v_lshl_add_u64 v[242:243], s[44:45], 0, v[132:133]
	s_mov_b32 m0, s52
	s_nop 0
	global_load_lds_dwordx4 v[242:243], off
	s_waitcnt vmcnt(8)
	s_waitcnt lgkmcnt(0)
	s_barrier
	s_setprio 1
	v_mfma_f32_16x16x32_bf16 v[126:129], v[168:171], v[202:205], v[126:129]
	v_mfma_f32_16x16x32_bf16 v[118:121], v[176:179], v[202:205], v[118:121]
	v_mfma_f32_16x16x32_bf16 v[110:113], v[168:171], v[210:213], v[110:113]
	v_mfma_f32_16x16x32_bf16 v[102:105], v[176:179], v[210:213], v[102:105]
	v_mfma_f32_16x16x32_bf16 v[94:97], v[168:171], v[218:221], v[94:97]
	v_mfma_f32_16x16x32_bf16 v[86:89], v[176:179], v[218:221], v[86:89]
	v_mfma_f32_16x16x32_bf16 v[78:81], v[168:171], v[226:229], v[78:81]
	v_mfma_f32_16x16x32_bf16 v[70:73], v[176:179], v[226:229], v[70:73]
	v_mfma_f32_16x16x32_bf16 v[126:129], v[172:175], v[206:209], v[126:129]
	v_mfma_f32_16x16x32_bf16 v[118:121], v[180:183], v[206:209], v[118:121]
	v_mfma_f32_16x16x32_bf16 v[110:113], v[172:175], v[214:217], v[110:113]
	v_mfma_f32_16x16x32_bf16 v[102:105], v[180:183], v[214:217], v[102:105]
	v_mfma_f32_16x16x32_bf16 v[94:97], v[172:175], v[222:225], v[94:97]
	v_mfma_f32_16x16x32_bf16 v[86:89], v[180:183], v[222:225], v[86:89]
	v_mfma_f32_16x16x32_bf16 v[78:81], v[172:175], v[230:233], v[78:81]
	v_mfma_f32_16x16x32_bf16 v[70:73], v[180:183], v[230:233], v[70:73]
	v_mfma_f32_16x16x32_bf16 v[122:125], v[186:189], v[202:205], v[122:125]
	v_mfma_f32_16x16x32_bf16 v[114:117], v[194:197], v[202:205], v[114:117]
	v_mfma_f32_16x16x32_bf16 v[106:109], v[186:189], v[210:213], v[106:109]
	v_mfma_f32_16x16x32_bf16 v[98:101], v[194:197], v[210:213], v[98:101]
	v_mfma_f32_16x16x32_bf16 v[90:93], v[186:189], v[218:221], v[90:93]
	v_mfma_f32_16x16x32_bf16 v[82:85], v[194:197], v[218:221], v[82:85]
	v_mfma_f32_16x16x32_bf16 v[74:77], v[186:189], v[226:229], v[74:77]
	v_mfma_f32_16x16x32_bf16 v[66:69], v[194:197], v[226:229], v[66:69]
	v_mfma_f32_16x16x32_bf16 v[122:125], v[190:193], v[206:209], v[122:125]
	v_mfma_f32_16x16x32_bf16 v[114:117], v[198:201], v[206:209], v[114:117]
	v_mfma_f32_16x16x32_bf16 v[106:109], v[190:193], v[214:217], v[106:109]
	v_mfma_f32_16x16x32_bf16 v[98:101], v[198:201], v[214:217], v[98:101]
	v_mfma_f32_16x16x32_bf16 v[90:93], v[190:193], v[222:225], v[90:93]
	v_mfma_f32_16x16x32_bf16 v[82:85], v[198:201], v[222:225], v[82:85]
	v_mfma_f32_16x16x32_bf16 v[74:77], v[190:193], v[230:233], v[74:77]
	v_mfma_f32_16x16x32_bf16 v[66:69], v[198:201], v[230:233], v[66:69]
	s_setprio 0
	s_barrier
; #define PG8_STAGE(bufoff, gbase, voff) do { _Pragma("unroll") for (int _i = 0; _i < 2; ++_i) \
;         __builtin_amdgcn_global_load_lds((const unsigned*)((const char*)(gbase) + (voff)[_i]), (LAS unsigned*)(lds + (bufoff) + ldsw + _i * 8192), 16, 0, 0); } while (0)
; #define PG8_LDA(dst, b, h) do { _Pragma("unroll") for (int m = 0; m < 4; ++m) _Pragma("unroll") for (int k = 0; k < 2; ++k) dst[m][k] = *(const LAS bf16x8*)(lds + PG8_SA(b, h) + aoff + m * 2048 + k * 1024); } while (0)
; #define PG8_LDB(dst, b, h) do { _Pragma("unroll") for (int n = 0; n < 2; ++n) _Pragma("unroll") for (int k = 0; k < 2; ++k) dst[n][k] = *(const LAS bf16x8*)(lds + PG8_SB(b, h) + boff + n * 2048 + k * 1024); } while (0)
; #define PG8_MMA(ai, bj, At, Bt) do { __builtin_amdgcn_s_setprio(1); _Pragma("unroll") for (int m = 0; m < 4; ++m) _Pragma("unroll") for (int n = 0; n < 2; ++n) _Pragma("unroll") for (int k = 0; k < 2; ++k) \
;         acc[ai][bj][m][n] = __builtin_amdgcn_mfma_f32_16x16x32_bf16(Bt[n][k], At[m][k], acc[ai][bj][m][n], 0, 0, 0); __builtin_amdgcn_s_setprio(0); } while (0)
; #define PG8_WAIT_V(n) asm volatile("s_waitcnt vmcnt(" #n ")" ::: "memory")
; #define PG8_WAIT_L(n) asm volatile("s_waitcnt lgkmcnt(" #n ")" ::: "memory")
; #define PG8_BAR __builtin_amdgcn_s_barrier()
; #define PG8_SCHED __builtin_amdgcn_sched_barrier(0)
; template <class Epi, class Sched>
; DI void gemm_phase(LAS unsigned char* lds, const Gemm g, const Sched& S, const Epi& E) {
;     ...
;         for (int t = 0; t < nt; t += 2) {
;             const bool last = (t == nt - 2);
;             const char* a1 = cA + (size_t)(t + 1) * kstep;
;             const char* a2 = last ? nA : cA + (size_t)(t + 2) * kstep; const char* b2 = last ? nB : cB + (size_t)(t + 2) * kstep;
;             const char* a3 = a2 + kstep; const char* b3 = b2 + kstep;
;             PG8_LDB(B0, 0, 0); PG8_LDB(B1, 0, 1); PG8_SCHED; PG8_LDA(At, 0, 0); PG8_STAGE(PG8_SA(1, 1), a1 + hstepA, voffA);
;     ...
;             PG8_LDA(At, 1, 1); PG8_STAGE(PG8_SB(1, 0), b3, voffB); PG8_STAGE(PG8_SB(1, 1), b3 + hstepB, voffB); PG8_STAGE(PG8_SA(1, 0), a3, voffA);
;             PG8_WAIT_V(8); PG8_WAIT_L(0); PG8_BAR; PG8_MMA(1, 0, At, B0); PG8_MMA(1, 1, At, B1); PG8_BAR; PG8_SCHED;
	s_add_i32 s44, s66, s46
	v_lshl_add_u64 v[234:235], v[234:235], 0, s[16:17]
	s_mov_b32 m0, s44
	ds_read_b128 v[202:205], v160 offset:49152
	ds_read_b128 v[206:209], v160 offset:50176
	ds_read_b128 v[210:213], v160 offset:51200
	ds_read_b128 v[214:217], v160 offset:52224
	ds_read_b128 v[218:221], v160 offset:53248
	ds_read_b128 v[222:225], v160 offset:54272
	ds_read_b128 v[226:229], v160 offset:55296
	ds_read_b128 v[230:233], v160 offset:56320
	global_load_lds_dwordx4 v[234:235], off
	s_add_i32 m0, s44, 0x2000
	s_add_u32 s42, s42, 0x40080
	v_lshl_add_u64 v[234:235], v[236:237], 0, s[16:17]
	s_addc_u32 s43, s43, 0
	s_add_i32 s44, s67, s46
	global_load_lds_dwordx4 v[234:235], off
	v_lshl_add_u64 v[234:235], s[42:43], 0, v[134:135]
	s_mov_b32 m0, s44
	s_nop 0
	global_load_lds_dwordx4 v[234:235], off
	v_lshl_add_u64 v[234:235], s[42:43], 0, v[130:131]
	s_add_i32 m0, s44, 0x2000
	s_nop 0
	global_load_lds_dwordx4 v[234:235], off
	v_lshl_add_u64 v[234:235], v[238:239], 0, s[16:17]
	s_mov_b32 m0, s54
	s_nop 0
	global_load_lds_dwordx4 v[234:235], off
	v_lshl_add_u64 v[234:235], v[240:241], 0, s[16:17]
	s_mov_b32 m0, s55
	s_nop 0
	global_load_lds_dwordx4 v[234:235], off
	s_waitcnt vmcnt(8)
	s_waitcnt lgkmcnt(0)
	s_nop 0
	s_barrier
	s_setprio 1
	v_mfma_f32_16x16x32_bf16 v[62:65], v[168:171], v[202:205], v[62:65]
	v_mfma_f32_16x16x32_bf16 v[54:57], v[176:179], v[202:205], v[54:57]
	v_mfma_f32_16x16x32_bf16 v[46:49], v[168:171], v[210:213], v[46:49]
	v_mfma_f32_16x16x32_bf16 v[38:41], v[176:179], v[210:213], v[38:41]
	v_mfma_f32_16x16x32_bf16 v[30:33], v[168:171], v[218:221], v[30:33]
	v_mfma_f32_16x16x32_bf16 v[22:25], v[176:179], v[218:221], v[22:25]
	v_mfma_f32_16x16x32_bf16 v[14:17], v[168:171], v[226:229], v[14:17]
	v_mfma_f32_16x16x32_bf16 v[6:9], v[176:179], v[226:229], v[6:9]
	v_mfma_f32_16x16x32_bf16 v[62:65], v[172:175], v[206:209], v[62:65]
	v_mfma_f32_16x16x32_bf16 v[54:57], v[180:183], v[206:209], v[54:57]
	v_mfma_f32_16x16x32_bf16 v[46:49], v[172:175], v[214:217], v[46:49]
	v_mfma_f32_16x16x32_bf16 v[38:41], v[180:183], v[214:217], v[38:41]
	v_mfma_f32_16x16x32_bf16 v[30:33], v[172:175], v[222:225], v[30:33]
	v_mfma_f32_16x16x32_bf16 v[22:25], v[180:183], v[222:225], v[22:25]
	v_mfma_f32_16x16x32_bf16 v[14:17], v[172:175], v[230:233], v[14:17]
	v_mfma_f32_16x16x32_bf16 v[6:9], v[180:183], v[230:233], v[6:9]
	v_mfma_f32_16x16x32_bf16 v[58:61], v[186:189], v[202:205], v[58:61]
	v_mfma_f32_16x16x32_bf16 v[50:53], v[194:197], v[202:205], v[50:53]
	v_mfma_f32_16x16x32_bf16 v[42:45], v[186:189], v[210:213], v[42:45]
	v_mfma_f32_16x16x32_bf16 v[34:37], v[194:197], v[210:213], v[34:37]
	v_mfma_f32_16x16x32_bf16 v[26:29], v[186:189], v[218:221], v[26:29]
	v_mfma_f32_16x16x32_bf16 v[18:21], v[194:197], v[218:221], v[18:21]
	v_mfma_f32_16x16x32_bf16 v[10:13], v[186:189], v[226:229], v[10:13]
	v_mfma_f32_16x16x32_bf16 v[2:5], v[194:197], v[226:229], v[2:5]
	v_mfma_f32_16x16x32_bf16 v[58:61], v[190:193], v[206:209], v[58:61]
	v_mfma_f32_16x16x32_bf16 v[50:53], v[198:201], v[206:209], v[50:53]
	v_mfma_f32_16x16x32_bf16 v[42:45], v[190:193], v[214:217], v[42:45]
	v_mfma_f32_16x16x32_bf16 v[34:37], v[198:201], v[214:217], v[34:37]
	v_mfma_f32_16x16x32_bf16 v[26:29], v[190:193], v[222:225], v[26:29]
	v_mfma_f32_16x16x32_bf16 v[18:21], v[198:201], v[222:225], v[18:21]
	v_mfma_f32_16x16x32_bf16 v[10:13], v[190:193], v[230:233], v[10:13]
	v_mfma_f32_16x16x32_bf16 v[2:5], v[198:201], v[230:233], v[2:5]
	s_setprio 0
	s_barrier
	s_add_i32 s65, s65, 2
	s_add_u32 s40, s40, 0x100
	s_addc_u32 s41, s41, 0
	s_add_u32 s63, s63, 0x100
	s_addc_u32 s64, s64, 0
	s_cmp_gt_u32 s65, 13
.LBB0_179:
	ds_read_b128 v[168:171], v162
	ds_read_b128 v[172:175], v162 offset:1024
	ds_read_b128 v[176:179], v162 offset:2048
	ds_read_b128 v[180:183], v162 offset:3072
	ds_read_b128 v[186:189], v163
	ds_read_b128 v[190:193], v163 offset:1024
	ds_read_b128 v[194:197], v163 offset:2048
	ds_read_b128 v[198:201], v163 offset:3072
	s_add_u32 s42, s40, 0xfffc0080
	s_addc_u32 s43, s41, -1
	s_cmp_eq_u32 s65, 12
	s_cselect_b32 s45, s35, s43
	s_cselect_b32 s44, s61, s42
	s_cselect_b32 s43, s21, s64
	s_cselect_b32 s42, s62, s63
	v_lshl_add_u64 v[234:235], s[40:41], 0, v[138:139]
	s_add_i32 m0, s49, 0xc000
	ds_read_b128 v[202:205], v160
	ds_read_b128 v[206:209], v160 offset:1024
	ds_read_b128 v[210:213], v160 offset:2048
	ds_read_b128 v[214:217], v160 offset:3072
	ds_read_b128 v[218:221], v160 offset:4096
	ds_read_b128 v[222:225], v160 offset:5120
	ds_read_b128 v[226:229], v160 offset:6144
	ds_read_b128 v[230:233], v160 offset:7168
	global_load_lds_dwordx4 v[234:235], off
	v_lshl_add_u64 v[234:235], s[40:41], 0, v[140:141]
	s_add_i32 m0, s49, 0xe000
	s_nop 0
	global_load_lds_dwordx4 v[234:235], off
	s_waitcnt vmcnt(8)
	s_waitcnt lgkmcnt(0)
	s_nop 0
	s_barrier
; #define PG8_STAGE(bufoff, gbase, voff) do { _Pragma("unroll") for (int _i = 0; _i < 2; ++_i) \
;         __builtin_amdgcn_global_load_lds((const unsigned*)((const char*)(gbase) + (voff)[_i]), (LAS unsigned*)(lds + (bufoff) + ldsw + _i * 8192), 16, 0, 0); } while (0)
; #define PG8_LDA(dst, b, h) do { _Pragma("unroll") for (int m = 0; m < 4; ++m) _Pragma("unroll") for (int k = 0; k < 2; ++k) dst[m][k] = *(const LAS bf16x8*)(lds + PG8_SA(b, h) + aoff + m * 2048 + k * 1024); } while (0)
; #define PG8_MMA(ai, bj, At, Bt) do { __builtin_amdgcn_s_setprio(1); _Pragma("unroll") for (int m = 0; m < 4; ++m) _Pragma("unroll") for (int n = 0; n < 2; ++n) _Pragma("unroll") for (int k = 0; k < 2; ++k) \
;         acc[ai][bj][m][n] = __builtin_amdgcn_mfma_f32_16x16x32_bf16(Bt[n][k], At[m][k], acc[ai][bj][m][n], 0, 0, 0); __builtin_amdgcn_s_setprio(0); } while (0)
; #define PG8_WAIT_V(n) asm volatile("s_waitcnt vmcnt(" #n ")" ::: "memory")
; #define PG8_WAIT_L(n) asm volatile("s_waitcnt lgkmcnt(" #n ")" ::: "memory")
; #define PG8_BAR __builtin_amdgcn_s_barrier()
; #define PG8_SCHED __builtin_amdgcn_sched_barrier(0)
; template <class Epi, class Sched>
; DI void gemm_phase(LAS unsigned char* lds, const Gemm g, const Sched& S, const Epi& E) {
;     ...
;             PG8_WAIT_V(8); PG8_WAIT_L(0); PG8_BAR; PG8_MMA(0, 0, At, B0); PG8_MMA(0, 1, At, B1); PG8_BAR; PG8_SCHED;
;             PG8_LDA(At, 0, 1); PG8_STAGE(PG8_SB(0, 0), b2, voffB); PG8_STAGE(PG8_SB(0, 1), b2 + hstepB, voffB); PG8_STAGE(PG8_SA(0, 0), a2, voffA);
;             PG8_WAIT_V(8); PG8_WAIT_L(0); PG8_BAR; PG8_MMA(1, 0, At, B0); PG8_MMA(1, 1, At, B1); PG8_BAR; PG8_SCHED;
	s_setprio 1
	v_mfma_f32_16x16x32_bf16 v[126:129], v[168:171], v[202:205], v[126:129]
	v_mfma_f32_16x16x32_bf16 v[118:121], v[176:179], v[202:205], v[118:121]
	v_mfma_f32_16x16x32_bf16 v[110:113], v[168:171], v[210:213], v[110:113]
	v_mfma_f32_16x16x32_bf16 v[102:105], v[176:179], v[210:213], v[102:105]
	v_mfma_f32_16x16x32_bf16 v[94:97], v[168:171], v[218:221], v[94:97]
	v_mfma_f32_16x16x32_bf16 v[86:89], v[176:179], v[218:221], v[86:89]
	v_mfma_f32_16x16x32_bf16 v[78:81], v[168:171], v[226:229], v[78:81]
	v_mfma_f32_16x16x32_bf16 v[70:73], v[176:179], v[226:229], v[70:73]
	v_mfma_f32_16x16x32_bf16 v[126:129], v[172:175], v[206:209], v[126:129]
	v_mfma_f32_16x16x32_bf16 v[118:121], v[180:183], v[206:209], v[118:121]
	v_mfma_f32_16x16x32_bf16 v[110:113], v[172:175], v[214:217], v[110:113]
	v_mfma_f32_16x16x32_bf16 v[102:105], v[180:183], v[214:217], v[102:105]
	v_mfma_f32_16x16x32_bf16 v[94:97], v[172:175], v[222:225], v[94:97]
	v_mfma_f32_16x16x32_bf16 v[86:89], v[180:183], v[222:225], v[86:89]
	v_mfma_f32_16x16x32_bf16 v[78:81], v[172:175], v[230:233], v[78:81]
	v_mfma_f32_16x16x32_bf16 v[70:73], v[180:183], v[230:233], v[70:73]
	v_mfma_f32_16x16x32_bf16 v[122:125], v[186:189], v[202:205], v[122:125]
	v_mfma_f32_16x16x32_bf16 v[114:117], v[194:197], v[202:205], v[114:117]
	v_mfma_f32_16x16x32_bf16 v[106:109], v[186:189], v[210:213], v[106:109]
	v_mfma_f32_16x16x32_bf16 v[98:101], v[194:197], v[210:213], v[98:101]
	v_mfma_f32_16x16x32_bf16 v[90:93], v[186:189], v[218:221], v[90:93]
	v_mfma_f32_16x16x32_bf16 v[82:85], v[194:197], v[218:221], v[82:85]
	v_mfma_f32_16x16x32_bf16 v[74:77], v[186:189], v[226:229], v[74:77]
	v_mfma_f32_16x16x32_bf16 v[66:69], v[194:197], v[226:229], v[66:69]
	v_mfma_f32_16x16x32_bf16 v[122:125], v[190:193], v[206:209], v[122:125]
	v_mfma_f32_16x16x32_bf16 v[114:117], v[198:201], v[206:209], v[114:117]
	v_mfma_f32_16x16x32_bf16 v[106:109], v[190:193], v[214:217], v[106:109]
	v_mfma_f32_16x16x32_bf16 v[98:101], v[198:201], v[214:217], v[98:101]
	v_mfma_f32_16x16x32_bf16 v[90:93], v[190:193], v[222:225], v[90:93]
	v_mfma_f32_16x16x32_bf16 v[82:85], v[198:201], v[222:225], v[82:85]
	v_mfma_f32_16x16x32_bf16 v[74:77], v[190:193], v[230:233], v[74:77]
	v_mfma_f32_16x16x32_bf16 v[66:69], v[198:201], v[230:233], v[66:69]
	s_setprio 0
	s_barrier
	s_add_i32 s66, s57, s46
	v_lshl_add_u64 v[234:235], s[42:43], 0, v[134:135]
	s_mov_b32 m0, s66
	ds_read_b128 v[202:205], v160 offset:16384
	ds_read_b128 v[206:209], v160 offset:17408
	ds_read_b128 v[210:213], v160 offset:18432
	ds_read_b128 v[214:217], v160 offset:19456
	ds_read_b128 v[218:221], v160 offset:20480
	ds_read_b128 v[222:225], v160 offset:21504
	ds_read_b128 v[226:229], v160 offset:22528
	ds_read_b128 v[230:233], v160 offset:23552
	global_load_lds_dwordx4 v[234:235], off
	s_add_i32 m0, s66, 0x2000
	s_add_u32 s66, s42, 0x40000
	v_lshl_add_u64 v[236:237], s[42:43], 0, v[130:131]
	s_addc_u32 s67, s43, 0
	s_add_i32 s68, s58, s46
	global_load_lds_dwordx4 v[236:237], off
	v_lshl_add_u64 v[238:239], s[66:67], 0, v[134:135]
	s_mov_b32 m0, s68
	v_lshl_add_u64 v[240:241], s[44:45], 0, v[132:133]
	global_load_lds_dwordx4 v[238:239], off
	v_lshl_add_u64 v[238:239], s[66:67], 0, v[130:131]
	s_add_i32 m0, s68, 0x2000
	s_nop 0
	global_load_lds_dwordx4 v[238:239], off
	v_lshl_add_u64 v[238:239], s[44:45], 0, v[136:137]
	s_mov_b32 m0, s49
	s_nop 0
	global_load_lds_dwordx4 v[238:239], off
	s_mov_b32 m0, s50
	s_nop 0
	global_load_lds_dwordx4 v[240:241], off
	s_waitcnt vmcnt(8)
	s_waitcnt lgkmcnt(0)
	s_barrier
	s_setprio 1
	v_mfma_f32_16x16x32_bf16 v[62:65], v[168:171], v[202:205], v[62:65]
	v_mfma_f32_16x16x32_bf16 v[54:57], v[176:179], v[202:205], v[54:57]
	v_mfma_f32_16x16x32_bf16 v[46:49], v[168:171], v[210:213], v[46:49]
	v_mfma_f32_16x16x32_bf16 v[38:41], v[176:179], v[210:213], v[38:41]
	v_mfma_f32_16x16x32_bf16 v[30:33], v[168:171], v[218:221], v[30:33]
	v_mfma_f32_16x16x32_bf16 v[22:25], v[176:179], v[218:221], v[22:25]
	v_mfma_f32_16x16x32_bf16 v[14:17], v[168:171], v[226:229], v[14:17]
	v_mfma_f32_16x16x32_bf16 v[6:9], v[176:179], v[226:229], v[6:9]
	v_mfma_f32_16x16x32_bf16 v[62:65], v[172:175], v[206:209], v[62:65]
	v_mfma_f32_16x16x32_bf16 v[54:57], v[180:183], v[206:209], v[54:57]
	v_mfma_f32_16x16x32_bf16 v[46:49], v[172:175], v[214:217], v[46:49]
	v_mfma_f32_16x16x32_bf16 v[38:41], v[180:183], v[214:217], v[38:41]
	v_mfma_f32_16x16x32_bf16 v[30:33], v[172:175], v[222:225], v[30:33]
	v_mfma_f32_16x16x32_bf16 v[22:25], v[180:183], v[222:225], v[22:25]
	v_mfma_f32_16x16x32_bf16 v[14:17], v[172:175], v[230:233], v[14:17]
	v_mfma_f32_16x16x32_bf16 v[6:9], v[180:183], v[230:233], v[6:9]
	v_mfma_f32_16x16x32_bf16 v[58:61], v[186:189], v[202:205], v[58:61]
	v_mfma_f32_16x16x32_bf16 v[50:53], v[194:197], v[202:205], v[50:53]
	v_mfma_f32_16x16x32_bf16 v[42:45], v[186:189], v[210:213], v[42:45]
	v_mfma_f32_16x16x32_bf16 v[34:37], v[194:197], v[210:213], v[34:37]
	v_mfma_f32_16x16x32_bf16 v[26:29], v[186:189], v[218:221], v[26:29]
	v_mfma_f32_16x16x32_bf16 v[18:21], v[194:197], v[218:221], v[18:21]
	v_mfma_f32_16x16x32_bf16 v[10:13], v[186:189], v[226:229], v[10:13]
	v_mfma_f32_16x16x32_bf16 v[2:5], v[194:197], v[226:229], v[2:5]
	v_mfma_f32_16x16x32_bf16 v[58:61], v[190:193], v[206:209], v[58:61]
	v_mfma_f32_16x16x32_bf16 v[50:53], v[198:201], v[206:209], v[50:53]
	v_mfma_f32_16x16x32_bf16 v[42:45], v[190:193], v[214:217], v[42:45]
	v_mfma_f32_16x16x32_bf16 v[34:37], v[198:201], v[214:217], v[34:37]
	v_mfma_f32_16x16x32_bf16 v[26:29], v[190:193], v[222:225], v[26:29]
	v_mfma_f32_16x16x32_bf16 v[18:21], v[198:201], v[222:225], v[18:21]
	v_mfma_f32_16x16x32_bf16 v[10:13], v[190:193], v[230:233], v[10:13]
	v_mfma_f32_16x16x32_bf16 v[2:5], v[198:201], v[230:233], v[2:5]
	s_setprio 0
	s_barrier
; #define PG8_STAGE(bufoff, gbase, voff) do { _Pragma("unroll") for (int _i = 0; _i < 2; ++_i) \
;         __builtin_amdgcn_global_load_lds((const unsigned*)((const char*)(gbase) + (voff)[_i]), (LAS unsigned*)(lds + (bufoff) + ldsw + _i * 8192), 16, 0, 0); } while (0)
; #define PG8_LDA(dst, b, h) do { _Pragma("unroll") for (int m = 0; m < 4; ++m) _Pragma("unroll") for (int k = 0; k < 2; ++k) dst[m][k] = *(const LAS bf16x8*)(lds + PG8_SA(b, h) + aoff + m * 2048 + k * 1024); } while (0)
; #define PG8_LDB(dst, b, h) do { _Pragma("unroll") for (int n = 0; n < 2; ++n) _Pragma("unroll") for (int k = 0; k < 2; ++k) dst[n][k] = *(const LAS bf16x8*)(lds + PG8_SB(b, h) + boff + n * 2048 + k * 1024); } while (0)
; #define PG8_MMA(ai, bj, At, Bt) do { __builtin_amdgcn_s_setprio(1); _Pragma("unroll") for (int m = 0; m < 4; ++m) _Pragma("unroll") for (int n = 0; n < 2; ++n) _Pragma("unroll") for (int k = 0; k < 2; ++k) \
;         acc[ai][bj][m][n] = __builtin_amdgcn_mfma_f32_16x16x32_bf16(Bt[n][k], At[m][k], acc[ai][bj][m][n], 0, 0, 0); __builtin_amdgcn_s_setprio(0); } while (0)
; #define PG8_WAIT_V(n) asm volatile("s_waitcnt vmcnt(" #n ")" ::: "memory")
; #define PG8_WAIT_L(n) asm volatile("s_waitcnt lgkmcnt(" #n ")" ::: "memory")
; #define PG8_BAR __builtin_amdgcn_s_barrier()
; #define PG8_SCHED __builtin_amdgcn_sched_barrier(0)
; template <class Epi, class Sched>
; DI void gemm_phase(LAS unsigned char* lds, const Gemm g, const Sched& S, const Epi& E) {
;     ...
;             PG8_LDB(B0, 1, 0); PG8_LDB(B1, 1, 1); PG8_SCHED; PG8_LDA(At, 1, 0); PG8_STAGE(PG8_SA(0, 1), a2 + hstepA, voffA);
;             PG8_WAIT_V(8); PG8_WAIT_L(0); PG8_BAR; PG8_MMA(0, 0, At, B0); PG8_MMA(0, 1, At, B1); PG8_BAR; PG8_SCHED;
	s_add_i32 s66, 0, 0x18000
	v_add_u32_e32 v167, s66, v158
	s_add_i32 s67, 0, 0x1c000
	ds_read_b128 v[168:171], v167
	ds_read_b128 v[172:175], v167 offset:1024
	ds_read_b128 v[176:179], v167 offset:2048
	ds_read_b128 v[180:183], v167 offset:3072
	v_add_u32_e32 v167, s67, v158
	ds_read_b128 v[186:189], v167
	ds_read_b128 v[190:193], v167 offset:1024
	ds_read_b128 v[194:197], v167 offset:2048
	ds_read_b128 v[198:201], v167 offset:3072
	s_add_u32 s44, s44, 0x40000
	s_addc_u32 s45, s45, 0
	s_mov_b32 m0, s51
	v_lshl_add_u64 v[242:243], s[44:45], 0, v[136:137]
	ds_read_b128 v[202:205], v160 offset:32768
	ds_read_b128 v[206:209], v160 offset:33792
	ds_read_b128 v[210:213], v160 offset:34816
	ds_read_b128 v[214:217], v160 offset:35840
	ds_read_b128 v[218:221], v160 offset:36864
	ds_read_b128 v[222:225], v160 offset:37888
	ds_read_b128 v[226:229], v160 offset:38912
	ds_read_b128 v[230:233], v160 offset:39936
	global_load_lds_dwordx4 v[242:243], off
	v_lshl_add_u64 v[242:243], s[44:45], 0, v[132:133]
	s_mov_b32 m0, s52
	s_nop 0
	global_load_lds_dwordx4 v[242:243], off
	s_waitcnt vmcnt(8)
	s_waitcnt lgkmcnt(0)
	s_barrier
	s_setprio 1
	v_mfma_f32_16x16x32_bf16 v[126:129], v[168:171], v[202:205], v[126:129]
	v_mfma_f32_16x16x32_bf16 v[118:121], v[176:179], v[202:205], v[118:121]
	v_mfma_f32_16x16x32_bf16 v[110:113], v[168:171], v[210:213], v[110:113]
	v_mfma_f32_16x16x32_bf16 v[102:105], v[176:179], v[210:213], v[102:105]
	v_mfma_f32_16x16x32_bf16 v[94:97], v[168:171], v[218:221], v[94:97]
	v_mfma_f32_16x16x32_bf16 v[86:89], v[176:179], v[218:221], v[86:89]
	v_mfma_f32_16x16x32_bf16 v[78:81], v[168:171], v[226:229], v[78:81]
	v_mfma_f32_16x16x32_bf16 v[70:73], v[176:179], v[226:229], v[70:73]
	v_mfma_f32_16x16x32_bf16 v[126:129], v[172:175], v[206:209], v[126:129]
	v_mfma_f32_16x16x32_bf16 v[118:121], v[180:183], v[206:209], v[118:121]
	v_mfma_f32_16x16x32_bf16 v[110:113], v[172:175], v[214:217], v[110:113]
	v_mfma_f32_16x16x32_bf16 v[102:105], v[180:183], v[214:217], v[102:105]
	v_mfma_f32_16x16x32_bf16 v[94:97], v[172:175], v[222:225], v[94:97]
	v_mfma_f32_16x16x32_bf16 v[86:89], v[180:183], v[222:225], v[86:89]
	v_mfma_f32_16x16x32_bf16 v[78:81], v[172:175], v[230:233], v[78:81]
	v_mfma_f32_16x16x32_bf16 v[70:73], v[180:183], v[230:233], v[70:73]
	v_mfma_f32_16x16x32_bf16 v[122:125], v[186:189], v[202:205], v[122:125]
	v_mfma_f32_16x16x32_bf16 v[114:117], v[194:197], v[202:205], v[114:117]
	v_mfma_f32_16x16x32_bf16 v[106:109], v[186:189], v[210:213], v[106:109]
	v_mfma_f32_16x16x32_bf16 v[98:101], v[194:197], v[210:213], v[98:101]
	v_mfma_f32_16x16x32_bf16 v[90:93], v[186:189], v[218:221], v[90:93]
	v_mfma_f32_16x16x32_bf16 v[82:85], v[194:197], v[218:221], v[82:85]
	v_mfma_f32_16x16x32_bf16 v[74:77], v[186:189], v[226:229], v[74:77]
	v_mfma_f32_16x16x32_bf16 v[66:69], v[194:197], v[226:229], v[66:69]
	v_mfma_f32_16x16x32_bf16 v[122:125], v[190:193], v[206:209], v[122:125]
	v_mfma_f32_16x16x32_bf16 v[114:117], v[198:201], v[206:209], v[114:117]
	v_mfma_f32_16x16x32_bf16 v[106:109], v[190:193], v[214:217], v[106:109]
	v_mfma_f32_16x16x32_bf16 v[98:101], v[198:201], v[214:217], v[98:101]
	v_mfma_f32_16x16x32_bf16 v[90:93], v[190:193], v[222:225], v[90:93]
	v_mfma_f32_16x16x32_bf16 v[82:85], v[198:201], v[222:225], v[82:85]
	v_mfma_f32_16x16x32_bf16 v[74:77], v[190:193], v[230:233], v[74:77]
	v_mfma_f32_16x16x32_bf16 v[66:69], v[198:201], v[230:233], v[66:69]
	s_setprio 0
	s_barrier
; #define PG8_STAGE(bufoff, gbase, voff) do { _Pragma("unroll") for (int _i = 0; _i < 2; ++_i) \
;         __builtin_amdgcn_global_load_lds((const unsigned*)((const char*)(gbase) + (voff)[_i]), (LAS unsigned*)(lds + (bufoff) + ldsw + _i * 8192), 16, 0, 0); } while (0)
; #define PG8_LDA(dst, b, h) do { _Pragma("unroll") for (int m = 0; m < 4; ++m) _Pragma("unroll") for (int k = 0; k < 2; ++k) dst[m][k] = *(const LAS bf16x8*)(lds + PG8_SA(b, h) + aoff + m * 2048 + k * 1024); } while (0)
; #define PG8_MMA(ai, bj, At, Bt) do { __builtin_amdgcn_s_setprio(1); _Pragma("unroll") for (int m = 0; m < 4; ++m) _Pragma("unroll") for (int n = 0; n < 2; ++n) _Pragma("unroll") for (int k = 0; k < 2; ++k) \
;         acc[ai][bj][m][n] = __builtin_amdgcn_mfma_f32_16x16x32_bf16(Bt[n][k], At[m][k], acc[ai][bj][m][n], 0, 0, 0); __builtin_amdgcn_s_setprio(0); } while (0)
; #define PG8_WAIT_V(n) asm volatile("s_waitcnt vmcnt(" #n ")" ::: "memory")
; #define PG8_WAIT_L(n) asm volatile("s_waitcnt lgkmcnt(" #n ")" ::: "memory")
; #define PG8_BAR __builtin_amdgcn_s_barrier()
; #define PG8_SCHED __builtin_amdgcn_sched_barrier(0)
;     DI void pre(Pre& pr, const pg8::Unit& u, int wr, int fr) const { load_rows(pr, ssq, u, wr, fr); }
;     DI void pre(Pre& pr, const pg8::Unit& u, int wr, int fr) const { load_rows(pr, ssq, u, wr, fr); }
; template <class Epi, class Sched>
; DI void gemm_phase(LAS unsigned char* lds, const Gemm g, const Sched& S, const Epi& E) {
;     ...
;             PG8_LDA(At, 1, 1); PG8_STAGE(PG8_SB(1, 0), b3, voffB); PG8_STAGE(PG8_SB(1, 1), b3 + hstepB, voffB); PG8_STAGE(PG8_SA(1, 0), a3, voffA);
;             PG8_WAIT_V(8); PG8_WAIT_L(0); PG8_BAR; PG8_MMA(1, 0, At, B0); PG8_MMA(1, 1, At, B1); PG8_BAR; PG8_SCHED;
;         }
;         if (wr == 0) PG8_BAR;
;         E(acc, cur, wr, wc, fr, fq, pre);
;         if (!has_next) break;
	s_add_i32 s44, s66, s46
	v_lshl_add_u64 v[234:235], v[234:235], 0, s[16:17]
	s_mov_b32 m0, s44
	ds_read_b128 v[202:205], v160 offset:49152
	ds_read_b128 v[206:209], v160 offset:50176
	ds_read_b128 v[210:213], v160 offset:51200
	ds_read_b128 v[214:217], v160 offset:52224
	ds_read_b128 v[218:221], v160 offset:53248
	ds_read_b128 v[222:225], v160 offset:54272
	ds_read_b128 v[226:229], v160 offset:55296
	ds_read_b128 v[230:233], v160 offset:56320
	global_load_lds_dwordx4 v[234:235], off
	s_add_i32 m0, s44, 0x2000
	s_add_u32 s42, s42, 0x40080
	v_lshl_add_u64 v[234:235], v[236:237], 0, s[16:17]
	s_addc_u32 s43, s43, 0
	s_add_i32 s44, s67, s46
	global_load_lds_dwordx4 v[234:235], off
	v_lshl_add_u64 v[234:235], s[42:43], 0, v[134:135]
	s_mov_b32 m0, s44
	s_nop 0
	global_load_lds_dwordx4 v[234:235], off
	v_lshl_add_u64 v[234:235], s[42:43], 0, v[130:131]
	s_add_i32 m0, s44, 0x2000
	s_nop 0
	global_load_lds_dwordx4 v[234:235], off
	v_lshl_add_u64 v[234:235], v[238:239], 0, s[16:17]
	s_mov_b32 m0, s54
	s_nop 0
	global_load_lds_dwordx4 v[234:235], off
	v_lshl_add_u64 v[234:235], v[240:241], 0, s[16:17]
	s_mov_b32 m0, s55
	s_nop 0
	global_load_lds_dwordx4 v[234:235], off
	s_waitcnt vmcnt(8)
	s_waitcnt lgkmcnt(0)
	s_nop 0
	s_barrier
	s_setprio 1
	v_mfma_f32_16x16x32_bf16 v[62:65], v[168:171], v[202:205], v[62:65]
	v_mfma_f32_16x16x32_bf16 v[54:57], v[176:179], v[202:205], v[54:57]
	v_mfma_f32_16x16x32_bf16 v[46:49], v[168:171], v[210:213], v[46:49]
	v_mfma_f32_16x16x32_bf16 v[38:41], v[176:179], v[210:213], v[38:41]
	v_mfma_f32_16x16x32_bf16 v[30:33], v[168:171], v[218:221], v[30:33]
	v_mfma_f32_16x16x32_bf16 v[22:25], v[176:179], v[218:221], v[22:25]
	v_mfma_f32_16x16x32_bf16 v[14:17], v[168:171], v[226:229], v[14:17]
	v_mfma_f32_16x16x32_bf16 v[6:9], v[176:179], v[226:229], v[6:9]
	v_mfma_f32_16x16x32_bf16 v[62:65], v[172:175], v[206:209], v[62:65]
	v_mfma_f32_16x16x32_bf16 v[54:57], v[180:183], v[206:209], v[54:57]
	v_mfma_f32_16x16x32_bf16 v[46:49], v[172:175], v[214:217], v[46:49]
	v_mfma_f32_16x16x32_bf16 v[38:41], v[180:183], v[214:217], v[38:41]
	v_mfma_f32_16x16x32_bf16 v[30:33], v[172:175], v[222:225], v[30:33]
	v_mfma_f32_16x16x32_bf16 v[22:25], v[180:183], v[222:225], v[22:25]
	v_mfma_f32_16x16x32_bf16 v[14:17], v[172:175], v[230:233], v[14:17]
	v_mfma_f32_16x16x32_bf16 v[6:9], v[180:183], v[230:233], v[6:9]
	v_mfma_f32_16x16x32_bf16 v[58:61], v[186:189], v[202:205], v[58:61]
	v_mfma_f32_16x16x32_bf16 v[50:53], v[194:197], v[202:205], v[50:53]
	v_mfma_f32_16x16x32_bf16 v[42:45], v[186:189], v[210:213], v[42:45]
	v_mfma_f32_16x16x32_bf16 v[34:37], v[194:197], v[210:213], v[34:37]
	v_mfma_f32_16x16x32_bf16 v[26:29], v[186:189], v[218:221], v[26:29]
	v_mfma_f32_16x16x32_bf16 v[18:21], v[194:197], v[218:221], v[18:21]
	v_mfma_f32_16x16x32_bf16 v[10:13], v[186:189], v[226:229], v[10:13]
	v_mfma_f32_16x16x32_bf16 v[2:5], v[194:197], v[226:229], v[2:5]
	v_mfma_f32_16x16x32_bf16 v[58:61], v[190:193], v[206:209], v[58:61]
	v_mfma_f32_16x16x32_bf16 v[50:53], v[198:201], v[206:209], v[50:53]
	v_mfma_f32_16x16x32_bf16 v[42:45], v[190:193], v[214:217], v[42:45]
	v_mfma_f32_16x16x32_bf16 v[34:37], v[198:201], v[214:217], v[34:37]
	v_mfma_f32_16x16x32_bf16 v[26:29], v[190:193], v[222:225], v[26:29]
	v_mfma_f32_16x16x32_bf16 v[18:21], v[198:201], v[222:225], v[18:21]
	v_mfma_f32_16x16x32_bf16 v[10:13], v[190:193], v[230:233], v[10:13]
	v_mfma_f32_16x16x32_bf16 v[2:5], v[198:201], v[230:233], v[2:5]
	s_setprio 0
	s_barrier
	s_add_i32 s65, s65, 2
	s_add_u32 s40, s40, 0x100
	s_addc_u32 s41, s41, 0
	s_add_u32 s63, s63, 0x100
	s_addc_u32 s64, s64, 0
	s_cmp_gt_u32 s65, 13
	s_cbranch_scc0 .LBB0_179
	s_mov_b32 s99, 1
	s_and_b64 vcc, exec, s[18:19]
	s_cbranch_vccz .LBB0_182
	s_barrier

; #define PG8_STAGE(bufoff, gbase, voff) do { _Pragma("unroll") for (int _i = 0; _i < 2; ++_i) \
;         __builtin_amdgcn_global_load_lds((const unsigned*)((const char*)(gbase) + (voff)[_i]), (LAS unsigned*)(lds + (bufoff) + ldsw + _i * 8192), 16, 0, 0); } while (0)
; #define PG8_LDA(dst, b, h) do { _Pragma("unroll") for (int m = 0; m < 4; ++m) _Pragma("unroll") for (int k = 0; k < 2; ++k) dst[m][k] = *(const LAS bf16x8*)(lds + PG8_SA(b, h) + aoff + m * 2048 + k * 1024); } while (0)
; #define PG8_LDB(dst, b, h) do { _Pragma("unroll") for (int n = 0; n < 2; ++n) _Pragma("unroll") for (int k = 0; k < 2; ++k) dst[n][k] = *(const LAS bf16x8*)(lds + PG8_SB(b, h) + boff + n * 2048 + k * 1024); } while (0)
; #define PG8_MMA(ai, bj, At, Bt) do { __builtin_amdgcn_s_setprio(1); _Pragma("unroll") for (int m = 0; m < 4; ++m) _Pragma("unroll") for (int n = 0; n < 2; ++n) _Pragma("unroll") for (int k = 0; k < 2; ++k) \
;         acc[ai][bj][m][n] = __builtin_amdgcn_mfma_f32_16x16x32_bf16(Bt[n][k], At[m][k], acc[ai][bj][m][n], 0, 0, 0); __builtin_amdgcn_s_setprio(0); } while (0)
; #define PG8_WAIT_V(n) asm volatile("s_waitcnt vmcnt(" #n ")" ::: "memory")
; #define PG8_WAIT_L(n) asm volatile("s_waitcnt lgkmcnt(" #n ")" ::: "memory")
; #define PG8_BAR __builtin_amdgcn_s_barrier()
; #define PG8_SCHED __builtin_amdgcn_sched_barrier(0)
; template <class Epi, class Sched>
; DI void gemm_phase(LAS unsigned char* lds, const Gemm g, const Sched& S, const Epi& E) {
;     ...
;             PG8_LDB(B0, 0, 0); PG8_LDB(B1, 0, 1); PG8_SCHED; PG8_LDA(At, 0, 0); PG8_STAGE(PG8_SA(1, 1), a1 + hstepA, voffA);
;             PG8_WAIT_V(8); PG8_WAIT_L(0); PG8_BAR; PG8_MMA(0, 0, At, B0); PG8_MMA(0, 1, At, B1); PG8_BAR; PG8_SCHED;
;             PG8_LDA(At, 0, 1); PG8_STAGE(PG8_SB(0, 0), b2, voffB); PG8_STAGE(PG8_SB(0, 1), b2 + hstepB, voffB); PG8_STAGE(PG8_SA(0, 0), a2, voffA);
;             PG8_WAIT_V(8); PG8_WAIT_L(0); PG8_BAR; PG8_MMA(1, 0, At, B0); PG8_MMA(1, 1, At, B1); PG8_BAR; PG8_SCHED;
;             PG8_LDB(B0, 1, 0); PG8_LDB(B1, 1, 1); PG8_SCHED; PG8_LDA(At, 1, 0); PG8_STAGE(PG8_SA(0, 1), a2 + hstepA, voffA);
;             PG8_WAIT_V(8); PG8_WAIT_L(0); PG8_BAR; PG8_MMA(0, 0, At, B0); PG8_MMA(0, 1, At, B1); PG8_BAR; PG8_SCHED;
.Lpk1_w2:
	s_mov_b32 s99, 0
	s_waitcnt lgkmcnt(0)
	s_nop 0
	s_barrier
	s_setprio 1
	v_mfma_f32_16x16x32_bf16 v[62:65], v[148:151], v[190:193], 0
	v_mfma_f32_16x16x32_bf16 v[58:61], v[162:165], v[190:193], 0
	v_mfma_f32_16x16x32_bf16 v[46:49], v[148:151], v[198:201], 0
	v_mfma_f32_16x16x32_bf16 v[42:45], v[162:165], v[198:201], 0
	v_mfma_f32_16x16x32_bf16 v[30:33], v[148:151], v[206:209], 0
	v_mfma_f32_16x16x32_bf16 v[26:29], v[162:165], v[206:209], 0
	v_mfma_f32_16x16x32_bf16 v[14:17], v[148:151], v[214:217], 0
	v_mfma_f32_16x16x32_bf16 v[10:13], v[162:165], v[214:217], 0
	v_mfma_f32_16x16x32_bf16 v[62:65], v[158:161], v[194:197], v[62:65]
	v_mfma_f32_16x16x32_bf16 v[58:61], v[166:169], v[194:197], v[58:61]
	v_mfma_f32_16x16x32_bf16 v[46:49], v[158:161], v[202:205], v[46:49]
	v_mfma_f32_16x16x32_bf16 v[42:45], v[166:169], v[202:205], v[42:45]
	v_mfma_f32_16x16x32_bf16 v[30:33], v[158:161], v[210:213], v[30:33]
	v_mfma_f32_16x16x32_bf16 v[26:29], v[166:169], v[210:213], v[26:29]
	v_mfma_f32_16x16x32_bf16 v[14:17], v[158:161], v[218:221], v[14:17]
	v_mfma_f32_16x16x32_bf16 v[10:13], v[166:169], v[218:221], v[10:13]
	v_mfma_f32_16x16x32_bf16 v[54:57], v[170:173], v[190:193], 0
	v_mfma_f32_16x16x32_bf16 v[50:53], v[178:181], v[190:193], 0
	v_mfma_f32_16x16x32_bf16 v[38:41], v[170:173], v[198:201], 0
	v_mfma_f32_16x16x32_bf16 v[34:37], v[178:181], v[198:201], 0
	v_mfma_f32_16x16x32_bf16 v[22:25], v[170:173], v[206:209], 0
	v_mfma_f32_16x16x32_bf16 v[18:21], v[178:181], v[206:209], 0
	v_mfma_f32_16x16x32_bf16 v[6:9], v[170:173], v[214:217], 0
	v_mfma_f32_16x16x32_bf16 v[2:5], v[178:181], v[214:217], 0
	v_mfma_f32_16x16x32_bf16 v[54:57], v[174:177], v[194:197], v[54:57]
	v_mfma_f32_16x16x32_bf16 v[50:53], v[186:189], v[194:197], v[50:53]
	v_mfma_f32_16x16x32_bf16 v[38:41], v[174:177], v[202:205], v[38:41]
	v_mfma_f32_16x16x32_bf16 v[34:37], v[186:189], v[202:205], v[34:37]
	v_mfma_f32_16x16x32_bf16 v[22:25], v[174:177], v[210:213], v[22:25]
	v_mfma_f32_16x16x32_bf16 v[18:21], v[186:189], v[210:213], v[18:21]
	v_mfma_f32_16x16x32_bf16 v[6:9], v[174:177], v[218:221], v[6:9]
	v_mfma_f32_16x16x32_bf16 v[2:5], v[186:189], v[218:221], v[2:5]
	s_setprio 0
	s_barrier
	s_add_i32 s63, 0, 0x18000
	s_add_i32 s64, 0, 0x1c000
	v_add_u32_e32 v166, s63, v152
	v_add_u32_e32 v185, s64, v152
	ds_read_b128 v[148:151], v166
	ds_read_b128 v[158:161], v166 offset:1024
	ds_read_b128 v[162:165], v166 offset:2048
	ds_read_b128 v[166:169], v166 offset:3072
	ds_read_b128 v[170:173], v185
	ds_read_b128 v[174:177], v185 offset:1024
	ds_read_b128 v[178:181], v185 offset:2048
	ds_read_b128 v[186:189], v185 offset:3072
	s_add_u32 s40, s40, 0xb0000
	s_addc_u32 s41, s41, 0
	s_mov_b32 m0, s47
	v_lshl_add_u64 v[228:229], s[40:41], 0, v[130:131]
	ds_read_b128 v[190:193], v156 offset:32768
	ds_read_b128 v[194:197], v156 offset:33792
	ds_read_b128 v[198:201], v156 offset:34816
	ds_read_b128 v[202:205], v156 offset:35840
	ds_read_b128 v[206:209], v156 offset:36864
	ds_read_b128 v[210:213], v156 offset:37888
	ds_read_b128 v[214:217], v156 offset:38912
	ds_read_b128 v[218:221], v156 offset:39936
	global_load_lds_dwordx4 v[228:229], off
	v_lshl_add_u64 v[228:229], s[40:41], 0, v[134:135]
	s_mov_b32 m0, s48
	s_nop 0
	global_load_lds_dwordx4 v[228:229], off
	s_waitcnt vmcnt(8)
	s_waitcnt lgkmcnt(0)
	s_barrier
	s_setprio 1
	v_mfma_f32_16x16x32_bf16 v[126:129], v[148:151], v[190:193], v[126:129]
	v_mfma_f32_16x16x32_bf16 v[122:125], v[162:165], v[190:193], v[122:125]
	v_mfma_f32_16x16x32_bf16 v[110:113], v[148:151], v[198:201], v[110:113]
	v_mfma_f32_16x16x32_bf16 v[106:109], v[162:165], v[198:201], v[106:109]
	v_mfma_f32_16x16x32_bf16 v[94:97], v[148:151], v[206:209], v[94:97]
	v_mfma_f32_16x16x32_bf16 v[90:93], v[162:165], v[206:209], v[90:93]
	v_mfma_f32_16x16x32_bf16 v[78:81], v[148:151], v[214:217], v[78:81]
	v_mfma_f32_16x16x32_bf16 v[74:77], v[162:165], v[214:217], v[74:77]
	v_mfma_f32_16x16x32_bf16 v[126:129], v[158:161], v[194:197], v[126:129]
	v_mfma_f32_16x16x32_bf16 v[122:125], v[166:169], v[194:197], v[122:125]
	v_mfma_f32_16x16x32_bf16 v[110:113], v[158:161], v[202:205], v[110:113]
	v_mfma_f32_16x16x32_bf16 v[106:109], v[166:169], v[202:205], v[106:109]
	v_mfma_f32_16x16x32_bf16 v[94:97], v[158:161], v[210:213], v[94:97]
	v_mfma_f32_16x16x32_bf16 v[90:93], v[166:169], v[210:213], v[90:93]
	v_mfma_f32_16x16x32_bf16 v[78:81], v[158:161], v[218:221], v[78:81]
	v_mfma_f32_16x16x32_bf16 v[74:77], v[166:169], v[218:221], v[74:77]
	v_mfma_f32_16x16x32_bf16 v[118:121], v[170:173], v[190:193], v[118:121]
	v_mfma_f32_16x16x32_bf16 v[114:117], v[178:181], v[190:193], v[114:117]
	v_mfma_f32_16x16x32_bf16 v[102:105], v[170:173], v[198:201], v[102:105]
	v_mfma_f32_16x16x32_bf16 v[98:101], v[178:181], v[198:201], v[98:101]
	v_mfma_f32_16x16x32_bf16 v[86:89], v[170:173], v[206:209], v[86:89]
	v_mfma_f32_16x16x32_bf16 v[82:85], v[178:181], v[206:209], v[82:85]
	v_mfma_f32_16x16x32_bf16 v[70:73], v[170:173], v[214:217], v[70:73]
	v_mfma_f32_16x16x32_bf16 v[66:69], v[178:181], v[214:217], v[66:69]
	v_mfma_f32_16x16x32_bf16 v[118:121], v[174:177], v[194:197], v[118:121]
	v_mfma_f32_16x16x32_bf16 v[114:117], v[186:189], v[194:197], v[114:117]
	v_mfma_f32_16x16x32_bf16 v[102:105], v[174:177], v[202:205], v[102:105]
	v_mfma_f32_16x16x32_bf16 v[98:101], v[186:189], v[202:205], v[98:101]
	v_mfma_f32_16x16x32_bf16 v[86:89], v[174:177], v[210:213], v[86:89]
	v_mfma_f32_16x16x32_bf16 v[82:85], v[186:189], v[210:213], v[82:85]
	v_mfma_f32_16x16x32_bf16 v[70:73], v[174:177], v[218:221], v[70:73]
	v_mfma_f32_16x16x32_bf16 v[66:69], v[186:189], v[218:221], v[66:69]
	s_setprio 0
	s_barrier
; #define PG8_STAGE(bufoff, gbase, voff) do { _Pragma("unroll") for (int _i = 0; _i < 2; ++_i) \
;         __builtin_amdgcn_global_load_lds((const unsigned*)((const char*)(gbase) + (voff)[_i]), (LAS unsigned*)(lds + (bufoff) + ldsw + _i * 8192), 16, 0, 0); } while (0)
; #define PG8_LDA(dst, b, h) do { _Pragma("unroll") for (int m = 0; m < 4; ++m) _Pragma("unroll") for (int k = 0; k < 2; ++k) dst[m][k] = *(const LAS bf16x8*)(lds + PG8_SA(b, h) + aoff + m * 2048 + k * 1024); } while (0)
; #define PG8_LDB(dst, b, h) do { _Pragma("unroll") for (int n = 0; n < 2; ++n) _Pragma("unroll") for (int k = 0; k < 2; ++k) dst[n][k] = *(const LAS bf16x8*)(lds + PG8_SB(b, h) + boff + n * 2048 + k * 1024); } while (0)
; #define PG8_MMA(ai, bj, At, Bt) do { __builtin_amdgcn_s_setprio(1); _Pragma("unroll") for (int m = 0; m < 4; ++m) _Pragma("unroll") for (int n = 0; n < 2; ++n) _Pragma("unroll") for (int k = 0; k < 2; ++k) \
;         acc[ai][bj][m][n] = __builtin_amdgcn_mfma_f32_16x16x32_bf16(Bt[n][k], At[m][k], acc[ai][bj][m][n], 0, 0, 0); __builtin_amdgcn_s_setprio(0); } while (0)
; #define PG8_WAIT_V(n) asm volatile("s_waitcnt vmcnt(" #n ")" ::: "memory")
; #define PG8_WAIT_L(n) asm volatile("s_waitcnt lgkmcnt(" #n ")" ::: "memory")
; #define PG8_BAR __builtin_amdgcn_s_barrier()
; #define PG8_SCHED __builtin_amdgcn_sched_barrier(0)
; template <class Epi, class Sched>
; DI void gemm_phase(LAS unsigned char* lds, const Gemm g, const Sched& S, const Epi& E) {
;     ...
;         for (int t = 0; t < nt; t += 2) {
;             const bool last = (t == nt - 2);
;             const char* a1 = cA + (size_t)(t + 1) * kstep;
;             const char* a2 = last ? nA : cA + (size_t)(t + 2) * kstep; const char* b2 = last ? nB : cB + (size_t)(t + 2) * kstep;
;             const char* a3 = a2 + kstep; const char* b3 = b2 + kstep;
;             PG8_LDB(B0, 0, 0); PG8_LDB(B1, 0, 1); PG8_SCHED; PG8_LDA(At, 0, 0); PG8_STAGE(PG8_SA(1, 1), a1 + hstepA, voffA);
;     ...
;             PG8_LDA(At, 1, 1); PG8_STAGE(PG8_SB(1, 0), b3, voffB); PG8_STAGE(PG8_SB(1, 1), b3 + hstepB, voffB); PG8_STAGE(PG8_SA(1, 0), a3, voffA);
;             PG8_WAIT_V(8); PG8_WAIT_L(0); PG8_BAR; PG8_MMA(1, 0, At, B0); PG8_MMA(1, 1, At, B1); PG8_BAR; PG8_SCHED;
	s_add_i32 s40, s63, s44
	v_lshl_add_u64 v[182:183], v[182:183], 0, s[16:17]
	s_mov_b32 m0, s40
	ds_read_b128 v[190:193], v156 offset:49152
	ds_read_b128 v[194:197], v156 offset:50176
	ds_read_b128 v[198:201], v156 offset:51200
	ds_read_b128 v[202:205], v156 offset:52224
	ds_read_b128 v[206:209], v156 offset:53248
	ds_read_b128 v[210:213], v156 offset:54272
	ds_read_b128 v[214:217], v156 offset:55296
	ds_read_b128 v[218:221], v156 offset:56320
	global_load_lds_dwordx4 v[182:183], off
	s_add_i32 m0, s40, 0x2000
	s_add_u32 s38, s38, 0xb0080
	v_lshl_add_u64 v[182:183], v[222:223], 0, s[16:17]
	s_addc_u32 s39, s39, 0
	s_add_i32 s40, s64, s44
	global_load_lds_dwordx4 v[182:183], off
	v_lshl_add_u64 v[182:183], s[38:39], 0, v[132:133]
	s_mov_b32 m0, s40
	s_nop 0
	global_load_lds_dwordx4 v[182:183], off
	v_lshl_add_u64 v[182:183], s[38:39], 0, v[136:137]
	s_add_i32 m0, s40, 0x2000
	s_nop 0
	global_load_lds_dwordx4 v[182:183], off
	v_lshl_add_u64 v[182:183], v[224:225], 0, s[16:17]
	s_mov_b32 m0, s50
	s_nop 0
	global_load_lds_dwordx4 v[182:183], off
	v_lshl_add_u64 v[182:183], v[226:227], 0, s[16:17]
	s_mov_b32 m0, s51
	s_nop 0
	global_load_lds_dwordx4 v[182:183], off
	s_waitcnt vmcnt(8)
	s_waitcnt lgkmcnt(0)
	s_nop 0
	s_barrier
	s_setprio 1
	v_mfma_f32_16x16x32_bf16 v[62:65], v[148:151], v[190:193], v[62:65]
	v_mfma_f32_16x16x32_bf16 v[58:61], v[162:165], v[190:193], v[58:61]
	v_mfma_f32_16x16x32_bf16 v[46:49], v[148:151], v[198:201], v[46:49]
	v_mfma_f32_16x16x32_bf16 v[42:45], v[162:165], v[198:201], v[42:45]
	v_mfma_f32_16x16x32_bf16 v[30:33], v[148:151], v[206:209], v[30:33]
	v_mfma_f32_16x16x32_bf16 v[26:29], v[162:165], v[206:209], v[26:29]
	v_mfma_f32_16x16x32_bf16 v[14:17], v[148:151], v[214:217], v[14:17]
	v_mfma_f32_16x16x32_bf16 v[10:13], v[162:165], v[214:217], v[10:13]
	v_mfma_f32_16x16x32_bf16 v[62:65], v[158:161], v[194:197], v[62:65]
	v_mfma_f32_16x16x32_bf16 v[58:61], v[166:169], v[194:197], v[58:61]
	v_mfma_f32_16x16x32_bf16 v[46:49], v[158:161], v[202:205], v[46:49]
	v_mfma_f32_16x16x32_bf16 v[42:45], v[166:169], v[202:205], v[42:45]
	v_mfma_f32_16x16x32_bf16 v[30:33], v[158:161], v[210:213], v[30:33]
	v_mfma_f32_16x16x32_bf16 v[26:29], v[166:169], v[210:213], v[26:29]
	v_mfma_f32_16x16x32_bf16 v[14:17], v[158:161], v[218:221], v[14:17]
	v_mfma_f32_16x16x32_bf16 v[10:13], v[166:169], v[218:221], v[10:13]
	v_mfma_f32_16x16x32_bf16 v[54:57], v[170:173], v[190:193], v[54:57]
	v_mfma_f32_16x16x32_bf16 v[50:53], v[178:181], v[190:193], v[50:53]
	v_mfma_f32_16x16x32_bf16 v[38:41], v[170:173], v[198:201], v[38:41]
	v_mfma_f32_16x16x32_bf16 v[34:37], v[178:181], v[198:201], v[34:37]
	v_mfma_f32_16x16x32_bf16 v[22:25], v[170:173], v[206:209], v[22:25]
	v_mfma_f32_16x16x32_bf16 v[18:21], v[178:181], v[206:209], v[18:21]
	v_mfma_f32_16x16x32_bf16 v[6:9], v[170:173], v[214:217], v[6:9]
	v_mfma_f32_16x16x32_bf16 v[2:5], v[178:181], v[214:217], v[2:5]
	v_mfma_f32_16x16x32_bf16 v[54:57], v[174:177], v[194:197], v[54:57]
	v_mfma_f32_16x16x32_bf16 v[50:53], v[186:189], v[194:197], v[50:53]
	v_mfma_f32_16x16x32_bf16 v[38:41], v[174:177], v[202:205], v[38:41]
	v_mfma_f32_16x16x32_bf16 v[34:37], v[186:189], v[202:205], v[34:37]
	v_mfma_f32_16x16x32_bf16 v[22:25], v[174:177], v[210:213], v[22:25]
	v_mfma_f32_16x16x32_bf16 v[18:21], v[186:189], v[210:213], v[18:21]
	v_mfma_f32_16x16x32_bf16 v[6:9], v[174:177], v[218:221], v[6:9]
	v_mfma_f32_16x16x32_bf16 v[2:5], v[186:189], v[218:221], v[2:5]
	s_setprio 0
	s_barrier
	s_add_i32 s62, s62, 2
	s_add_u32 s36, s36, 0x100
	s_addc_u32 s37, s37, 0
	s_add_u32 s60, s60, 0x100
	s_addc_u32 s61, s61, 0
	s_cmp_gt_u32 s62, 41
.LBB0_278:
	ds_read_b128 v[148:151], v154
	ds_read_b128 v[158:161], v154 offset:1024
	ds_read_b128 v[162:165], v154 offset:2048
	ds_read_b128 v[166:169], v154 offset:3072
	ds_read_b128 v[170:173], v155
	ds_read_b128 v[174:177], v155 offset:1024
	ds_read_b128 v[178:181], v155 offset:2048
	ds_read_b128 v[186:189], v155 offset:3072
	s_add_u32 s38, s36, 0xfff50080
	s_addc_u32 s39, s37, -1
	s_cmp_eq_u32 s62, 40
	s_cselect_b32 s41, s9, s39
	s_cselect_b32 s40, s8, s38
	s_cselect_b32 s39, s35, s61
	s_cselect_b32 s38, s34, s60
	v_lshl_add_u64 v[182:183], s[36:37], 0, v[138:139]
	s_add_i32 m0, s45, 0xc000
	ds_read_b128 v[190:193], v156
	ds_read_b128 v[194:197], v156 offset:1024
	ds_read_b128 v[198:201], v156 offset:2048
	ds_read_b128 v[202:205], v156 offset:3072
	ds_read_b128 v[206:209], v156 offset:4096
	ds_read_b128 v[210:213], v156 offset:5120
	ds_read_b128 v[214:217], v156 offset:6144
	ds_read_b128 v[218:221], v156 offset:7168
	global_load_lds_dwordx4 v[182:183], off
	v_lshl_add_u64 v[182:183], s[36:37], 0, v[140:141]
	s_add_i32 m0, s45, 0xe000
	s_nop 0
	global_load_lds_dwordx4 v[182:183], off
	s_waitcnt vmcnt(8)
	s_waitcnt lgkmcnt(0)
	s_nop 0
	s_barrier
; #define PG8_STAGE(bufoff, gbase, voff) do { _Pragma("unroll") for (int _i = 0; _i < 2; ++_i) \
;         __builtin_amdgcn_global_load_lds((const unsigned*)((const char*)(gbase) + (voff)[_i]), (LAS unsigned*)(lds + (bufoff) + ldsw + _i * 8192), 16, 0, 0); } while (0)
; #define PG8_LDA(dst, b, h) do { _Pragma("unroll") for (int m = 0; m < 4; ++m) _Pragma("unroll") for (int k = 0; k < 2; ++k) dst[m][k] = *(const LAS bf16x8*)(lds + PG8_SA(b, h) + aoff + m * 2048 + k * 1024); } while (0)
; #define PG8_MMA(ai, bj, At, Bt) do { __builtin_amdgcn_s_setprio(1); _Pragma("unroll") for (int m = 0; m < 4; ++m) _Pragma("unroll") for (int n = 0; n < 2; ++n) _Pragma("unroll") for (int k = 0; k < 2; ++k) \
;         acc[ai][bj][m][n] = __builtin_amdgcn_mfma_f32_16x16x32_bf16(Bt[n][k], At[m][k], acc[ai][bj][m][n], 0, 0, 0); __builtin_amdgcn_s_setprio(0); } while (0)
; #define PG8_WAIT_V(n) asm volatile("s_waitcnt vmcnt(" #n ")" ::: "memory")
; #define PG8_WAIT_L(n) asm volatile("s_waitcnt lgkmcnt(" #n ")" ::: "memory")
; #define PG8_BAR __builtin_amdgcn_s_barrier()
; #define PG8_SCHED __builtin_amdgcn_sched_barrier(0)
; template <class Epi, class Sched>
; DI void gemm_phase(LAS unsigned char* lds, const Gemm g, const Sched& S, const Epi& E) {
;     ...
;             PG8_WAIT_V(8); PG8_WAIT_L(0); PG8_BAR; PG8_MMA(0, 0, At, B0); PG8_MMA(0, 1, At, B1); PG8_BAR; PG8_SCHED;
;             PG8_LDA(At, 0, 1); PG8_STAGE(PG8_SB(0, 0), b2, voffB); PG8_STAGE(PG8_SB(0, 1), b2 + hstepB, voffB); PG8_STAGE(PG8_SA(0, 0), a2, voffA);
;             PG8_WAIT_V(8); PG8_WAIT_L(0); PG8_BAR; PG8_MMA(1, 0, At, B0); PG8_MMA(1, 1, At, B1); PG8_BAR; PG8_SCHED;
	s_setprio 1
	v_mfma_f32_16x16x32_bf16 v[126:129], v[148:151], v[190:193], v[126:129]
	v_mfma_f32_16x16x32_bf16 v[122:125], v[162:165], v[190:193], v[122:125]
	v_mfma_f32_16x16x32_bf16 v[110:113], v[148:151], v[198:201], v[110:113]
	v_mfma_f32_16x16x32_bf16 v[106:109], v[162:165], v[198:201], v[106:109]
	v_mfma_f32_16x16x32_bf16 v[94:97], v[148:151], v[206:209], v[94:97]
	v_mfma_f32_16x16x32_bf16 v[90:93], v[162:165], v[206:209], v[90:93]
	v_mfma_f32_16x16x32_bf16 v[78:81], v[148:151], v[214:217], v[78:81]
	v_mfma_f32_16x16x32_bf16 v[74:77], v[162:165], v[214:217], v[74:77]
	v_mfma_f32_16x16x32_bf16 v[126:129], v[158:161], v[194:197], v[126:129]
	v_mfma_f32_16x16x32_bf16 v[122:125], v[166:169], v[194:197], v[122:125]
	v_mfma_f32_16x16x32_bf16 v[110:113], v[158:161], v[202:205], v[110:113]
	v_mfma_f32_16x16x32_bf16 v[106:109], v[166:169], v[202:205], v[106:109]
	v_mfma_f32_16x16x32_bf16 v[94:97], v[158:161], v[210:213], v[94:97]
	v_mfma_f32_16x16x32_bf16 v[90:93], v[166:169], v[210:213], v[90:93]
	v_mfma_f32_16x16x32_bf16 v[78:81], v[158:161], v[218:221], v[78:81]
	v_mfma_f32_16x16x32_bf16 v[74:77], v[166:169], v[218:221], v[74:77]
	v_mfma_f32_16x16x32_bf16 v[118:121], v[170:173], v[190:193], v[118:121]
	v_mfma_f32_16x16x32_bf16 v[114:117], v[178:181], v[190:193], v[114:117]
	v_mfma_f32_16x16x32_bf16 v[102:105], v[170:173], v[198:201], v[102:105]
	v_mfma_f32_16x16x32_bf16 v[98:101], v[178:181], v[198:201], v[98:101]
	v_mfma_f32_16x16x32_bf16 v[86:89], v[170:173], v[206:209], v[86:89]
	v_mfma_f32_16x16x32_bf16 v[82:85], v[178:181], v[206:209], v[82:85]
	v_mfma_f32_16x16x32_bf16 v[70:73], v[170:173], v[214:217], v[70:73]
	v_mfma_f32_16x16x32_bf16 v[66:69], v[178:181], v[214:217], v[66:69]
	v_mfma_f32_16x16x32_bf16 v[118:121], v[174:177], v[194:197], v[118:121]
	v_mfma_f32_16x16x32_bf16 v[114:117], v[186:189], v[194:197], v[114:117]
	v_mfma_f32_16x16x32_bf16 v[102:105], v[174:177], v[202:205], v[102:105]
	v_mfma_f32_16x16x32_bf16 v[98:101], v[186:189], v[202:205], v[98:101]
	v_mfma_f32_16x16x32_bf16 v[86:89], v[174:177], v[210:213], v[86:89]
	v_mfma_f32_16x16x32_bf16 v[82:85], v[186:189], v[210:213], v[82:85]
	v_mfma_f32_16x16x32_bf16 v[70:73], v[174:177], v[218:221], v[70:73]
	v_mfma_f32_16x16x32_bf16 v[66:69], v[186:189], v[218:221], v[66:69]
	s_setprio 0
	s_barrier
	s_add_i32 s63, s54, s44
	v_lshl_add_u64 v[182:183], s[38:39], 0, v[132:133]
	s_mov_b32 m0, s63
	ds_read_b128 v[190:193], v156 offset:16384
	ds_read_b128 v[194:197], v156 offset:17408
	ds_read_b128 v[198:201], v156 offset:18432
	ds_read_b128 v[202:205], v156 offset:19456
	ds_read_b128 v[206:209], v156 offset:20480
	ds_read_b128 v[210:213], v156 offset:21504
	ds_read_b128 v[214:217], v156 offset:22528
	ds_read_b128 v[218:221], v156 offset:23552
	global_load_lds_dwordx4 v[182:183], off
	s_add_i32 m0, s63, 0x2000
	s_add_u32 s64, s38, 0xb0000
	v_lshl_add_u64 v[222:223], s[38:39], 0, v[136:137]
	s_addc_u32 s65, s39, 0
	s_add_i32 s63, s55, s44
	global_load_lds_dwordx4 v[222:223], off
	v_lshl_add_u64 v[224:225], s[64:65], 0, v[132:133]
	s_mov_b32 m0, s63
	v_lshl_add_u64 v[226:227], s[40:41], 0, v[134:135]
	global_load_lds_dwordx4 v[224:225], off
	v_lshl_add_u64 v[224:225], s[64:65], 0, v[136:137]
	s_add_i32 m0, s63, 0x2000
	s_nop 0
	global_load_lds_dwordx4 v[224:225], off
	v_lshl_add_u64 v[224:225], s[40:41], 0, v[130:131]
	s_mov_b32 m0, s45
	s_nop 0
	global_load_lds_dwordx4 v[224:225], off
	s_mov_b32 m0, s46
	s_nop 0
	global_load_lds_dwordx4 v[226:227], off
	s_waitcnt vmcnt(8)
	s_waitcnt lgkmcnt(0)
	s_barrier
	s_setprio 1
	v_mfma_f32_16x16x32_bf16 v[62:65], v[148:151], v[190:193], v[62:65]
	v_mfma_f32_16x16x32_bf16 v[58:61], v[162:165], v[190:193], v[58:61]
	v_mfma_f32_16x16x32_bf16 v[46:49], v[148:151], v[198:201], v[46:49]
	v_mfma_f32_16x16x32_bf16 v[42:45], v[162:165], v[198:201], v[42:45]
	v_mfma_f32_16x16x32_bf16 v[30:33], v[148:151], v[206:209], v[30:33]
	v_mfma_f32_16x16x32_bf16 v[26:29], v[162:165], v[206:209], v[26:29]
	v_mfma_f32_16x16x32_bf16 v[14:17], v[148:151], v[214:217], v[14:17]
	v_mfma_f32_16x16x32_bf16 v[10:13], v[162:165], v[214:217], v[10:13]
	v_mfma_f32_16x16x32_bf16 v[62:65], v[158:161], v[194:197], v[62:65]
	v_mfma_f32_16x16x32_bf16 v[58:61], v[166:169], v[194:197], v[58:61]
	v_mfma_f32_16x16x32_bf16 v[46:49], v[158:161], v[202:205], v[46:49]
	v_mfma_f32_16x16x32_bf16 v[42:45], v[166:169], v[202:205], v[42:45]
	v_mfma_f32_16x16x32_bf16 v[30:33], v[158:161], v[210:213], v[30:33]
	v_mfma_f32_16x16x32_bf16 v[26:29], v[166:169], v[210:213], v[26:29]
	v_mfma_f32_16x16x32_bf16 v[14:17], v[158:161], v[218:221], v[14:17]
	v_mfma_f32_16x16x32_bf16 v[10:13], v[166:169], v[218:221], v[10:13]
	v_mfma_f32_16x16x32_bf16 v[54:57], v[170:173], v[190:193], v[54:57]
	v_mfma_f32_16x16x32_bf16 v[50:53], v[178:181], v[190:193], v[50:53]
	v_mfma_f32_16x16x32_bf16 v[38:41], v[170:173], v[198:201], v[38:41]
	v_mfma_f32_16x16x32_bf16 v[34:37], v[178:181], v[198:201], v[34:37]
	v_mfma_f32_16x16x32_bf16 v[22:25], v[170:173], v[206:209], v[22:25]
	v_mfma_f32_16x16x32_bf16 v[18:21], v[178:181], v[206:209], v[18:21]
	v_mfma_f32_16x16x32_bf16 v[6:9], v[170:173], v[214:217], v[6:9]
	v_mfma_f32_16x16x32_bf16 v[2:5], v[178:181], v[214:217], v[2:5]
	v_mfma_f32_16x16x32_bf16 v[54:57], v[174:177], v[194:197], v[54:57]
	v_mfma_f32_16x16x32_bf16 v[50:53], v[186:189], v[194:197], v[50:53]
	v_mfma_f32_16x16x32_bf16 v[38:41], v[174:177], v[202:205], v[38:41]
	v_mfma_f32_16x16x32_bf16 v[34:37], v[186:189], v[202:205], v[34:37]
	v_mfma_f32_16x16x32_bf16 v[22:25], v[174:177], v[210:213], v[22:25]
	v_mfma_f32_16x16x32_bf16 v[18:21], v[186:189], v[210:213], v[18:21]
	v_mfma_f32_16x16x32_bf16 v[6:9], v[174:177], v[218:221], v[6:9]
	v_mfma_f32_16x16x32_bf16 v[2:5], v[186:189], v[218:221], v[2:5]
	s_setprio 0
	s_barrier
; #define PG8_STAGE(bufoff, gbase, voff) do { _Pragma("unroll") for (int _i = 0; _i < 2; ++_i) \
;         __builtin_amdgcn_global_load_lds((const unsigned*)((const char*)(gbase) + (voff)[_i]), (LAS unsigned*)(lds + (bufoff) + ldsw + _i * 8192), 16, 0, 0); } while (0)
; #define PG8_LDA(dst, b, h) do { _Pragma("unroll") for (int m = 0; m < 4; ++m) _Pragma("unroll") for (int k = 0; k < 2; ++k) dst[m][k] = *(const LAS bf16x8*)(lds + PG8_SA(b, h) + aoff + m * 2048 + k * 1024); } while (0)
; #define PG8_LDB(dst, b, h) do { _Pragma("unroll") for (int n = 0; n < 2; ++n) _Pragma("unroll") for (int k = 0; k < 2; ++k) dst[n][k] = *(const LAS bf16x8*)(lds + PG8_SB(b, h) + boff + n * 2048 + k * 1024); } while (0)
; #define PG8_MMA(ai, bj, At, Bt) do { __builtin_amdgcn_s_setprio(1); _Pragma("unroll") for (int m = 0; m < 4; ++m) _Pragma("unroll") for (int n = 0; n < 2; ++n) _Pragma("unroll") for (int k = 0; k < 2; ++k) \
;         acc[ai][bj][m][n] = __builtin_amdgcn_mfma_f32_16x16x32_bf16(Bt[n][k], At[m][k], acc[ai][bj][m][n], 0, 0, 0); __builtin_amdgcn_s_setprio(0); } while (0)
; #define PG8_WAIT_V(n) asm volatile("s_waitcnt vmcnt(" #n ")" ::: "memory")
; #define PG8_WAIT_L(n) asm volatile("s_waitcnt lgkmcnt(" #n ")" ::: "memory")
; #define PG8_BAR __builtin_amdgcn_s_barrier()
; #define PG8_SCHED __builtin_amdgcn_sched_barrier(0)
; template <class Epi, class Sched>
; DI void gemm_phase(LAS unsigned char* lds, const Gemm g, const Sched& S, const Epi& E) {
;     ...
;             PG8_LDB(B0, 1, 0); PG8_LDB(B1, 1, 1); PG8_SCHED; PG8_LDA(At, 1, 0); PG8_STAGE(PG8_SA(0, 1), a2 + hstepA, voffA);
;             PG8_WAIT_V(8); PG8_WAIT_L(0); PG8_BAR; PG8_MMA(0, 0, At, B0); PG8_MMA(0, 1, At, B1); PG8_BAR; PG8_SCHED;
	s_add_i32 s63, 0, 0x18000
	s_add_i32 s64, 0, 0x1c000
	v_add_u32_e32 v166, s63, v152
	v_add_u32_e32 v185, s64, v152
	ds_read_b128 v[148:151], v166
	ds_read_b128 v[158:161], v166 offset:1024
	ds_read_b128 v[162:165], v166 offset:2048
	ds_read_b128 v[166:169], v166 offset:3072
	ds_read_b128 v[170:173], v185
	ds_read_b128 v[174:177], v185 offset:1024
	ds_read_b128 v[178:181], v185 offset:2048
	ds_read_b128 v[186:189], v185 offset:3072
	s_add_u32 s40, s40, 0xb0000
	s_addc_u32 s41, s41, 0
	s_mov_b32 m0, s47
	v_lshl_add_u64 v[228:229], s[40:41], 0, v[130:131]
	ds_read_b128 v[190:193], v156 offset:32768
	ds_read_b128 v[194:197], v156 offset:33792
	ds_read_b128 v[198:201], v156 offset:34816
	ds_read_b128 v[202:205], v156 offset:35840
	ds_read_b128 v[206:209], v156 offset:36864
	ds_read_b128 v[210:213], v156 offset:37888
	ds_read_b128 v[214:217], v156 offset:38912
	ds_read_b128 v[218:221], v156 offset:39936
	global_load_lds_dwordx4 v[228:229], off
	v_lshl_add_u64 v[228:229], s[40:41], 0, v[134:135]
	s_mov_b32 m0, s48
	s_nop 0
	global_load_lds_dwordx4 v[228:229], off
	s_waitcnt vmcnt(8)
	s_waitcnt lgkmcnt(0)
	s_barrier
	s_setprio 1
	v_mfma_f32_16x16x32_bf16 v[126:129], v[148:151], v[190:193], v[126:129]
	v_mfma_f32_16x16x32_bf16 v[122:125], v[162:165], v[190:193], v[122:125]
	v_mfma_f32_16x16x32_bf16 v[110:113], v[148:151], v[198:201], v[110:113]
	v_mfma_f32_16x16x32_bf16 v[106:109], v[162:165], v[198:201], v[106:109]
	v_mfma_f32_16x16x32_bf16 v[94:97], v[148:151], v[206:209], v[94:97]
	v_mfma_f32_16x16x32_bf16 v[90:93], v[162:165], v[206:209], v[90:93]
	v_mfma_f32_16x16x32_bf16 v[78:81], v[148:151], v[214:217], v[78:81]
	v_mfma_f32_16x16x32_bf16 v[74:77], v[162:165], v[214:217], v[74:77]
	v_mfma_f32_16x16x32_bf16 v[126:129], v[158:161], v[194:197], v[126:129]
	v_mfma_f32_16x16x32_bf16 v[122:125], v[166:169], v[194:197], v[122:125]
	v_mfma_f32_16x16x32_bf16 v[110:113], v[158:161], v[202:205], v[110:113]
	v_mfma_f32_16x16x32_bf16 v[106:109], v[166:169], v[202:205], v[106:109]
	v_mfma_f32_16x16x32_bf16 v[94:97], v[158:161], v[210:213], v[94:97]
	v_mfma_f32_16x16x32_bf16 v[90:93], v[166:169], v[210:213], v[90:93]
	v_mfma_f32_16x16x32_bf16 v[78:81], v[158:161], v[218:221], v[78:81]
	v_mfma_f32_16x16x32_bf16 v[74:77], v[166:169], v[218:221], v[74:77]
	v_mfma_f32_16x16x32_bf16 v[118:121], v[170:173], v[190:193], v[118:121]
	v_mfma_f32_16x16x32_bf16 v[114:117], v[178:181], v[190:193], v[114:117]
	v_mfma_f32_16x16x32_bf16 v[102:105], v[170:173], v[198:201], v[102:105]
	v_mfma_f32_16x16x32_bf16 v[98:101], v[178:181], v[198:201], v[98:101]
	v_mfma_f32_16x16x32_bf16 v[86:89], v[170:173], v[206:209], v[86:89]
	v_mfma_f32_16x16x32_bf16 v[82:85], v[178:181], v[206:209], v[82:85]
	v_mfma_f32_16x16x32_bf16 v[70:73], v[170:173], v[214:217], v[70:73]
	v_mfma_f32_16x16x32_bf16 v[66:69], v[178:181], v[214:217], v[66:69]
	v_mfma_f32_16x16x32_bf16 v[118:121], v[174:177], v[194:197], v[118:121]
	v_mfma_f32_16x16x32_bf16 v[114:117], v[186:189], v[194:197], v[114:117]
	v_mfma_f32_16x16x32_bf16 v[102:105], v[174:177], v[202:205], v[102:105]
	v_mfma_f32_16x16x32_bf16 v[98:101], v[186:189], v[202:205], v[98:101]
	v_mfma_f32_16x16x32_bf16 v[86:89], v[174:177], v[210:213], v[86:89]
	v_mfma_f32_16x16x32_bf16 v[82:85], v[186:189], v[210:213], v[82:85]
	v_mfma_f32_16x16x32_bf16 v[70:73], v[174:177], v[218:221], v[70:73]
	v_mfma_f32_16x16x32_bf16 v[66:69], v[186:189], v[218:221], v[66:69]
	s_setprio 0
	s_barrier
; #define PG8_STAGE(bufoff, gbase, voff) do { _Pragma("unroll") for (int _i = 0; _i < 2; ++_i) \
;         __builtin_amdgcn_global_load_lds((const unsigned*)((const char*)(gbase) + (voff)[_i]), (LAS unsigned*)(lds + (bufoff) + ldsw + _i * 8192), 16, 0, 0); } while (0)
; #define PG8_LDA(dst, b, h) do { _Pragma("unroll") for (int m = 0; m < 4; ++m) _Pragma("unroll") for (int k = 0; k < 2; ++k) dst[m][k] = *(const LAS bf16x8*)(lds + PG8_SA(b, h) + aoff + m * 2048 + k * 1024); } while (0)
; #define PG8_MMA(ai, bj, At, Bt) do { __builtin_amdgcn_s_setprio(1); _Pragma("unroll") for (int m = 0; m < 4; ++m) _Pragma("unroll") for (int n = 0; n < 2; ++n) _Pragma("unroll") for (int k = 0; k < 2; ++k) \
;         acc[ai][bj][m][n] = __builtin_amdgcn_mfma_f32_16x16x32_bf16(Bt[n][k], At[m][k], acc[ai][bj][m][n], 0, 0, 0); __builtin_amdgcn_s_setprio(0); } while (0)
; #define PG8_WAIT_V(n) asm volatile("s_waitcnt vmcnt(" #n ")" ::: "memory")
; #define PG8_WAIT_L(n) asm volatile("s_waitcnt lgkmcnt(" #n ")" ::: "memory")
; #define PG8_BAR __builtin_amdgcn_s_barrier()
; #define PG8_SCHED __builtin_amdgcn_sched_barrier(0)
;     DI void pre(Pre& pr, const pg8::Unit& u, int wr, int fr) const { load_rows(pr, ssq, u, wr, fr); }
;     DI void pre(Pre& pr, const pg8::Unit& u, int wr, int fr) const { load_rows(pr, ssq, u, wr, fr); }
; template <class Epi, class Sched>
; DI void gemm_phase(LAS unsigned char* lds, const Gemm g, const Sched& S, const Epi& E) {
;     ...
;             PG8_LDA(At, 1, 1); PG8_STAGE(PG8_SB(1, 0), b3, voffB); PG8_STAGE(PG8_SB(1, 1), b3 + hstepB, voffB); PG8_STAGE(PG8_SA(1, 0), a3, voffA);
;             PG8_WAIT_V(8); PG8_WAIT_L(0); PG8_BAR; PG8_MMA(1, 0, At, B0); PG8_MMA(1, 1, At, B1); PG8_BAR; PG8_SCHED;
;         }
;         if (wr == 0) PG8_BAR;
;         E(acc, cur, wr, wc, fr, fq, pre);
;         if (!has_next) break;
	s_add_i32 s40, s63, s44
	v_lshl_add_u64 v[182:183], v[182:183], 0, s[16:17]
	s_mov_b32 m0, s40
	ds_read_b128 v[190:193], v156 offset:49152
	ds_read_b128 v[194:197], v156 offset:50176
	ds_read_b128 v[198:201], v156 offset:51200
	ds_read_b128 v[202:205], v156 offset:52224
	ds_read_b128 v[206:209], v156 offset:53248
	ds_read_b128 v[210:213], v156 offset:54272
	ds_read_b128 v[214:217], v156 offset:55296
	ds_read_b128 v[218:221], v156 offset:56320
	global_load_lds_dwordx4 v[182:183], off
	s_add_i32 m0, s40, 0x2000
	s_add_u32 s38, s38, 0xb0080
	v_lshl_add_u64 v[182:183], v[222:223], 0, s[16:17]
	s_addc_u32 s39, s39, 0
	s_add_i32 s40, s64, s44
	global_load_lds_dwordx4 v[182:183], off
	v_lshl_add_u64 v[182:183], s[38:39], 0, v[132:133]
	s_mov_b32 m0, s40
	s_nop 0
	global_load_lds_dwordx4 v[182:183], off
	v_lshl_add_u64 v[182:183], s[38:39], 0, v[136:137]
	s_add_i32 m0, s40, 0x2000
	s_nop 0
	global_load_lds_dwordx4 v[182:183], off
	v_lshl_add_u64 v[182:183], v[224:225], 0, s[16:17]
	s_mov_b32 m0, s50
	s_nop 0
	global_load_lds_dwordx4 v[182:183], off
	v_lshl_add_u64 v[182:183], v[226:227], 0, s[16:17]
	s_mov_b32 m0, s51
	s_nop 0
	global_load_lds_dwordx4 v[182:183], off
	s_waitcnt vmcnt(8)
	s_waitcnt lgkmcnt(0)
	s_nop 0
	s_barrier
	s_setprio 1
	v_mfma_f32_16x16x32_bf16 v[62:65], v[148:151], v[190:193], v[62:65]
	v_mfma_f32_16x16x32_bf16 v[58:61], v[162:165], v[190:193], v[58:61]
	v_mfma_f32_16x16x32_bf16 v[46:49], v[148:151], v[198:201], v[46:49]
	v_mfma_f32_16x16x32_bf16 v[42:45], v[162:165], v[198:201], v[42:45]
	v_mfma_f32_16x16x32_bf16 v[30:33], v[148:151], v[206:209], v[30:33]
	v_mfma_f32_16x16x32_bf16 v[26:29], v[162:165], v[206:209], v[26:29]
	v_mfma_f32_16x16x32_bf16 v[14:17], v[148:151], v[214:217], v[14:17]
	v_mfma_f32_16x16x32_bf16 v[10:13], v[162:165], v[214:217], v[10:13]
	v_mfma_f32_16x16x32_bf16 v[62:65], v[158:161], v[194:197], v[62:65]
	v_mfma_f32_16x16x32_bf16 v[58:61], v[166:169], v[194:197], v[58:61]
	v_mfma_f32_16x16x32_bf16 v[46:49], v[158:161], v[202:205], v[46:49]
	v_mfma_f32_16x16x32_bf16 v[42:45], v[166:169], v[202:205], v[42:45]
	v_mfma_f32_16x16x32_bf16 v[30:33], v[158:161], v[210:213], v[30:33]
	v_mfma_f32_16x16x32_bf16 v[26:29], v[166:169], v[210:213], v[26:29]
	v_mfma_f32_16x16x32_bf16 v[14:17], v[158:161], v[218:221], v[14:17]
	v_mfma_f32_16x16x32_bf16 v[10:13], v[166:169], v[218:221], v[10:13]
	v_mfma_f32_16x16x32_bf16 v[54:57], v[170:173], v[190:193], v[54:57]
	v_mfma_f32_16x16x32_bf16 v[50:53], v[178:181], v[190:193], v[50:53]
	v_mfma_f32_16x16x32_bf16 v[38:41], v[170:173], v[198:201], v[38:41]
	v_mfma_f32_16x16x32_bf16 v[34:37], v[178:181], v[198:201], v[34:37]
	v_mfma_f32_16x16x32_bf16 v[22:25], v[170:173], v[206:209], v[22:25]
	v_mfma_f32_16x16x32_bf16 v[18:21], v[178:181], v[206:209], v[18:21]
	v_mfma_f32_16x16x32_bf16 v[6:9], v[170:173], v[214:217], v[6:9]
	v_mfma_f32_16x16x32_bf16 v[2:5], v[178:181], v[214:217], v[2:5]
	v_mfma_f32_16x16x32_bf16 v[54:57], v[174:177], v[194:197], v[54:57]
	v_mfma_f32_16x16x32_bf16 v[50:53], v[186:189], v[194:197], v[50:53]
	v_mfma_f32_16x16x32_bf16 v[38:41], v[174:177], v[202:205], v[38:41]
	v_mfma_f32_16x16x32_bf16 v[34:37], v[186:189], v[202:205], v[34:37]
	v_mfma_f32_16x16x32_bf16 v[22:25], v[174:177], v[210:213], v[22:25]
	v_mfma_f32_16x16x32_bf16 v[18:21], v[186:189], v[210:213], v[18:21]
	v_mfma_f32_16x16x32_bf16 v[6:9], v[174:177], v[218:221], v[6:9]
	v_mfma_f32_16x16x32_bf16 v[2:5], v[186:189], v[218:221], v[2:5]
	s_setprio 0
	s_barrier
	s_add_i32 s62, s62, 2
	s_add_u32 s36, s36, 0x100
	s_addc_u32 s37, s37, 0
	s_add_u32 s60, s60, 0x100
	s_addc_u32 s61, s61, 0
	s_cmp_gt_u32 s62, 41
	s_cbranch_scc0 .LBB0_278
	s_mov_b32 s99, 1
	s_and_b64 vcc, exec, s[18:19]
	s_cbranch_vccz .LBB0_281
	s_barrier

; #define PG8_STAGE(bufoff, gbase, voff) do { _Pragma("unroll") for (int _i = 0; _i < 2; ++_i) \
;         __builtin_amdgcn_global_load_lds((const unsigned*)((const char*)(gbase) + (voff)[_i]), (LAS unsigned*)(lds + (bufoff) + ldsw + _i * 8192), 16, 0, 0); } while (0)
; #define PG8_LDA(dst, b, h) do { _Pragma("unroll") for (int m = 0; m < 4; ++m) _Pragma("unroll") for (int k = 0; k < 2; ++k) dst[m][k] = *(const LAS bf16x8*)(lds + PG8_SA(b, h) + aoff + m * 2048 + k * 1024); } while (0)
; #define PG8_LDB(dst, b, h) do { _Pragma("unroll") for (int n = 0; n < 2; ++n) _Pragma("unroll") for (int k = 0; k < 2; ++k) dst[n][k] = *(const LAS bf16x8*)(lds + PG8_SB(b, h) + boff + n * 2048 + k * 1024); } while (0)
; #define PG8_MMA(ai, bj, At, Bt) do { __builtin_amdgcn_s_setprio(1); _Pragma("unroll") for (int m = 0; m < 4; ++m) _Pragma("unroll") for (int n = 0; n < 2; ++n) _Pragma("unroll") for (int k = 0; k < 2; ++k) \
;         acc[ai][bj][m][n] = __builtin_amdgcn_mfma_f32_16x16x32_bf16(Bt[n][k], At[m][k], acc[ai][bj][m][n], 0, 0, 0); __builtin_amdgcn_s_setprio(0); } while (0)
; #define PG8_WAIT_V(n) asm volatile("s_waitcnt vmcnt(" #n ")" ::: "memory")
; #define PG8_WAIT_L(n) asm volatile("s_waitcnt lgkmcnt(" #n ")" ::: "memory")
; template <class Epi, class Sched>
; DI void gemm_phase(LAS unsigned char* lds, const Gemm g, const Sched& S, const Epi& E) {
;     ...
;             PG8_LDB(B0, 0, 0); PG8_LDB(B1, 0, 1); PG8_SCHED; PG8_LDA(At, 0, 0); PG8_STAGE(PG8_SA(1, 1), a1 + hstepA, voffA);
;             PG8_WAIT_V(8); PG8_WAIT_L(0); PG8_BAR; PG8_MMA(0, 0, At, B0); PG8_MMA(0, 1, At, B1); PG8_BAR; PG8_SCHED;
;             PG8_LDA(At, 0, 1); PG8_STAGE(PG8_SB(0, 0), b2, voffB); PG8_STAGE(PG8_SB(0, 1), b2 + hstepB, voffB); PG8_STAGE(PG8_SA(0, 0), a2, voffA);
;             PG8_WAIT_V(8); PG8_WAIT_L(0); PG8_BAR; PG8_MMA(1, 0, At, B0); PG8_MMA(1, 1, At, B1); PG8_BAR; PG8_SCHED;
;             PG8_LDB(B0, 1, 0); PG8_LDB(B1, 1, 1); PG8_SCHED; PG8_LDA(At, 1, 0); PG8_STAGE(PG8_SA(0, 1), a2 + hstepA, voffA);
;             PG8_WAIT_V(8); PG8_WAIT_L(0); PG8_BAR; PG8_MMA(0, 0, At, B0); PG8_MMA(0, 1, At, B1); PG8_BAR; PG8_SCHED;
;             PG8_LDA(At, 1, 1); PG8_STAGE(PG8_SB(1, 0), b3, voffB); PG8_STAGE(PG8_SB(1, 1), b3 + hstepB, voffB); PG8_STAGE(PG8_SA(1, 0), a3, voffA);
;             PG8_WAIT_V(8); PG8_WAIT_L(0); PG8_BAR; PG8_MMA(1, 0, At, B0); PG8_MMA(1, 1, At, B1); PG8_BAR; PG8_SCHED;
.Lpk2_w2:
	s_mov_b32 s99, 0
	s_waitcnt lgkmcnt(0)
	s_nop 0
	s_barrier
	s_setprio 1
	v_mfma_f32_16x16x32_bf16 v[62:65], v[138:141], v[218:221], 0
	v_mfma_f32_16x16x32_bf16 v[58:61], v[176:179], v[218:221], 0
	v_mfma_f32_16x16x32_bf16 v[46:49], v[138:141], v[226:229], 0
	v_mfma_f32_16x16x32_bf16 v[42:45], v[176:179], v[226:229], 0
	v_mfma_f32_16x16x32_bf16 v[30:33], v[138:141], v[234:237], 0
	v_mfma_f32_16x16x32_bf16 v[26:29], v[176:179], v[234:237], 0
	v_mfma_f32_16x16x32_bf16 v[14:17], v[138:141], v[242:245], 0
	v_mfma_f32_16x16x32_bf16 v[10:13], v[176:179], v[242:245], 0
	v_mfma_f32_16x16x32_bf16 v[62:65], v[142:145], v[222:225], v[62:65]
	v_mfma_f32_16x16x32_bf16 v[58:61], v[198:201], v[222:225], v[58:61]
	v_mfma_f32_16x16x32_bf16 v[46:49], v[142:145], v[230:233], v[46:49]
	v_mfma_f32_16x16x32_bf16 v[42:45], v[198:201], v[230:233], v[42:45]
	v_mfma_f32_16x16x32_bf16 v[30:33], v[142:145], v[238:241], v[30:33]
	v_mfma_f32_16x16x32_bf16 v[26:29], v[198:201], v[238:241], v[26:29]
	v_mfma_f32_16x16x32_bf16 v[14:17], v[142:145], v[246:249], v[14:17]
	v_mfma_f32_16x16x32_bf16 v[10:13], v[198:201], v[246:249], v[10:13]
	v_mfma_f32_16x16x32_bf16 v[54:57], v[202:205], v[218:221], 0
	v_mfma_f32_16x16x32_bf16 v[50:53], v[210:213], v[218:221], 0
	v_mfma_f32_16x16x32_bf16 v[38:41], v[202:205], v[226:229], 0
	v_mfma_f32_16x16x32_bf16 v[34:37], v[210:213], v[226:229], 0
	v_mfma_f32_16x16x32_bf16 v[22:25], v[202:205], v[234:237], 0
	v_mfma_f32_16x16x32_bf16 v[18:21], v[210:213], v[234:237], 0
	v_mfma_f32_16x16x32_bf16 v[6:9], v[202:205], v[242:245], 0
	v_mfma_f32_16x16x32_bf16 v[2:5], v[210:213], v[242:245], 0
	v_mfma_f32_16x16x32_bf16 v[54:57], v[206:209], v[222:225], v[54:57]
	v_mfma_f32_16x16x32_bf16 v[50:53], v[214:217], v[222:225], v[50:53]
	v_mfma_f32_16x16x32_bf16 v[38:41], v[206:209], v[230:233], v[38:41]
	v_mfma_f32_16x16x32_bf16 v[34:37], v[214:217], v[230:233], v[34:37]
	v_mfma_f32_16x16x32_bf16 v[22:25], v[206:209], v[238:241], v[22:25]
	v_mfma_f32_16x16x32_bf16 v[18:21], v[214:217], v[238:241], v[18:21]
	v_mfma_f32_16x16x32_bf16 v[6:9], v[206:209], v[246:249], v[6:9]
	v_mfma_f32_16x16x32_bf16 v[2:5], v[214:217], v[246:249], v[2:5]
	s_setprio 0
	s_barrier
	s_add_i32 s70, 0, 0x18000
	v_add_u32_e32 v156, s70, v159
	s_add_i32 s71, 0, 0x1c000
	ds_read_b128 v[138:141], v156
	ds_read_b128 v[142:145], v156 offset:1024
	ds_read_b128 v[176:179], v156 offset:2048
	ds_read_b128 v[198:201], v156 offset:3072
	v_add_u32_e32 v156, s71, v159
	ds_read_b128 v[202:205], v156
	ds_read_b128 v[206:209], v156 offset:1024
	ds_read_b128 v[210:213], v156 offset:2048
	ds_read_b128 v[214:217], v156 offset:3072
	s_add_u32 s66, s66, 0x40000
	s_addc_u32 s67, s67, 0
	s_mov_b32 m0, s81
	v_lshl_add_u64 v[254:255], s[66:67], 0, v[148:149]
	ds_read_b128 v[218:221], v186 offset:32768
	ds_read_b128 v[222:225], v186 offset:33792
	ds_read_b128 v[226:229], v186 offset:34816
	ds_read_b128 v[230:233], v186 offset:35840
	ds_read_b128 v[234:237], v186 offset:36864
	ds_read_b128 v[238:241], v186 offset:37888
	ds_read_b128 v[242:245], v186 offset:38912
	ds_read_b128 v[246:249], v186 offset:39936
	global_load_lds_dwordx4 v[254:255], off
	v_lshl_add_u64 v[254:255], s[66:67], 0, v[152:153]
	s_mov_b32 m0, s82
	s_nop 0
	global_load_lds_dwordx4 v[254:255], off
	s_waitcnt vmcnt(8)
	s_waitcnt lgkmcnt(0)
	s_barrier
	s_setprio 1
	v_mfma_f32_16x16x32_bf16 v[126:129], v[138:141], v[218:221], v[126:129]
	v_mfma_f32_16x16x32_bf16 v[122:125], v[176:179], v[218:221], v[122:125]
	v_mfma_f32_16x16x32_bf16 v[110:113], v[138:141], v[226:229], v[110:113]
	v_mfma_f32_16x16x32_bf16 v[106:109], v[176:179], v[226:229], v[106:109]
	v_mfma_f32_16x16x32_bf16 v[94:97], v[138:141], v[234:237], v[94:97]
	v_mfma_f32_16x16x32_bf16 v[90:93], v[176:179], v[234:237], v[90:93]
	v_mfma_f32_16x16x32_bf16 v[78:81], v[138:141], v[242:245], v[78:81]
	v_mfma_f32_16x16x32_bf16 v[74:77], v[176:179], v[242:245], v[74:77]
	v_mfma_f32_16x16x32_bf16 v[126:129], v[142:145], v[222:225], v[126:129]
	v_mfma_f32_16x16x32_bf16 v[122:125], v[198:201], v[222:225], v[122:125]
	v_mfma_f32_16x16x32_bf16 v[110:113], v[142:145], v[230:233], v[110:113]
	v_mfma_f32_16x16x32_bf16 v[106:109], v[198:201], v[230:233], v[106:109]
	v_mfma_f32_16x16x32_bf16 v[94:97], v[142:145], v[238:241], v[94:97]
	v_mfma_f32_16x16x32_bf16 v[90:93], v[198:201], v[238:241], v[90:93]
	v_mfma_f32_16x16x32_bf16 v[78:81], v[142:145], v[246:249], v[78:81]
	v_mfma_f32_16x16x32_bf16 v[74:77], v[198:201], v[246:249], v[74:77]
	v_mfma_f32_16x16x32_bf16 v[118:121], v[202:205], v[218:221], v[118:121]
	v_mfma_f32_16x16x32_bf16 v[114:117], v[210:213], v[218:221], v[114:117]
	v_mfma_f32_16x16x32_bf16 v[102:105], v[202:205], v[226:229], v[102:105]
	v_mfma_f32_16x16x32_bf16 v[98:101], v[210:213], v[226:229], v[98:101]
	v_mfma_f32_16x16x32_bf16 v[86:89], v[202:205], v[234:237], v[86:89]
	v_mfma_f32_16x16x32_bf16 v[82:85], v[210:213], v[234:237], v[82:85]
	v_mfma_f32_16x16x32_bf16 v[70:73], v[202:205], v[242:245], v[70:73]
	v_mfma_f32_16x16x32_bf16 v[66:69], v[210:213], v[242:245], v[66:69]
	v_mfma_f32_16x16x32_bf16 v[118:121], v[206:209], v[222:225], v[118:121]
	v_mfma_f32_16x16x32_bf16 v[114:117], v[214:217], v[222:225], v[114:117]
	v_mfma_f32_16x16x32_bf16 v[102:105], v[206:209], v[230:233], v[102:105]
	v_mfma_f32_16x16x32_bf16 v[98:101], v[214:217], v[230:233], v[98:101]
	v_mfma_f32_16x16x32_bf16 v[86:89], v[206:209], v[238:241], v[86:89]
	v_mfma_f32_16x16x32_bf16 v[82:85], v[214:217], v[238:241], v[82:85]
	v_mfma_f32_16x16x32_bf16 v[70:73], v[206:209], v[246:249], v[70:73]
	v_mfma_f32_16x16x32_bf16 v[66:69], v[214:217], v[246:249], v[66:69]
	s_setprio 0
	s_barrier
; #define PG8_STAGE(bufoff, gbase, voff) do { _Pragma("unroll") for (int _i = 0; _i < 2; ++_i) \
;         __builtin_amdgcn_global_load_lds((const unsigned*)((const char*)(gbase) + (voff)[_i]), (LAS unsigned*)(lds + (bufoff) + ldsw + _i * 8192), 16, 0, 0); } while (0)
; #define PG8_LDA(dst, b, h) do { _Pragma("unroll") for (int m = 0; m < 4; ++m) _Pragma("unroll") for (int k = 0; k < 2; ++k) dst[m][k] = *(const LAS bf16x8*)(lds + PG8_SA(b, h) + aoff + m * 2048 + k * 1024); } while (0)
; #define PG8_LDB(dst, b, h) do { _Pragma("unroll") for (int n = 0; n < 2; ++n) _Pragma("unroll") for (int k = 0; k < 2; ++k) dst[n][k] = *(const LAS bf16x8*)(lds + PG8_SB(b, h) + boff + n * 2048 + k * 1024); } while (0)
; #define PG8_MMA(ai, bj, At, Bt) do { __builtin_amdgcn_s_setprio(1); _Pragma("unroll") for (int m = 0; m < 4; ++m) _Pragma("unroll") for (int n = 0; n < 2; ++n) _Pragma("unroll") for (int k = 0; k < 2; ++k) \
;         acc[ai][bj][m][n] = __builtin_amdgcn_mfma_f32_16x16x32_bf16(Bt[n][k], At[m][k], acc[ai][bj][m][n], 0, 0, 0); __builtin_amdgcn_s_setprio(0); } while (0)
; #define PG8_WAIT_V(n) asm volatile("s_waitcnt vmcnt(" #n ")" ::: "memory")
; #define PG8_WAIT_L(n) asm volatile("s_waitcnt lgkmcnt(" #n ")" ::: "memory")
; template <class Epi, class Sched>
; DI void gemm_phase(LAS unsigned char* lds, const Gemm g, const Sched& S, const Epi& E) {
;     ...
;             PG8_LDB(B0, 0, 0); PG8_LDB(B1, 0, 1); PG8_SCHED; PG8_LDA(At, 0, 0); PG8_STAGE(PG8_SA(1, 1), a1 + hstepA, voffA);
;             PG8_WAIT_V(8); PG8_WAIT_L(0); PG8_BAR; PG8_MMA(0, 0, At, B0); PG8_MMA(0, 1, At, B1); PG8_BAR; PG8_SCHED;
;             PG8_LDA(At, 0, 1); PG8_STAGE(PG8_SB(0, 0), b2, voffB); PG8_STAGE(PG8_SB(0, 1), b2 + hstepB, voffB); PG8_STAGE(PG8_SA(0, 0), a2, voffA);
;             PG8_WAIT_V(8); PG8_WAIT_L(0); PG8_BAR; PG8_MMA(1, 0, At, B0); PG8_MMA(1, 1, At, B1); PG8_BAR; PG8_SCHED;
;             PG8_LDB(B0, 1, 0); PG8_LDB(B1, 1, 1); PG8_SCHED; PG8_LDA(At, 1, 0); PG8_STAGE(PG8_SA(0, 1), a2 + hstepA, voffA);
;             PG8_WAIT_V(8); PG8_WAIT_L(0); PG8_BAR; PG8_MMA(0, 0, At, B0); PG8_MMA(0, 1, At, B1); PG8_BAR; PG8_SCHED;
;             PG8_LDA(At, 1, 1); PG8_STAGE(PG8_SB(1, 0), b3, voffB); PG8_STAGE(PG8_SB(1, 1), b3 + hstepB, voffB); PG8_STAGE(PG8_SA(1, 0), a3, voffA);
;             PG8_WAIT_V(8); PG8_WAIT_L(0); PG8_BAR; PG8_MMA(1, 0, At, B0); PG8_MMA(1, 1, At, B1); PG8_BAR; PG8_SCHED;
	s_add_i32 s66, s70, s78
	v_lshl_add_u64 v[172:173], v[172:173], 0, s[50:51]
	s_mov_b32 m0, s66
	ds_read_b128 v[218:221], v186 offset:49152
	ds_read_b128 v[222:225], v186 offset:50176
	ds_read_b128 v[226:229], v186 offset:51200
	ds_read_b128 v[230:233], v186 offset:52224
	ds_read_b128 v[234:237], v186 offset:53248
	ds_read_b128 v[238:241], v186 offset:54272
	ds_read_b128 v[242:245], v186 offset:55296
	ds_read_b128 v[246:249], v186 offset:56320
	global_load_lds_dwordx4 v[172:173], off
	s_add_i32 m0, s66, 0x2000
	s_add_u32 s64, s64, 0x40080
	v_lshl_add_u64 v[172:173], v[180:181], 0, s[50:51]
	s_addc_u32 s65, s65, 0
	s_add_i32 s66, s71, s78
	global_load_lds_dwordx4 v[172:173], off
	v_lshl_add_u64 v[172:173], s[64:65], 0, v[150:151]
	s_mov_b32 m0, s66
	s_nop 0
	global_load_lds_dwordx4 v[172:173], off
	v_lshl_add_u64 v[172:173], s[64:65], 0, v[154:155]
	s_add_i32 m0, s66, 0x2000
	s_nop 0
	global_load_lds_dwordx4 v[172:173], off
	v_lshl_add_u64 v[172:173], v[250:251], 0, s[50:51]
	s_mov_b32 m0, s86
	s_nop 0
	global_load_lds_dwordx4 v[172:173], off
	v_lshl_add_u64 v[172:173], v[252:253], 0, s[50:51]
	s_mov_b32 m0, s87
	s_nop 0
	global_load_lds_dwordx4 v[172:173], off
	s_waitcnt vmcnt(8)
	s_waitcnt lgkmcnt(0)
	s_nop 0
	s_barrier
	s_setprio 1
	v_mfma_f32_16x16x32_bf16 v[62:65], v[138:141], v[218:221], v[62:65]
	v_mfma_f32_16x16x32_bf16 v[58:61], v[176:179], v[218:221], v[58:61]
	v_mfma_f32_16x16x32_bf16 v[46:49], v[138:141], v[226:229], v[46:49]
	v_mfma_f32_16x16x32_bf16 v[42:45], v[176:179], v[226:229], v[42:45]
	v_mfma_f32_16x16x32_bf16 v[30:33], v[138:141], v[234:237], v[30:33]
	v_mfma_f32_16x16x32_bf16 v[26:29], v[176:179], v[234:237], v[26:29]
	v_mfma_f32_16x16x32_bf16 v[14:17], v[138:141], v[242:245], v[14:17]
	v_mfma_f32_16x16x32_bf16 v[10:13], v[176:179], v[242:245], v[10:13]
	v_mfma_f32_16x16x32_bf16 v[62:65], v[142:145], v[222:225], v[62:65]
	v_mfma_f32_16x16x32_bf16 v[58:61], v[198:201], v[222:225], v[58:61]
	v_mfma_f32_16x16x32_bf16 v[46:49], v[142:145], v[230:233], v[46:49]
	v_mfma_f32_16x16x32_bf16 v[42:45], v[198:201], v[230:233], v[42:45]
	v_mfma_f32_16x16x32_bf16 v[30:33], v[142:145], v[238:241], v[30:33]
	v_mfma_f32_16x16x32_bf16 v[26:29], v[198:201], v[238:241], v[26:29]
	v_mfma_f32_16x16x32_bf16 v[14:17], v[142:145], v[246:249], v[14:17]
	v_mfma_f32_16x16x32_bf16 v[10:13], v[198:201], v[246:249], v[10:13]
	v_mfma_f32_16x16x32_bf16 v[54:57], v[202:205], v[218:221], v[54:57]
	v_mfma_f32_16x16x32_bf16 v[50:53], v[210:213], v[218:221], v[50:53]
	v_mfma_f32_16x16x32_bf16 v[38:41], v[202:205], v[226:229], v[38:41]
	v_mfma_f32_16x16x32_bf16 v[34:37], v[210:213], v[226:229], v[34:37]
	v_mfma_f32_16x16x32_bf16 v[22:25], v[202:205], v[234:237], v[22:25]
	v_mfma_f32_16x16x32_bf16 v[18:21], v[210:213], v[234:237], v[18:21]
	v_mfma_f32_16x16x32_bf16 v[6:9], v[202:205], v[242:245], v[6:9]
	v_mfma_f32_16x16x32_bf16 v[2:5], v[210:213], v[242:245], v[2:5]
	v_mfma_f32_16x16x32_bf16 v[54:57], v[206:209], v[222:225], v[54:57]
	v_mfma_f32_16x16x32_bf16 v[50:53], v[214:217], v[222:225], v[50:53]
	v_mfma_f32_16x16x32_bf16 v[38:41], v[206:209], v[230:233], v[38:41]
	v_mfma_f32_16x16x32_bf16 v[34:37], v[214:217], v[230:233], v[34:37]
	v_mfma_f32_16x16x32_bf16 v[22:25], v[206:209], v[238:241], v[22:25]
	v_mfma_f32_16x16x32_bf16 v[18:21], v[214:217], v[238:241], v[18:21]
	v_mfma_f32_16x16x32_bf16 v[6:9], v[206:209], v[246:249], v[6:9]
	v_mfma_f32_16x16x32_bf16 v[2:5], v[214:217], v[246:249], v[2:5]
	s_setprio 0
	s_barrier
	s_add_i32 s69, s69, 2
	s_add_u32 s10, s10, 0x100
	s_addc_u32 s11, s11, 0
	s_add_u32 s59, s59, 0x100
	s_addc_u32 s68, s68, 0
	s_cmp_gt_u32 s69, 13
.LBB0_381:
	ds_read_b128 v[138:141], v188
	ds_read_b128 v[142:145], v188 offset:1024
	ds_read_b128 v[176:179], v188 offset:2048
	ds_read_b128 v[198:201], v188 offset:3072
	ds_read_b128 v[202:205], v189
	ds_read_b128 v[206:209], v189 offset:1024
	ds_read_b128 v[210:213], v189 offset:2048
	ds_read_b128 v[214:217], v189 offset:3072
	s_add_u32 s64, s10, 0xfffc0080
	s_addc_u32 s65, s11, -1
	s_cmp_eq_u32 s69, 12
	s_cselect_b32 s67, s13, s65
	s_cselect_b32 s66, s29, s64
	s_cselect_b32 s65, s36, s68
	s_cselect_b32 s64, s57, s59
	v_lshl_add_u64 v[172:173], s[10:11], 0, v[162:163]
	s_add_i32 m0, s79, 0xc000
	ds_read_b128 v[218:221], v186
	ds_read_b128 v[222:225], v186 offset:1024
	ds_read_b128 v[226:229], v186 offset:2048
	ds_read_b128 v[230:233], v186 offset:3072
	ds_read_b128 v[234:237], v186 offset:4096
	ds_read_b128 v[238:241], v186 offset:5120
	ds_read_b128 v[242:245], v186 offset:6144
	ds_read_b128 v[246:249], v186 offset:7168
	global_load_lds_dwordx4 v[172:173], off
	v_lshl_add_u64 v[172:173], s[10:11], 0, v[164:165]
	s_add_i32 m0, s79, 0xe000
	s_nop 0
	global_load_lds_dwordx4 v[172:173], off
	s_waitcnt vmcnt(8)
	s_waitcnt lgkmcnt(0)
	s_nop 0
	s_barrier
; #define PG8_STAGE(bufoff, gbase, voff) do { _Pragma("unroll") for (int _i = 0; _i < 2; ++_i) \
;         __builtin_amdgcn_global_load_lds((const unsigned*)((const char*)(gbase) + (voff)[_i]), (LAS unsigned*)(lds + (bufoff) + ldsw + _i * 8192), 16, 0, 0); } while (0)
; #define PG8_LDA(dst, b, h) do { _Pragma("unroll") for (int m = 0; m < 4; ++m) _Pragma("unroll") for (int k = 0; k < 2; ++k) dst[m][k] = *(const LAS bf16x8*)(lds + PG8_SA(b, h) + aoff + m * 2048 + k * 1024); } while (0)
; #define PG8_LDB(dst, b, h) do { _Pragma("unroll") for (int n = 0; n < 2; ++n) _Pragma("unroll") for (int k = 0; k < 2; ++k) dst[n][k] = *(const LAS bf16x8*)(lds + PG8_SB(b, h) + boff + n * 2048 + k * 1024); } while (0)
; #define PG8_MMA(ai, bj, At, Bt) do { __builtin_amdgcn_s_setprio(1); _Pragma("unroll") for (int m = 0; m < 4; ++m) _Pragma("unroll") for (int n = 0; n < 2; ++n) _Pragma("unroll") for (int k = 0; k < 2; ++k) \
;         acc[ai][bj][m][n] = __builtin_amdgcn_mfma_f32_16x16x32_bf16(Bt[n][k], At[m][k], acc[ai][bj][m][n], 0, 0, 0); __builtin_amdgcn_s_setprio(0); } while (0)
; #define PG8_WAIT_V(n) asm volatile("s_waitcnt vmcnt(" #n ")" ::: "memory")
; #define PG8_WAIT_L(n) asm volatile("s_waitcnt lgkmcnt(" #n ")" ::: "memory")
; #define PG8_BAR __builtin_amdgcn_s_barrier()
; #define PG8_SCHED __builtin_amdgcn_sched_barrier(0)
; template <class Epi, class Sched>
; DI void gemm_phase(LAS unsigned char* lds, const Gemm g, const Sched& S, const Epi& E) {
;     ...
;             PG8_LDB(B0, 0, 0); PG8_LDB(B1, 0, 1); PG8_SCHED; PG8_LDA(At, 0, 0); PG8_STAGE(PG8_SA(1, 1), a1 + hstepA, voffA);
;             PG8_WAIT_V(8); PG8_WAIT_L(0); PG8_BAR; PG8_MMA(0, 0, At, B0); PG8_MMA(0, 1, At, B1); PG8_BAR; PG8_SCHED;
;             PG8_LDA(At, 0, 1); PG8_STAGE(PG8_SB(0, 0), b2, voffB); PG8_STAGE(PG8_SB(0, 1), b2 + hstepB, voffB); PG8_STAGE(PG8_SA(0, 0), a2, voffA);
;             PG8_WAIT_V(8); PG8_WAIT_L(0); PG8_BAR; PG8_MMA(1, 0, At, B0); PG8_MMA(1, 1, At, B1); PG8_BAR; PG8_SCHED;
	s_setprio 1
	v_mfma_f32_16x16x32_bf16 v[126:129], v[138:141], v[218:221], v[126:129]
	v_mfma_f32_16x16x32_bf16 v[122:125], v[176:179], v[218:221], v[122:125]
	v_mfma_f32_16x16x32_bf16 v[110:113], v[138:141], v[226:229], v[110:113]
	v_mfma_f32_16x16x32_bf16 v[106:109], v[176:179], v[226:229], v[106:109]
	v_mfma_f32_16x16x32_bf16 v[94:97], v[138:141], v[234:237], v[94:97]
	v_mfma_f32_16x16x32_bf16 v[90:93], v[176:179], v[234:237], v[90:93]
	v_mfma_f32_16x16x32_bf16 v[78:81], v[138:141], v[242:245], v[78:81]
	v_mfma_f32_16x16x32_bf16 v[74:77], v[176:179], v[242:245], v[74:77]
	v_mfma_f32_16x16x32_bf16 v[126:129], v[142:145], v[222:225], v[126:129]
	v_mfma_f32_16x16x32_bf16 v[122:125], v[198:201], v[222:225], v[122:125]
	v_mfma_f32_16x16x32_bf16 v[110:113], v[142:145], v[230:233], v[110:113]
	v_mfma_f32_16x16x32_bf16 v[106:109], v[198:201], v[230:233], v[106:109]
	v_mfma_f32_16x16x32_bf16 v[94:97], v[142:145], v[238:241], v[94:97]
	v_mfma_f32_16x16x32_bf16 v[90:93], v[198:201], v[238:241], v[90:93]
	v_mfma_f32_16x16x32_bf16 v[78:81], v[142:145], v[246:249], v[78:81]
	v_mfma_f32_16x16x32_bf16 v[74:77], v[198:201], v[246:249], v[74:77]
	v_mfma_f32_16x16x32_bf16 v[118:121], v[202:205], v[218:221], v[118:121]
	v_mfma_f32_16x16x32_bf16 v[114:117], v[210:213], v[218:221], v[114:117]
	v_mfma_f32_16x16x32_bf16 v[102:105], v[202:205], v[226:229], v[102:105]
	v_mfma_f32_16x16x32_bf16 v[98:101], v[210:213], v[226:229], v[98:101]
	v_mfma_f32_16x16x32_bf16 v[86:89], v[202:205], v[234:237], v[86:89]
	v_mfma_f32_16x16x32_bf16 v[82:85], v[210:213], v[234:237], v[82:85]
	v_mfma_f32_16x16x32_bf16 v[70:73], v[202:205], v[242:245], v[70:73]
	v_mfma_f32_16x16x32_bf16 v[66:69], v[210:213], v[242:245], v[66:69]
	v_mfma_f32_16x16x32_bf16 v[118:121], v[206:209], v[222:225], v[118:121]
	v_mfma_f32_16x16x32_bf16 v[114:117], v[214:217], v[222:225], v[114:117]
	v_mfma_f32_16x16x32_bf16 v[102:105], v[206:209], v[230:233], v[102:105]
	v_mfma_f32_16x16x32_bf16 v[98:101], v[214:217], v[230:233], v[98:101]
	v_mfma_f32_16x16x32_bf16 v[86:89], v[206:209], v[238:241], v[86:89]
	v_mfma_f32_16x16x32_bf16 v[82:85], v[214:217], v[238:241], v[82:85]
	v_mfma_f32_16x16x32_bf16 v[70:73], v[206:209], v[246:249], v[70:73]
	v_mfma_f32_16x16x32_bf16 v[66:69], v[214:217], v[246:249], v[66:69]
	s_setprio 0
	s_barrier
	s_add_i32 s70, s94, s78
	v_lshl_add_u64 v[172:173], s[64:65], 0, v[150:151]
	s_mov_b32 m0, s70
	ds_read_b128 v[218:221], v186 offset:16384
	ds_read_b128 v[222:225], v186 offset:17408
	ds_read_b128 v[226:229], v186 offset:18432
	ds_read_b128 v[230:233], v186 offset:19456
	ds_read_b128 v[234:237], v186 offset:20480
	ds_read_b128 v[238:241], v186 offset:21504
	ds_read_b128 v[242:245], v186 offset:22528
	ds_read_b128 v[246:249], v186 offset:23552
	global_load_lds_dwordx4 v[172:173], off
	s_add_i32 m0, s70, 0x2000
	s_add_u32 s70, s64, 0x40000
	v_lshl_add_u64 v[180:181], s[64:65], 0, v[154:155]
	s_addc_u32 s71, s65, 0
	s_add_i32 s72, s95, s78
	global_load_lds_dwordx4 v[180:181], off
	v_lshl_add_u64 v[250:251], s[70:71], 0, v[150:151]
	s_mov_b32 m0, s72
	v_lshl_add_u64 v[252:253], s[66:67], 0, v[152:153]
	global_load_lds_dwordx4 v[250:251], off
	v_lshl_add_u64 v[250:251], s[70:71], 0, v[154:155]
	s_add_i32 m0, s72, 0x2000
	s_nop 0
	global_load_lds_dwordx4 v[250:251], off
	v_lshl_add_u64 v[250:251], s[66:67], 0, v[148:149]
	s_mov_b32 m0, s79
	s_nop 0
	global_load_lds_dwordx4 v[250:251], off
	s_mov_b32 m0, s80
	s_nop 0
	global_load_lds_dwordx4 v[252:253], off
	s_waitcnt vmcnt(8)
	s_waitcnt lgkmcnt(0)
	s_barrier
	s_setprio 1
	v_mfma_f32_16x16x32_bf16 v[62:65], v[138:141], v[218:221], v[62:65]
	v_mfma_f32_16x16x32_bf16 v[58:61], v[176:179], v[218:221], v[58:61]
	v_mfma_f32_16x16x32_bf16 v[46:49], v[138:141], v[226:229], v[46:49]
	v_mfma_f32_16x16x32_bf16 v[42:45], v[176:179], v[226:229], v[42:45]
	v_mfma_f32_16x16x32_bf16 v[30:33], v[138:141], v[234:237], v[30:33]
	v_mfma_f32_16x16x32_bf16 v[26:29], v[176:179], v[234:237], v[26:29]
	v_mfma_f32_16x16x32_bf16 v[14:17], v[138:141], v[242:245], v[14:17]
	v_mfma_f32_16x16x32_bf16 v[10:13], v[176:179], v[242:245], v[10:13]
	v_mfma_f32_16x16x32_bf16 v[62:65], v[142:145], v[222:225], v[62:65]
	v_mfma_f32_16x16x32_bf16 v[58:61], v[198:201], v[222:225], v[58:61]
	v_mfma_f32_16x16x32_bf16 v[46:49], v[142:145], v[230:233], v[46:49]
	v_mfma_f32_16x16x32_bf16 v[42:45], v[198:201], v[230:233], v[42:45]
	v_mfma_f32_16x16x32_bf16 v[30:33], v[142:145], v[238:241], v[30:33]
	v_mfma_f32_16x16x32_bf16 v[26:29], v[198:201], v[238:241], v[26:29]
	v_mfma_f32_16x16x32_bf16 v[14:17], v[142:145], v[246:249], v[14:17]
	v_mfma_f32_16x16x32_bf16 v[10:13], v[198:201], v[246:249], v[10:13]
	v_mfma_f32_16x16x32_bf16 v[54:57], v[202:205], v[218:221], v[54:57]
	v_mfma_f32_16x16x32_bf16 v[50:53], v[210:213], v[218:221], v[50:53]
	v_mfma_f32_16x16x32_bf16 v[38:41], v[202:205], v[226:229], v[38:41]
	v_mfma_f32_16x16x32_bf16 v[34:37], v[210:213], v[226:229], v[34:37]
	v_mfma_f32_16x16x32_bf16 v[22:25], v[202:205], v[234:237], v[22:25]
	v_mfma_f32_16x16x32_bf16 v[18:21], v[210:213], v[234:237], v[18:21]
	v_mfma_f32_16x16x32_bf16 v[6:9], v[202:205], v[242:245], v[6:9]
	v_mfma_f32_16x16x32_bf16 v[2:5], v[210:213], v[242:245], v[2:5]
	v_mfma_f32_16x16x32_bf16 v[54:57], v[206:209], v[222:225], v[54:57]
	v_mfma_f32_16x16x32_bf16 v[50:53], v[214:217], v[222:225], v[50:53]
	v_mfma_f32_16x16x32_bf16 v[38:41], v[206:209], v[230:233], v[38:41]
	v_mfma_f32_16x16x32_bf16 v[34:37], v[214:217], v[230:233], v[34:37]
	v_mfma_f32_16x16x32_bf16 v[22:25], v[206:209], v[238:241], v[22:25]
	v_mfma_f32_16x16x32_bf16 v[18:21], v[214:217], v[238:241], v[18:21]
	v_mfma_f32_16x16x32_bf16 v[6:9], v[206:209], v[246:249], v[6:9]
	v_mfma_f32_16x16x32_bf16 v[2:5], v[214:217], v[246:249], v[2:5]
	s_setprio 0
	s_barrier
; #define PG8_STAGE(bufoff, gbase, voff) do { _Pragma("unroll") for (int _i = 0; _i < 2; ++_i) \
;         __builtin_amdgcn_global_load_lds((const unsigned*)((const char*)(gbase) + (voff)[_i]), (LAS unsigned*)(lds + (bufoff) + ldsw + _i * 8192), 16, 0, 0); } while (0)
; #define PG8_LDA(dst, b, h) do { _Pragma("unroll") for (int m = 0; m < 4; ++m) _Pragma("unroll") for (int k = 0; k < 2; ++k) dst[m][k] = *(const LAS bf16x8*)(lds + PG8_SA(b, h) + aoff + m * 2048 + k * 1024); } while (0)
; #define PG8_LDB(dst, b, h) do { _Pragma("unroll") for (int n = 0; n < 2; ++n) _Pragma("unroll") for (int k = 0; k < 2; ++k) dst[n][k] = *(const LAS bf16x8*)(lds + PG8_SB(b, h) + boff + n * 2048 + k * 1024); } while (0)
; #define PG8_MMA(ai, bj, At, Bt) do { __builtin_amdgcn_s_setprio(1); _Pragma("unroll") for (int m = 0; m < 4; ++m) _Pragma("unroll") for (int n = 0; n < 2; ++n) _Pragma("unroll") for (int k = 0; k < 2; ++k) \
;         acc[ai][bj][m][n] = __builtin_amdgcn_mfma_f32_16x16x32_bf16(Bt[n][k], At[m][k], acc[ai][bj][m][n], 0, 0, 0); __builtin_amdgcn_s_setprio(0); } while (0)
; #define PG8_WAIT_V(n) asm volatile("s_waitcnt vmcnt(" #n ")" ::: "memory")
; #define PG8_WAIT_L(n) asm volatile("s_waitcnt lgkmcnt(" #n ")" ::: "memory")
; #define PG8_BAR __builtin_amdgcn_s_barrier()
; #define PG8_SCHED __builtin_amdgcn_sched_barrier(0)
; template <class Epi, class Sched>
; DI void gemm_phase(LAS unsigned char* lds, const Gemm g, const Sched& S, const Epi& E) {
;     ...
;             PG8_LDB(B0, 1, 0); PG8_LDB(B1, 1, 1); PG8_SCHED; PG8_LDA(At, 1, 0); PG8_STAGE(PG8_SA(0, 1), a2 + hstepA, voffA);
;             PG8_WAIT_V(8); PG8_WAIT_L(0); PG8_BAR; PG8_MMA(0, 0, At, B0); PG8_MMA(0, 1, At, B1); PG8_BAR; PG8_SCHED;
	s_add_i32 s70, 0, 0x18000
	v_add_u32_e32 v156, s70, v159
	s_add_i32 s71, 0, 0x1c000
	ds_read_b128 v[138:141], v156
	ds_read_b128 v[142:145], v156 offset:1024
	ds_read_b128 v[176:179], v156 offset:2048
	ds_read_b128 v[198:201], v156 offset:3072
	v_add_u32_e32 v156, s71, v159
	ds_read_b128 v[202:205], v156
	ds_read_b128 v[206:209], v156 offset:1024
	ds_read_b128 v[210:213], v156 offset:2048
	ds_read_b128 v[214:217], v156 offset:3072
	s_add_u32 s66, s66, 0x40000
	s_addc_u32 s67, s67, 0
	s_mov_b32 m0, s81
	v_lshl_add_u64 v[254:255], s[66:67], 0, v[148:149]
	ds_read_b128 v[218:221], v186 offset:32768
	ds_read_b128 v[222:225], v186 offset:33792
	ds_read_b128 v[226:229], v186 offset:34816
	ds_read_b128 v[230:233], v186 offset:35840
	ds_read_b128 v[234:237], v186 offset:36864
	ds_read_b128 v[238:241], v186 offset:37888
	ds_read_b128 v[242:245], v186 offset:38912
	ds_read_b128 v[246:249], v186 offset:39936
	global_load_lds_dwordx4 v[254:255], off
	v_lshl_add_u64 v[254:255], s[66:67], 0, v[152:153]
	s_mov_b32 m0, s82
	s_nop 0
	global_load_lds_dwordx4 v[254:255], off
	s_waitcnt vmcnt(8)
	s_waitcnt lgkmcnt(0)
	s_barrier
	s_setprio 1
	v_mfma_f32_16x16x32_bf16 v[126:129], v[138:141], v[218:221], v[126:129]
	v_mfma_f32_16x16x32_bf16 v[122:125], v[176:179], v[218:221], v[122:125]
	v_mfma_f32_16x16x32_bf16 v[110:113], v[138:141], v[226:229], v[110:113]
	v_mfma_f32_16x16x32_bf16 v[106:109], v[176:179], v[226:229], v[106:109]
	v_mfma_f32_16x16x32_bf16 v[94:97], v[138:141], v[234:237], v[94:97]
	v_mfma_f32_16x16x32_bf16 v[90:93], v[176:179], v[234:237], v[90:93]
	v_mfma_f32_16x16x32_bf16 v[78:81], v[138:141], v[242:245], v[78:81]
	v_mfma_f32_16x16x32_bf16 v[74:77], v[176:179], v[242:245], v[74:77]
	v_mfma_f32_16x16x32_bf16 v[126:129], v[142:145], v[222:225], v[126:129]
	v_mfma_f32_16x16x32_bf16 v[122:125], v[198:201], v[222:225], v[122:125]
	v_mfma_f32_16x16x32_bf16 v[110:113], v[142:145], v[230:233], v[110:113]
	v_mfma_f32_16x16x32_bf16 v[106:109], v[198:201], v[230:233], v[106:109]
	v_mfma_f32_16x16x32_bf16 v[94:97], v[142:145], v[238:241], v[94:97]
	v_mfma_f32_16x16x32_bf16 v[90:93], v[198:201], v[238:241], v[90:93]
	v_mfma_f32_16x16x32_bf16 v[78:81], v[142:145], v[246:249], v[78:81]
	v_mfma_f32_16x16x32_bf16 v[74:77], v[198:201], v[246:249], v[74:77]
	v_mfma_f32_16x16x32_bf16 v[118:121], v[202:205], v[218:221], v[118:121]
	v_mfma_f32_16x16x32_bf16 v[114:117], v[210:213], v[218:221], v[114:117]
	v_mfma_f32_16x16x32_bf16 v[102:105], v[202:205], v[226:229], v[102:105]
	v_mfma_f32_16x16x32_bf16 v[98:101], v[210:213], v[226:229], v[98:101]
	v_mfma_f32_16x16x32_bf16 v[86:89], v[202:205], v[234:237], v[86:89]
	v_mfma_f32_16x16x32_bf16 v[82:85], v[210:213], v[234:237], v[82:85]
	v_mfma_f32_16x16x32_bf16 v[70:73], v[202:205], v[242:245], v[70:73]
	v_mfma_f32_16x16x32_bf16 v[66:69], v[210:213], v[242:245], v[66:69]
	v_mfma_f32_16x16x32_bf16 v[118:121], v[206:209], v[222:225], v[118:121]
	v_mfma_f32_16x16x32_bf16 v[114:117], v[214:217], v[222:225], v[114:117]
	v_mfma_f32_16x16x32_bf16 v[102:105], v[206:209], v[230:233], v[102:105]
	v_mfma_f32_16x16x32_bf16 v[98:101], v[214:217], v[230:233], v[98:101]
	v_mfma_f32_16x16x32_bf16 v[86:89], v[206:209], v[238:241], v[86:89]
	v_mfma_f32_16x16x32_bf16 v[82:85], v[214:217], v[238:241], v[82:85]
	v_mfma_f32_16x16x32_bf16 v[70:73], v[206:209], v[246:249], v[70:73]
	v_mfma_f32_16x16x32_bf16 v[66:69], v[214:217], v[246:249], v[66:69]
	s_setprio 0
	s_barrier
; #define PG8_STAGE(bufoff, gbase, voff) do { _Pragma("unroll") for (int _i = 0; _i < 2; ++_i) \
;         __builtin_amdgcn_global_load_lds((const unsigned*)((const char*)(gbase) + (voff)[_i]), (LAS unsigned*)(lds + (bufoff) + ldsw + _i * 8192), 16, 0, 0); } while (0)
; #define PG8_LDA(dst, b, h) do { _Pragma("unroll") for (int m = 0; m < 4; ++m) _Pragma("unroll") for (int k = 0; k < 2; ++k) dst[m][k] = *(const LAS bf16x8*)(lds + PG8_SA(b, h) + aoff + m * 2048 + k * 1024); } while (0)
; #define PG8_MMA(ai, bj, At, Bt) do { __builtin_amdgcn_s_setprio(1); _Pragma("unroll") for (int m = 0; m < 4; ++m) _Pragma("unroll") for (int n = 0; n < 2; ++n) _Pragma("unroll") for (int k = 0; k < 2; ++k) \
;         acc[ai][bj][m][n] = __builtin_amdgcn_mfma_f32_16x16x32_bf16(Bt[n][k], At[m][k], acc[ai][bj][m][n], 0, 0, 0); __builtin_amdgcn_s_setprio(0); } while (0)
; #define PG8_WAIT_V(n) asm volatile("s_waitcnt vmcnt(" #n ")" ::: "memory")
; #define PG8_WAIT_L(n) asm volatile("s_waitcnt lgkmcnt(" #n ")" ::: "memory")
; #define PG8_BAR __builtin_amdgcn_s_barrier()
; #define PG8_SCHED __builtin_amdgcn_sched_barrier(0)
;     DI void pre(Pre& pr, const pg8::Unit& u, int wr, int fr) const { load_rows(pr, ssq, u, wr, fr); }
;     DI void pre(Pre& pr, const pg8::Unit& u, int wr, int fr) const { load_rows(pr, ssq, u, wr, fr); }
; template <class Epi, class Sched>
; DI void gemm_phase(LAS unsigned char* lds, const Gemm g, const Sched& S, const Epi& E) {
;     ...
;             PG8_LDA(At, 1, 1); PG8_STAGE(PG8_SB(1, 0), b3, voffB); PG8_STAGE(PG8_SB(1, 1), b3 + hstepB, voffB); PG8_STAGE(PG8_SA(1, 0), a3, voffA);
;             PG8_WAIT_V(8); PG8_WAIT_L(0); PG8_BAR; PG8_MMA(1, 0, At, B0); PG8_MMA(1, 1, At, B1); PG8_BAR; PG8_SCHED;
;         }
;         if (wr == 0) PG8_BAR;
;         E(acc, cur, wr, wc, fr, fq, pre);
;         if (!has_next) break;
;         if (!(Epi::CHAIN && cur.src == 0)) {
	s_add_i32 s66, s70, s78
	v_lshl_add_u64 v[172:173], v[172:173], 0, s[50:51]
	s_mov_b32 m0, s66
	ds_read_b128 v[218:221], v186 offset:49152
	ds_read_b128 v[222:225], v186 offset:50176
	ds_read_b128 v[226:229], v186 offset:51200
	ds_read_b128 v[230:233], v186 offset:52224
	ds_read_b128 v[234:237], v186 offset:53248
	ds_read_b128 v[238:241], v186 offset:54272
	ds_read_b128 v[242:245], v186 offset:55296
	ds_read_b128 v[246:249], v186 offset:56320
	global_load_lds_dwordx4 v[172:173], off
	s_add_i32 m0, s66, 0x2000
	s_add_u32 s64, s64, 0x40080
	v_lshl_add_u64 v[172:173], v[180:181], 0, s[50:51]
	s_addc_u32 s65, s65, 0
	s_add_i32 s66, s71, s78
	global_load_lds_dwordx4 v[172:173], off
	v_lshl_add_u64 v[172:173], s[64:65], 0, v[150:151]
	s_mov_b32 m0, s66
	s_nop 0
	global_load_lds_dwordx4 v[172:173], off
	v_lshl_add_u64 v[172:173], s[64:65], 0, v[154:155]
	s_add_i32 m0, s66, 0x2000
	s_nop 0
	global_load_lds_dwordx4 v[172:173], off
	v_lshl_add_u64 v[172:173], v[250:251], 0, s[50:51]
	s_mov_b32 m0, s86
	s_nop 0
	global_load_lds_dwordx4 v[172:173], off
	v_lshl_add_u64 v[172:173], v[252:253], 0, s[50:51]
	s_mov_b32 m0, s87
	s_nop 0
	global_load_lds_dwordx4 v[172:173], off
	s_waitcnt vmcnt(8)
	s_waitcnt lgkmcnt(0)
	s_nop 0
	s_barrier
	s_setprio 1
	v_mfma_f32_16x16x32_bf16 v[62:65], v[138:141], v[218:221], v[62:65]
	v_mfma_f32_16x16x32_bf16 v[58:61], v[176:179], v[218:221], v[58:61]
	v_mfma_f32_16x16x32_bf16 v[46:49], v[138:141], v[226:229], v[46:49]
	v_mfma_f32_16x16x32_bf16 v[42:45], v[176:179], v[226:229], v[42:45]
	v_mfma_f32_16x16x32_bf16 v[30:33], v[138:141], v[234:237], v[30:33]
	v_mfma_f32_16x16x32_bf16 v[26:29], v[176:179], v[234:237], v[26:29]
	v_mfma_f32_16x16x32_bf16 v[14:17], v[138:141], v[242:245], v[14:17]
	v_mfma_f32_16x16x32_bf16 v[10:13], v[176:179], v[242:245], v[10:13]
	v_mfma_f32_16x16x32_bf16 v[62:65], v[142:145], v[222:225], v[62:65]
	v_mfma_f32_16x16x32_bf16 v[58:61], v[198:201], v[222:225], v[58:61]
	v_mfma_f32_16x16x32_bf16 v[46:49], v[142:145], v[230:233], v[46:49]
	v_mfma_f32_16x16x32_bf16 v[42:45], v[198:201], v[230:233], v[42:45]
	v_mfma_f32_16x16x32_bf16 v[30:33], v[142:145], v[238:241], v[30:33]
	v_mfma_f32_16x16x32_bf16 v[26:29], v[198:201], v[238:241], v[26:29]
	v_mfma_f32_16x16x32_bf16 v[14:17], v[142:145], v[246:249], v[14:17]
	v_mfma_f32_16x16x32_bf16 v[10:13], v[198:201], v[246:249], v[10:13]
	v_mfma_f32_16x16x32_bf16 v[54:57], v[202:205], v[218:221], v[54:57]
	v_mfma_f32_16x16x32_bf16 v[50:53], v[210:213], v[218:221], v[50:53]
	v_mfma_f32_16x16x32_bf16 v[38:41], v[202:205], v[226:229], v[38:41]
	v_mfma_f32_16x16x32_bf16 v[34:37], v[210:213], v[226:229], v[34:37]
	v_mfma_f32_16x16x32_bf16 v[22:25], v[202:205], v[234:237], v[22:25]
	v_mfma_f32_16x16x32_bf16 v[18:21], v[210:213], v[234:237], v[18:21]
	v_mfma_f32_16x16x32_bf16 v[6:9], v[202:205], v[242:245], v[6:9]
	v_mfma_f32_16x16x32_bf16 v[2:5], v[210:213], v[242:245], v[2:5]
	v_mfma_f32_16x16x32_bf16 v[54:57], v[206:209], v[222:225], v[54:57]
	v_mfma_f32_16x16x32_bf16 v[50:53], v[214:217], v[222:225], v[50:53]
	v_mfma_f32_16x16x32_bf16 v[38:41], v[206:209], v[230:233], v[38:41]
	v_mfma_f32_16x16x32_bf16 v[34:37], v[214:217], v[230:233], v[34:37]
	v_mfma_f32_16x16x32_bf16 v[22:25], v[206:209], v[238:241], v[22:25]
	v_mfma_f32_16x16x32_bf16 v[18:21], v[214:217], v[238:241], v[18:21]
	v_mfma_f32_16x16x32_bf16 v[6:9], v[206:209], v[246:249], v[6:9]
	v_mfma_f32_16x16x32_bf16 v[2:5], v[214:217], v[246:249], v[2:5]
	s_setprio 0
	s_barrier
	s_add_i32 s69, s69, 2
	s_add_u32 s10, s10, 0x100
	s_addc_u32 s11, s11, 0
	s_add_u32 s59, s59, 0x100
	s_addc_u32 s68, s68, 0
	s_cmp_gt_u32 s69, 13
	s_cbranch_scc0 .LBB0_381
	s_waitcnt vmcnt(0)
	s_mov_b32 s99, 1
	s_and_b64 vcc, exec, s[52:53]
	s_cbranch_vccnz .LBB0_386
	s_cmp_gt_i32 s12, 4
	s_mov_b64 s[10:11], -1
	s_cbranch_scc1 .LBB0_387

; #define PG8_STAGE(bufoff, gbase, voff) do { _Pragma("unroll") for (int _i = 0; _i < 2; ++_i) \
;         __builtin_amdgcn_global_load_lds((const unsigned*)((const char*)(gbase) + (voff)[_i]), (LAS unsigned*)(lds + (bufoff) + ldsw + _i * 8192), 16, 0, 0); } while (0)
; #define PG8_LDA(dst, b, h) do { _Pragma("unroll") for (int m = 0; m < 4; ++m) _Pragma("unroll") for (int k = 0; k < 2; ++k) dst[m][k] = *(const LAS bf16x8*)(lds + PG8_SA(b, h) + aoff + m * 2048 + k * 1024); } while (0)
; #define PG8_LDB(dst, b, h) do { _Pragma("unroll") for (int n = 0; n < 2; ++n) _Pragma("unroll") for (int k = 0; k < 2; ++k) dst[n][k] = *(const LAS bf16x8*)(lds + PG8_SB(b, h) + boff + n * 2048 + k * 1024); } while (0)
; #define PG8_MMA(ai, bj, At, Bt) do { __builtin_amdgcn_s_setprio(1); _Pragma("unroll") for (int m = 0; m < 4; ++m) _Pragma("unroll") for (int n = 0; n < 2; ++n) _Pragma("unroll") for (int k = 0; k < 2; ++k) \
;         acc[ai][bj][m][n] = __builtin_amdgcn_mfma_f32_16x16x32_bf16(Bt[n][k], At[m][k], acc[ai][bj][m][n], 0, 0, 0); __builtin_amdgcn_s_setprio(0); } while (0)
; #define PG8_WAIT_V(n) asm volatile("s_waitcnt vmcnt(" #n ")" ::: "memory")
; #define PG8_WAIT_L(n) asm volatile("s_waitcnt lgkmcnt(" #n ")" ::: "memory")
; #define PG8_BAR __builtin_amdgcn_s_barrier()
; #define PG8_SCHED __builtin_amdgcn_sched_barrier(0)
; template <class Epi, class Sched>
; DI void gemm_phase(LAS unsigned char* lds, const Gemm g, const Sched& S, const Epi& E) {
;     ...
;             PG8_LDB(B0, 0, 0); PG8_LDB(B1, 0, 1); PG8_SCHED; PG8_LDA(At, 0, 0); PG8_STAGE(PG8_SA(1, 1), a1 + hstepA, voffA);
;             PG8_WAIT_V(8); PG8_WAIT_L(0); PG8_BAR; PG8_MMA(0, 0, At, B0); PG8_MMA(0, 1, At, B1); PG8_BAR; PG8_SCHED;
;             PG8_LDA(At, 0, 1); PG8_STAGE(PG8_SB(0, 0), b2, voffB); PG8_STAGE(PG8_SB(0, 1), b2 + hstepB, voffB); PG8_STAGE(PG8_SA(0, 0), a2, voffA);
;             PG8_WAIT_V(8); PG8_WAIT_L(0); PG8_BAR; PG8_MMA(1, 0, At, B0); PG8_MMA(1, 1, At, B1); PG8_BAR; PG8_SCHED;
.LBB0_579:
	ds_read_b128 v[150:153], v142
	ds_read_b128 v[154:157], v142 offset:1024
	ds_read_b128 v[158:161], v142 offset:2048
	ds_read_b128 v[162:165], v142 offset:3072
	ds_read_b128 v[166:169], v143
	ds_read_b128 v[170:173], v143 offset:1024
	ds_read_b128 v[174:177], v143 offset:2048
	ds_read_b128 v[178:181], v143 offset:3072
	s_add_u32 s16, s8, s12
	s_addc_u32 s17, s9, s13
	s_add_u32 s16, s16, 0x100
	s_addc_u32 s17, s17, 0
	s_add_u32 s52, s39, s12
	s_addc_u32 s53, s40, s13
	s_cmpk_eq_i32 s12, 0xf00
	s_cselect_b32 s19, s9, s17
	s_cselect_b32 s18, s8, s16
	s_cselect_b32 s17, s7, s53
	s_cselect_b32 s16, s6, s52
	s_mov_b32 m0, s42
	v_lshl_add_u64 v[182:183], v[138:139], 0, s[12:13]
	ds_read_b128 v[186:189], v145
	ds_read_b128 v[190:193], v145 offset:1024
	ds_read_b128 v[194:197], v145 offset:2048
	ds_read_b128 v[198:201], v145 offset:3072
	ds_read_b128 v[202:205], v145 offset:4096
	ds_read_b128 v[206:209], v145 offset:5120
	ds_read_b128 v[210:213], v145 offset:6144
	ds_read_b128 v[214:217], v145 offset:7168
	global_load_lds_dwordx4 v[182:183], off
	v_lshl_add_u64 v[182:183], v[140:141], 0, s[12:13]
	s_mov_b32 m0, s43
	s_nop 0
	global_load_lds_dwordx4 v[182:183], off
	s_waitcnt vmcnt(8)
	s_waitcnt lgkmcnt(0)
	s_barrier
	s_setprio 1
	v_mfma_f32_16x16x32_bf16 v[126:129], v[150:153], v[186:189], v[126:129]
	v_mfma_f32_16x16x32_bf16 v[122:125], v[158:161], v[186:189], v[122:125]
	v_mfma_f32_16x16x32_bf16 v[118:121], v[150:153], v[194:197], v[118:121]
	v_mfma_f32_16x16x32_bf16 v[114:117], v[158:161], v[194:197], v[114:117]
	v_mfma_f32_16x16x32_bf16 v[110:113], v[150:153], v[202:205], v[110:113]
	v_mfma_f32_16x16x32_bf16 v[106:109], v[158:161], v[202:205], v[106:109]
	v_mfma_f32_16x16x32_bf16 v[102:105], v[150:153], v[210:213], v[102:105]
	v_mfma_f32_16x16x32_bf16 v[98:101], v[158:161], v[210:213], v[98:101]
	v_mfma_f32_16x16x32_bf16 v[126:129], v[154:157], v[190:193], v[126:129]
	v_mfma_f32_16x16x32_bf16 v[122:125], v[162:165], v[190:193], v[122:125]
	v_mfma_f32_16x16x32_bf16 v[118:121], v[154:157], v[198:201], v[118:121]
	v_mfma_f32_16x16x32_bf16 v[114:117], v[162:165], v[198:201], v[114:117]
	v_mfma_f32_16x16x32_bf16 v[110:113], v[154:157], v[206:209], v[110:113]
	v_mfma_f32_16x16x32_bf16 v[106:109], v[162:165], v[206:209], v[106:109]
	v_mfma_f32_16x16x32_bf16 v[102:105], v[154:157], v[214:217], v[102:105]
	v_mfma_f32_16x16x32_bf16 v[98:101], v[162:165], v[214:217], v[98:101]
	v_mfma_f32_16x16x32_bf16 v[62:65], v[166:169], v[186:189], v[62:65]
	v_mfma_f32_16x16x32_bf16 v[58:61], v[174:177], v[186:189], v[58:61]
	v_mfma_f32_16x16x32_bf16 v[54:57], v[166:169], v[194:197], v[54:57]
	v_mfma_f32_16x16x32_bf16 v[50:53], v[174:177], v[194:197], v[50:53]
	v_mfma_f32_16x16x32_bf16 v[46:49], v[166:169], v[202:205], v[46:49]
	v_mfma_f32_16x16x32_bf16 v[42:45], v[174:177], v[202:205], v[42:45]
	v_mfma_f32_16x16x32_bf16 v[38:41], v[166:169], v[210:213], v[38:41]
	v_mfma_f32_16x16x32_bf16 v[34:37], v[174:177], v[210:213], v[34:37]
	v_mfma_f32_16x16x32_bf16 v[62:65], v[170:173], v[190:193], v[62:65]
	v_mfma_f32_16x16x32_bf16 v[58:61], v[178:181], v[190:193], v[58:61]
	v_mfma_f32_16x16x32_bf16 v[54:57], v[170:173], v[198:201], v[54:57]
	v_mfma_f32_16x16x32_bf16 v[50:53], v[178:181], v[198:201], v[50:53]
	v_mfma_f32_16x16x32_bf16 v[46:49], v[170:173], v[206:209], v[46:49]
	v_mfma_f32_16x16x32_bf16 v[42:45], v[178:181], v[206:209], v[42:45]
	v_mfma_f32_16x16x32_bf16 v[38:41], v[170:173], v[214:217], v[38:41]
	v_mfma_f32_16x16x32_bf16 v[34:37], v[178:181], v[214:217], v[34:37]
	s_setprio 0
	s_barrier
	s_mov_b32 m0, s44
	v_lshl_add_u64 v[182:183], s[16:17], 0, v[134:135]
	s_add_u32 s52, s16, 0x80000
	ds_read_b128 v[186:189], v145 offset:16384
	ds_read_b128 v[190:193], v145 offset:17408
	ds_read_b128 v[194:197], v145 offset:18432
	ds_read_b128 v[198:201], v145 offset:19456
	ds_read_b128 v[202:205], v145 offset:20480
	ds_read_b128 v[206:209], v145 offset:21504
	ds_read_b128 v[210:213], v145 offset:22528
	ds_read_b128 v[214:217], v145 offset:23552
	global_load_lds_dwordx4 v[182:183], off
	v_lshl_add_u64 v[218:219], s[16:17], 0, v[130:131]
	s_mov_b32 m0, s45
	s_addc_u32 s53, s17, 0
	global_load_lds_dwordx4 v[218:219], off
	v_lshl_add_u64 v[220:221], s[52:53], 0, v[134:135]
	s_mov_b32 m0, s46
	v_lshl_add_u64 v[222:223], s[18:19], 0, v[132:133]
	global_load_lds_dwordx4 v[220:221], off
	v_lshl_add_u64 v[220:221], s[52:53], 0, v[130:131]
	s_mov_b32 m0, s47
	s_nop 0
	global_load_lds_dwordx4 v[220:221], off
	v_lshl_add_u64 v[220:221], s[18:19], 0, v[136:137]
	s_mov_b32 m0, s28
	s_nop 0
	global_load_lds_dwordx4 v[220:221], off
	s_mov_b32 m0, s29
	s_nop 0
	global_load_lds_dwordx4 v[222:223], off
	s_waitcnt vmcnt(8)
	s_waitcnt lgkmcnt(0)
	s_barrier
; #define PG8_STAGE(bufoff, gbase, voff) do { _Pragma("unroll") for (int _i = 0; _i < 2; ++_i) \
;         __builtin_amdgcn_global_load_lds((const unsigned*)((const char*)(gbase) + (voff)[_i]), (LAS unsigned*)(lds + (bufoff) + ldsw + _i * 8192), 16, 0, 0); } while (0)
; #define PG8_LDA(dst, b, h) do { _Pragma("unroll") for (int m = 0; m < 4; ++m) _Pragma("unroll") for (int k = 0; k < 2; ++k) dst[m][k] = *(const LAS bf16x8*)(lds + PG8_SA(b, h) + aoff + m * 2048 + k * 1024); } while (0)
; #define PG8_LDB(dst, b, h) do { _Pragma("unroll") for (int n = 0; n < 2; ++n) _Pragma("unroll") for (int k = 0; k < 2; ++k) dst[n][k] = *(const LAS bf16x8*)(lds + PG8_SB(b, h) + boff + n * 2048 + k * 1024); } while (0)
; #define PG8_MMA(ai, bj, At, Bt) do { __builtin_amdgcn_s_setprio(1); _Pragma("unroll") for (int m = 0; m < 4; ++m) _Pragma("unroll") for (int n = 0; n < 2; ++n) _Pragma("unroll") for (int k = 0; k < 2; ++k) \
;         acc[ai][bj][m][n] = __builtin_amdgcn_mfma_f32_16x16x32_bf16(Bt[n][k], At[m][k], acc[ai][bj][m][n], 0, 0, 0); __builtin_amdgcn_s_setprio(0); } while (0)
; #define PG8_WAIT_V(n) asm volatile("s_waitcnt vmcnt(" #n ")" ::: "memory")
; #define PG8_WAIT_L(n) asm volatile("s_waitcnt lgkmcnt(" #n ")" ::: "memory")
; #define PG8_BAR __builtin_amdgcn_s_barrier()
; #define PG8_SCHED __builtin_amdgcn_sched_barrier(0)
; template <class Epi, class Sched>
; DI void gemm_phase(LAS unsigned char* lds, const Gemm g, const Sched& S, const Epi& E) {
;     ...
;             PG8_WAIT_V(8); PG8_WAIT_L(0); PG8_BAR; PG8_MMA(1, 0, At, B0); PG8_MMA(1, 1, At, B1); PG8_BAR; PG8_SCHED;
;             PG8_LDB(B0, 1, 0); PG8_LDB(B1, 1, 1); PG8_SCHED; PG8_LDA(At, 1, 0); PG8_STAGE(PG8_SA(0, 1), a2 + hstepA, voffA);
;             PG8_WAIT_V(8); PG8_WAIT_L(0); PG8_BAR; PG8_MMA(0, 0, At, B0); PG8_MMA(0, 1, At, B1); PG8_BAR; PG8_SCHED;
	s_setprio 1
	v_mfma_f32_16x16x32_bf16 v[94:97], v[150:153], v[186:189], v[94:97]
	v_mfma_f32_16x16x32_bf16 v[90:93], v[158:161], v[186:189], v[90:93]
	v_mfma_f32_16x16x32_bf16 v[86:89], v[150:153], v[194:197], v[86:89]
	v_mfma_f32_16x16x32_bf16 v[82:85], v[158:161], v[194:197], v[82:85]
	v_mfma_f32_16x16x32_bf16 v[78:81], v[150:153], v[202:205], v[78:81]
	v_mfma_f32_16x16x32_bf16 v[74:77], v[158:161], v[202:205], v[74:77]
	v_mfma_f32_16x16x32_bf16 v[70:73], v[150:153], v[210:213], v[70:73]
	v_mfma_f32_16x16x32_bf16 v[66:69], v[158:161], v[210:213], v[66:69]
	v_mfma_f32_16x16x32_bf16 v[94:97], v[154:157], v[190:193], v[94:97]
	v_mfma_f32_16x16x32_bf16 v[90:93], v[162:165], v[190:193], v[90:93]
	v_mfma_f32_16x16x32_bf16 v[86:89], v[154:157], v[198:201], v[86:89]
	v_mfma_f32_16x16x32_bf16 v[82:85], v[162:165], v[198:201], v[82:85]
	v_mfma_f32_16x16x32_bf16 v[78:81], v[154:157], v[206:209], v[78:81]
	v_mfma_f32_16x16x32_bf16 v[74:77], v[162:165], v[206:209], v[74:77]
	v_mfma_f32_16x16x32_bf16 v[70:73], v[154:157], v[214:217], v[70:73]
	v_mfma_f32_16x16x32_bf16 v[66:69], v[162:165], v[214:217], v[66:69]
	v_mfma_f32_16x16x32_bf16 v[30:33], v[166:169], v[186:189], v[30:33]
	v_mfma_f32_16x16x32_bf16 v[26:29], v[174:177], v[186:189], v[26:29]
	v_mfma_f32_16x16x32_bf16 v[22:25], v[166:169], v[194:197], v[22:25]
	v_mfma_f32_16x16x32_bf16 v[18:21], v[174:177], v[194:197], v[18:21]
	v_mfma_f32_16x16x32_bf16 v[14:17], v[166:169], v[202:205], v[14:17]
	v_mfma_f32_16x16x32_bf16 v[10:13], v[174:177], v[202:205], v[10:13]
	v_mfma_f32_16x16x32_bf16 v[6:9], v[166:169], v[210:213], v[6:9]
	v_mfma_f32_16x16x32_bf16 v[2:5], v[174:177], v[210:213], v[2:5]
	v_mfma_f32_16x16x32_bf16 v[30:33], v[170:173], v[190:193], v[30:33]
	v_mfma_f32_16x16x32_bf16 v[26:29], v[178:181], v[190:193], v[26:29]
	v_mfma_f32_16x16x32_bf16 v[22:25], v[170:173], v[198:201], v[22:25]
	v_mfma_f32_16x16x32_bf16 v[18:21], v[178:181], v[198:201], v[18:21]
	v_mfma_f32_16x16x32_bf16 v[14:17], v[170:173], v[206:209], v[14:17]
	v_mfma_f32_16x16x32_bf16 v[10:13], v[178:181], v[206:209], v[10:13]
	v_mfma_f32_16x16x32_bf16 v[6:9], v[170:173], v[214:217], v[6:9]
	v_mfma_f32_16x16x32_bf16 v[2:5], v[178:181], v[214:217], v[2:5]
	s_setprio 0
	s_barrier
	ds_read_b128 v[150:153], v147
	ds_read_b128 v[154:157], v147 offset:1024
	ds_read_b128 v[158:161], v147 offset:2048
	ds_read_b128 v[162:165], v147 offset:3072
	ds_read_b128 v[166:169], v148
	ds_read_b128 v[170:173], v148 offset:1024
	ds_read_b128 v[174:177], v148 offset:2048
	ds_read_b128 v[178:181], v148 offset:3072
	s_add_u32 s18, s18, 0x40000
	s_addc_u32 s19, s19, 0
	s_mov_b32 m0, s34
	v_lshl_add_u64 v[224:225], s[18:19], 0, v[136:137]
	ds_read_b128 v[186:189], v145 offset:32768
	ds_read_b128 v[190:193], v145 offset:33792
	ds_read_b128 v[194:197], v145 offset:34816
	ds_read_b128 v[198:201], v145 offset:35840
	ds_read_b128 v[202:205], v145 offset:36864
	ds_read_b128 v[206:209], v145 offset:37888
	ds_read_b128 v[210:213], v145 offset:38912
	ds_read_b128 v[214:217], v145 offset:39936
	global_load_lds_dwordx4 v[224:225], off
	v_lshl_add_u64 v[224:225], s[18:19], 0, v[132:133]
	s_mov_b32 m0, s35
	s_nop 0
	global_load_lds_dwordx4 v[224:225], off
	s_waitcnt vmcnt(8)
	s_waitcnt lgkmcnt(0)
	s_barrier
	s_setprio 1
	v_mfma_f32_16x16x32_bf16 v[126:129], v[150:153], v[186:189], v[126:129]
	v_mfma_f32_16x16x32_bf16 v[122:125], v[158:161], v[186:189], v[122:125]
	v_mfma_f32_16x16x32_bf16 v[118:121], v[150:153], v[194:197], v[118:121]
	v_mfma_f32_16x16x32_bf16 v[114:117], v[158:161], v[194:197], v[114:117]
	v_mfma_f32_16x16x32_bf16 v[110:113], v[150:153], v[202:205], v[110:113]
	v_mfma_f32_16x16x32_bf16 v[106:109], v[158:161], v[202:205], v[106:109]
	v_mfma_f32_16x16x32_bf16 v[102:105], v[150:153], v[210:213], v[102:105]
	v_mfma_f32_16x16x32_bf16 v[98:101], v[158:161], v[210:213], v[98:101]
	v_mfma_f32_16x16x32_bf16 v[126:129], v[154:157], v[190:193], v[126:129]
	v_mfma_f32_16x16x32_bf16 v[122:125], v[162:165], v[190:193], v[122:125]
	v_mfma_f32_16x16x32_bf16 v[118:121], v[154:157], v[198:201], v[118:121]
	v_mfma_f32_16x16x32_bf16 v[114:117], v[162:165], v[198:201], v[114:117]
	v_mfma_f32_16x16x32_bf16 v[110:113], v[154:157], v[206:209], v[110:113]
	v_mfma_f32_16x16x32_bf16 v[106:109], v[162:165], v[206:209], v[106:109]
	v_mfma_f32_16x16x32_bf16 v[102:105], v[154:157], v[214:217], v[102:105]
	v_mfma_f32_16x16x32_bf16 v[98:101], v[162:165], v[214:217], v[98:101]
	v_mfma_f32_16x16x32_bf16 v[62:65], v[166:169], v[186:189], v[62:65]
	v_mfma_f32_16x16x32_bf16 v[58:61], v[174:177], v[186:189], v[58:61]
	v_mfma_f32_16x16x32_bf16 v[54:57], v[166:169], v[194:197], v[54:57]
	v_mfma_f32_16x16x32_bf16 v[50:53], v[174:177], v[194:197], v[50:53]
	v_mfma_f32_16x16x32_bf16 v[46:49], v[166:169], v[202:205], v[46:49]
	v_mfma_f32_16x16x32_bf16 v[42:45], v[174:177], v[202:205], v[42:45]
	v_mfma_f32_16x16x32_bf16 v[38:41], v[166:169], v[210:213], v[38:41]
	v_mfma_f32_16x16x32_bf16 v[34:37], v[174:177], v[210:213], v[34:37]
	v_mfma_f32_16x16x32_bf16 v[62:65], v[170:173], v[190:193], v[62:65]
	v_mfma_f32_16x16x32_bf16 v[58:61], v[178:181], v[190:193], v[58:61]
	v_mfma_f32_16x16x32_bf16 v[54:57], v[170:173], v[198:201], v[54:57]
	v_mfma_f32_16x16x32_bf16 v[50:53], v[178:181], v[198:201], v[50:53]
	v_mfma_f32_16x16x32_bf16 v[46:49], v[170:173], v[206:209], v[46:49]
	v_mfma_f32_16x16x32_bf16 v[42:45], v[178:181], v[206:209], v[42:45]
	v_mfma_f32_16x16x32_bf16 v[38:41], v[170:173], v[214:217], v[38:41]
	v_mfma_f32_16x16x32_bf16 v[34:37], v[178:181], v[214:217], v[34:37]
	s_setprio 0
	s_barrier
; #define PG8_STAGE(bufoff, gbase, voff) do { _Pragma("unroll") for (int _i = 0; _i < 2; ++_i) \
;         __builtin_amdgcn_global_load_lds((const unsigned*)((const char*)(gbase) + (voff)[_i]), (LAS unsigned*)(lds + (bufoff) + ldsw + _i * 8192), 16, 0, 0); } while (0)
; #define PG8_LDA(dst, b, h) do { _Pragma("unroll") for (int m = 0; m < 4; ++m) _Pragma("unroll") for (int k = 0; k < 2; ++k) dst[m][k] = *(const LAS bf16x8*)(lds + PG8_SA(b, h) + aoff + m * 2048 + k * 1024); } while (0)
; #define PG8_MMA(ai, bj, At, Bt) do { __builtin_amdgcn_s_setprio(1); _Pragma("unroll") for (int m = 0; m < 4; ++m) _Pragma("unroll") for (int n = 0; n < 2; ++n) _Pragma("unroll") for (int k = 0; k < 2; ++k) \
;         acc[ai][bj][m][n] = __builtin_amdgcn_mfma_f32_16x16x32_bf16(Bt[n][k], At[m][k], acc[ai][bj][m][n], 0, 0, 0); __builtin_amdgcn_s_setprio(0); } while (0)
; #define PG8_WAIT_V(n) asm volatile("s_waitcnt vmcnt(" #n ")" ::: "memory")
; #define PG8_WAIT_L(n) asm volatile("s_waitcnt lgkmcnt(" #n ")" ::: "memory")
; #define PG8_BAR __builtin_amdgcn_s_barrier()
; #define PG8_SCHED __builtin_amdgcn_sched_barrier(0)
; template <class Epi, class Sched>
; DI void gemm_phase(LAS unsigned char* lds, const Gemm g, const Sched& S, const Epi& E) {
;     ...
;             PG8_LDA(At, 1, 1); PG8_STAGE(PG8_SB(1, 0), b3, voffB); PG8_STAGE(PG8_SB(1, 1), b3 + hstepB, voffB); PG8_STAGE(PG8_SA(1, 0), a3, voffA);
;             PG8_WAIT_V(8); PG8_WAIT_L(0); PG8_BAR; PG8_MMA(1, 0, At, B0); PG8_MMA(1, 1, At, B1); PG8_BAR; PG8_SCHED;
;         }
;         if (wr == 0) PG8_BAR;
	s_mov_b32 m0, s48
	v_lshl_add_u64 v[182:183], v[182:183], 0, s[10:11]
	s_add_u32 s16, s16, 0x80080
	ds_read_b128 v[186:189], v145 offset:49152
	ds_read_b128 v[190:193], v145 offset:50176
	ds_read_b128 v[194:197], v145 offset:51200
	ds_read_b128 v[198:201], v145 offset:52224
	ds_read_b128 v[202:205], v145 offset:53248
	ds_read_b128 v[206:209], v145 offset:54272
	ds_read_b128 v[210:213], v145 offset:55296
	ds_read_b128 v[214:217], v145 offset:56320
	global_load_lds_dwordx4 v[182:183], off
	v_lshl_add_u64 v[182:183], v[218:219], 0, s[10:11]
	s_mov_b32 m0, s49
	s_addc_u32 s17, s17, 0
	global_load_lds_dwordx4 v[182:183], off
	v_lshl_add_u64 v[182:183], s[16:17], 0, v[134:135]
	s_mov_b32 m0, s50
	s_nop 0
	global_load_lds_dwordx4 v[182:183], off
	v_lshl_add_u64 v[182:183], s[16:17], 0, v[130:131]
	s_mov_b32 m0, s51
	s_nop 0
	global_load_lds_dwordx4 v[182:183], off
	v_lshl_add_u64 v[182:183], v[220:221], 0, s[10:11]
	s_mov_b32 m0, s37
	s_nop 0
	global_load_lds_dwordx4 v[182:183], off
	v_lshl_add_u64 v[182:183], v[222:223], 0, s[10:11]
	s_mov_b32 m0, s38
	s_nop 0
	global_load_lds_dwordx4 v[182:183], off
	s_waitcnt vmcnt(8)
	s_waitcnt lgkmcnt(0)
	s_nop 0
	s_barrier
	s_setprio 1
	v_mfma_f32_16x16x32_bf16 v[94:97], v[150:153], v[186:189], v[94:97]
	v_mfma_f32_16x16x32_bf16 v[90:93], v[158:161], v[186:189], v[90:93]
	v_mfma_f32_16x16x32_bf16 v[86:89], v[150:153], v[194:197], v[86:89]
	v_mfma_f32_16x16x32_bf16 v[82:85], v[158:161], v[194:197], v[82:85]
	v_mfma_f32_16x16x32_bf16 v[78:81], v[150:153], v[202:205], v[78:81]
	v_mfma_f32_16x16x32_bf16 v[74:77], v[158:161], v[202:205], v[74:77]
	v_mfma_f32_16x16x32_bf16 v[70:73], v[150:153], v[210:213], v[70:73]
	v_mfma_f32_16x16x32_bf16 v[66:69], v[158:161], v[210:213], v[66:69]
	v_mfma_f32_16x16x32_bf16 v[94:97], v[154:157], v[190:193], v[94:97]
	v_mfma_f32_16x16x32_bf16 v[90:93], v[162:165], v[190:193], v[90:93]
	v_mfma_f32_16x16x32_bf16 v[86:89], v[154:157], v[198:201], v[86:89]
	v_mfma_f32_16x16x32_bf16 v[82:85], v[162:165], v[198:201], v[82:85]
	v_mfma_f32_16x16x32_bf16 v[78:81], v[154:157], v[206:209], v[78:81]
	v_mfma_f32_16x16x32_bf16 v[74:77], v[162:165], v[206:209], v[74:77]
	v_mfma_f32_16x16x32_bf16 v[70:73], v[154:157], v[214:217], v[70:73]
	v_mfma_f32_16x16x32_bf16 v[66:69], v[162:165], v[214:217], v[66:69]
	v_mfma_f32_16x16x32_bf16 v[30:33], v[166:169], v[186:189], v[30:33]
	v_mfma_f32_16x16x32_bf16 v[26:29], v[174:177], v[186:189], v[26:29]
	v_mfma_f32_16x16x32_bf16 v[22:25], v[166:169], v[194:197], v[22:25]
	v_mfma_f32_16x16x32_bf16 v[18:21], v[174:177], v[194:197], v[18:21]
	v_mfma_f32_16x16x32_bf16 v[14:17], v[166:169], v[202:205], v[14:17]
	v_mfma_f32_16x16x32_bf16 v[10:13], v[174:177], v[202:205], v[10:13]
	v_mfma_f32_16x16x32_bf16 v[6:9], v[166:169], v[210:213], v[6:9]
	v_mfma_f32_16x16x32_bf16 v[2:5], v[174:177], v[210:213], v[2:5]
	v_mfma_f32_16x16x32_bf16 v[30:33], v[170:173], v[190:193], v[30:33]
	v_mfma_f32_16x16x32_bf16 v[26:29], v[178:181], v[190:193], v[26:29]
	v_mfma_f32_16x16x32_bf16 v[22:25], v[170:173], v[198:201], v[22:25]
	v_mfma_f32_16x16x32_bf16 v[18:21], v[178:181], v[198:201], v[18:21]
	v_mfma_f32_16x16x32_bf16 v[14:17], v[170:173], v[206:209], v[14:17]
	v_mfma_f32_16x16x32_bf16 v[10:13], v[178:181], v[206:209], v[10:13]
	v_mfma_f32_16x16x32_bf16 v[6:9], v[170:173], v[214:217], v[6:9]
	v_mfma_f32_16x16x32_bf16 v[2:5], v[178:181], v[214:217], v[2:5]
	s_setprio 0
	s_barrier
	s_add_i32 s41, s41, 2
	s_add_u32 s12, s12, 0x100
	s_addc_u32 s13, s13, 0
	s_cmp_gt_u32 s41, 29
	s_cbranch_scc0 .LBB0_579
	s_cmpk_lt_u32 s21, 0x100
	s_cbranch_scc0 .LBB0_582
	s_barrier

; DI void xcd_barrier(const XcdBarrier& b) {
;     asm volatile("s_waitcnt vmcnt(0)" ::: "memory");
;     __syncthreads();
;     if (threadIdx.x == 0) {
;         unsigned* bar = b.bar;
;         __builtin_amdgcn_s_waitcnt(0);
;         unsigned nloc = b.st[0], nx = b.st[1];
;         if (nloc == 0u) { xcd_barrier_complete(bar, b.x, nloc, nx); b.st[0] = nloc; b.st[1] = nx; }
.LBB0_583:
	s_nop 0
	s_cmp_gt_i32 s27, 5
	s_cselect_b64 s[6:7], -1, 0
	s_and_b64 s[4:5], s[4:5], s[6:7]
	s_andn2_b64 vcc, exec, s[4:5]
	s_cbranch_vccnz .LBB0_651
	s_cmp_gt_i32 s26, -1
	s_mov_b64 s[4:5], -1
	s_cbranch_scc0 .LBB0_638
	s_waitcnt vmcnt(0)
	s_waitcnt vmcnt(0) lgkmcnt(0)
	s_barrier
	s_and_saveexec_b64 s[4:5], s[14:15]
	s_cbranch_execz .LBB0_637
	s_add_i32 s8, 0, 0x23fc0
	v_mov_b32_e32 v1, s8
	s_waitcnt vmcnt(0) expcnt(0) lgkmcnt(0)
	ds_read_b32 v3, v1
	s_add_i32 s8, 0, 0x23fc4
	v_mov_b32_e32 v1, s8
	ds_read_b32 v1, v1
	s_waitcnt lgkmcnt(1)
	v_cmp_ne_u32_e32 vcc, 0, v3
	s_cbranch_vccnz .LBB0_601
	s_add_u32 s8, s24, 0x1000
	s_addc_u32 s9, s25, 0
	s_add_u32 s10, s24, 0x1100
	s_addc_u32 s11, s25, 0
	s_add_u32 s12, s24, 0x1200
	s_addc_u32 s13, s25, 0
	s_mul_i32 s28, s87, s3
	s_add_u32 s16, s24, 0x1300
	s_mul_i32 s28, s28, s86
	s_addc_u32 s17, s25, 0
	s_mov_b32 s29, 1
	v_mov_b32_e32 v17, 0
	s_branch .LBB0_589

;     DI bool next(int i, Unit& u) const { if (i > 0 || c >= 64) return false; u.pm = c & 31; u.pn = 0; u.src = c >> 5; return true; }
; #define PG8_STAGE(bufoff, gbase, voff) do { _Pragma("unroll") for (int _i = 0; _i < 2; ++_i) \
;         __builtin_amdgcn_global_load_lds((const unsigned*)((const char*)(gbase) + (voff)[_i]), (LAS unsigned*)(lds + (bufoff) + ldsw + _i * 8192), 16, 0, 0); } while (0)
; #define PG8_LDA(dst, b, h) do { _Pragma("unroll") for (int m = 0; m < 4; ++m) _Pragma("unroll") for (int k = 0; k < 2; ++k) dst[m][k] = *(const LAS bf16x8*)(lds + PG8_SA(b, h) + aoff + m * 2048 + k * 1024); } while (0)
; #define PG8_LDB(dst, b, h) do { _Pragma("unroll") for (int n = 0; n < 2; ++n) _Pragma("unroll") for (int k = 0; k < 2; ++k) dst[n][k] = *(const LAS bf16x8*)(lds + PG8_SB(b, h) + boff + n * 2048 + k * 1024); } while (0)
; #define PG8_WAIT_V(n) asm volatile("s_waitcnt vmcnt(" #n ")" ::: "memory")
; #define PG8_WAIT_L(n) asm volatile("s_waitcnt lgkmcnt(" #n ")" ::: "memory")
; #define PG8_BAR __builtin_amdgcn_s_barrier()
; template <class Epi, class Sched>
; DI void gemm_phase(LAS unsigned char* lds, const Gemm g, const Sched& S, const Epi& E) {
;     ...
;     for (;;) {
;         const bool has_next = S.next(ui + 1, nxt);
;         E.pre(pre, cur, wr, fr);
;         const char* nA = has_next ? (const char*)(nxt.src ? g.A1 : g.A0) + (size_t)nxt.pm * tstepA : cA; const char* nB = has_next ? (const char*)(nxt.src ? g.B1 : g.B0) + (size_t)nxt.pn * tstepB : cB;
;         for (int t = 0; t < nt; t += 2) {
;             const bool last = (t == nt - 2);
;             const char* a1 = cA + (size_t)(t + 1) * kstep;
;             const char* a2 = last ? nA : cA + (size_t)(t + 2) * kstep; const char* b2 = last ? nB : cB + (size_t)(t + 2) * kstep;
;             const char* a3 = a2 + kstep; const char* b3 = b2 + kstep;
;             PG8_LDB(B0, 0, 0); PG8_LDB(B1, 0, 1); PG8_SCHED; PG8_LDA(At, 0, 0); PG8_STAGE(PG8_SA(1, 1), a1 + hstepA, voffA);
;             PG8_WAIT_V(8); PG8_WAIT_L(0); PG8_BAR; PG8_MMA(0, 0, At, B0); PG8_MMA(0, 1, At, B1); PG8_BAR; PG8_SCHED;
;             PG8_LDA(At, 0, 1); PG8_STAGE(PG8_SB(0, 0), b2, voffB); PG8_STAGE(PG8_SB(0, 1), b2 + hstepB, voffB); PG8_STAGE(PG8_SA(0, 0), a2, voffA);
;             PG8_WAIT_V(8); PG8_WAIT_L(0); PG8_BAR; PG8_MMA(1, 0, At, B0); PG8_MMA(1, 1, At, B1); PG8_BAR; PG8_SCHED;
.Lpk3_w1:
	s_waitcnt lgkmcnt(0)
	s_nop 0
	s_nop 0
	s_barrier
	s_setprio 1
	v_mfma_f32_16x16x32_bf16 v[126:129], v[146:149], v[186:189], v[126:129]
	v_mfma_f32_16x16x32_bf16 v[122:125], v[154:157], v[186:189], v[122:125]
	v_mfma_f32_16x16x32_bf16 v[118:121], v[146:149], v[194:197], v[118:121]
	v_mfma_f32_16x16x32_bf16 v[114:117], v[154:157], v[194:197], v[114:117]
	v_mfma_f32_16x16x32_bf16 v[110:113], v[146:149], v[202:205], v[110:113]
	v_mfma_f32_16x16x32_bf16 v[106:109], v[154:157], v[202:205], v[106:109]
	v_mfma_f32_16x16x32_bf16 v[102:105], v[146:149], v[210:213], v[102:105]
	v_mfma_f32_16x16x32_bf16 v[98:101], v[154:157], v[210:213], v[98:101]
	v_mfma_f32_16x16x32_bf16 v[126:129], v[150:153], v[190:193], v[126:129]
	v_mfma_f32_16x16x32_bf16 v[122:125], v[158:161], v[190:193], v[122:125]
	v_mfma_f32_16x16x32_bf16 v[118:121], v[150:153], v[198:201], v[118:121]
	v_mfma_f32_16x16x32_bf16 v[114:117], v[158:161], v[198:201], v[114:117]
	v_mfma_f32_16x16x32_bf16 v[110:113], v[150:153], v[206:209], v[110:113]
	v_mfma_f32_16x16x32_bf16 v[106:109], v[158:161], v[206:209], v[106:109]
	v_mfma_f32_16x16x32_bf16 v[102:105], v[150:153], v[214:217], v[102:105]
	v_mfma_f32_16x16x32_bf16 v[98:101], v[158:161], v[214:217], v[98:101]
	v_mfma_f32_16x16x32_bf16 v[94:97], v[168:171], v[186:189], v[94:97]
	v_mfma_f32_16x16x32_bf16 v[90:93], v[176:179], v[186:189], v[90:93]
	v_mfma_f32_16x16x32_bf16 v[86:89], v[168:171], v[194:197], v[86:89]
	v_mfma_f32_16x16x32_bf16 v[82:85], v[176:179], v[194:197], v[82:85]
	v_mfma_f32_16x16x32_bf16 v[78:81], v[168:171], v[202:205], v[78:81]
	v_mfma_f32_16x16x32_bf16 v[74:77], v[176:179], v[202:205], v[74:77]
	v_mfma_f32_16x16x32_bf16 v[70:73], v[168:171], v[210:213], v[70:73]
	v_mfma_f32_16x16x32_bf16 v[66:69], v[176:179], v[210:213], v[66:69]
	v_mfma_f32_16x16x32_bf16 v[94:97], v[172:175], v[190:193], v[94:97]
	v_mfma_f32_16x16x32_bf16 v[90:93], v[180:183], v[190:193], v[90:93]
	v_mfma_f32_16x16x32_bf16 v[86:89], v[172:175], v[198:201], v[86:89]
	v_mfma_f32_16x16x32_bf16 v[82:85], v[180:183], v[198:201], v[82:85]
	v_mfma_f32_16x16x32_bf16 v[78:81], v[172:175], v[206:209], v[78:81]
	v_mfma_f32_16x16x32_bf16 v[74:77], v[180:183], v[206:209], v[74:77]
	v_mfma_f32_16x16x32_bf16 v[70:73], v[172:175], v[214:217], v[70:73]
	v_mfma_f32_16x16x32_bf16 v[66:69], v[180:183], v[214:217], v[66:69]
	s_setprio 0
	s_barrier
	s_add_i32 s73, s64, s52
	v_lshl_add_u64 v[218:219], s[46:47], 0, v[132:133]
	s_mov_b32 m0, s73
	ds_read_b128 v[186:189], v167 offset:16384
	ds_read_b128 v[190:193], v167 offset:17408
	ds_read_b128 v[194:197], v167 offset:18432
	ds_read_b128 v[198:201], v167 offset:19456
	ds_read_b128 v[202:205], v167 offset:20480
	ds_read_b128 v[206:209], v167 offset:21504
	ds_read_b128 v[210:213], v167 offset:22528
	ds_read_b128 v[214:217], v167 offset:23552
	global_load_lds_dwordx4 v[218:219], off
	s_add_i32 m0, s73, 0x2000
	s_add_u32 s74, s46, 0x20000
	v_lshl_add_u64 v[220:221], s[46:47], 0, v[136:137]
	s_addc_u32 s75, s47, 0
	s_add_i32 s73, s65, s52
	global_load_lds_dwordx4 v[220:221], off
	v_lshl_add_u64 v[222:223], s[74:75], 0, v[132:133]
	s_mov_b32 m0, s73
	v_lshl_add_u64 v[224:225], s[48:49], 0, v[134:135]
	global_load_lds_dwordx4 v[222:223], off
	v_lshl_add_u64 v[222:223], s[74:75], 0, v[136:137]
	s_add_i32 m0, s73, 0x2000
	s_nop 0
	global_load_lds_dwordx4 v[222:223], off
	v_lshl_add_u64 v[222:223], s[48:49], 0, v[130:131]
	s_mov_b32 m0, s53
	s_nop 0
	global_load_lds_dwordx4 v[222:223], off
	s_mov_b32 m0, s54
	s_nop 0
	global_load_lds_dwordx4 v[224:225], off
	s_cmp_lg_u32 s99, 0
	s_cbranch_scc1 .Lpk3_w2
	s_waitcnt vmcnt(8)
.Lpk3_w2:
	s_mov_b32 s99, 0
	s_waitcnt lgkmcnt(0)
	s_nop 0
	s_barrier
	s_setprio 1
	v_mfma_f32_16x16x32_bf16 v[62:65], v[146:149], v[186:189], v[62:65]
	v_mfma_f32_16x16x32_bf16 v[58:61], v[154:157], v[186:189], v[58:61]
	v_mfma_f32_16x16x32_bf16 v[54:57], v[146:149], v[194:197], v[54:57]
	v_mfma_f32_16x16x32_bf16 v[50:53], v[154:157], v[194:197], v[50:53]
	v_mfma_f32_16x16x32_bf16 v[46:49], v[146:149], v[202:205], v[46:49]
	v_mfma_f32_16x16x32_bf16 v[42:45], v[154:157], v[202:205], v[42:45]
	v_mfma_f32_16x16x32_bf16 v[38:41], v[146:149], v[210:213], v[38:41]
	v_mfma_f32_16x16x32_bf16 v[34:37], v[154:157], v[210:213], v[34:37]
	v_mfma_f32_16x16x32_bf16 v[62:65], v[150:153], v[190:193], v[62:65]
	v_mfma_f32_16x16x32_bf16 v[58:61], v[158:161], v[190:193], v[58:61]
	v_mfma_f32_16x16x32_bf16 v[54:57], v[150:153], v[198:201], v[54:57]
	v_mfma_f32_16x16x32_bf16 v[50:53], v[158:161], v[198:201], v[50:53]
	v_mfma_f32_16x16x32_bf16 v[46:49], v[150:153], v[206:209], v[46:49]
	v_mfma_f32_16x16x32_bf16 v[42:45], v[158:161], v[206:209], v[42:45]
	v_mfma_f32_16x16x32_bf16 v[38:41], v[150:153], v[214:217], v[38:41]
	v_mfma_f32_16x16x32_bf16 v[34:37], v[158:161], v[214:217], v[34:37]
	v_mfma_f32_16x16x32_bf16 v[30:33], v[168:171], v[186:189], v[30:33]
	v_mfma_f32_16x16x32_bf16 v[26:29], v[176:179], v[186:189], v[26:29]
	v_mfma_f32_16x16x32_bf16 v[22:25], v[168:171], v[194:197], v[22:25]
	v_mfma_f32_16x16x32_bf16 v[18:21], v[176:179], v[194:197], v[18:21]
	v_mfma_f32_16x16x32_bf16 v[14:17], v[168:171], v[202:205], v[14:17]
	v_mfma_f32_16x16x32_bf16 v[10:13], v[176:179], v[202:205], v[10:13]
	v_mfma_f32_16x16x32_bf16 v[6:9], v[168:171], v[210:213], v[6:9]
	v_mfma_f32_16x16x32_bf16 v[2:5], v[176:179], v[210:213], v[2:5]
	v_mfma_f32_16x16x32_bf16 v[30:33], v[172:175], v[190:193], v[30:33]
	v_mfma_f32_16x16x32_bf16 v[26:29], v[180:183], v[190:193], v[26:29]
	v_mfma_f32_16x16x32_bf16 v[22:25], v[172:175], v[198:201], v[22:25]
	v_mfma_f32_16x16x32_bf16 v[18:21], v[180:183], v[198:201], v[18:21]
	v_mfma_f32_16x16x32_bf16 v[14:17], v[172:175], v[206:209], v[14:17]
	v_mfma_f32_16x16x32_bf16 v[10:13], v[180:183], v[206:209], v[10:13]
	v_mfma_f32_16x16x32_bf16 v[6:9], v[172:175], v[214:217], v[6:9]
	v_mfma_f32_16x16x32_bf16 v[2:5], v[180:183], v[214:217], v[2:5]
	s_setprio 0
	s_barrier
; #define PG8_STAGE(bufoff, gbase, voff) do { _Pragma("unroll") for (int _i = 0; _i < 2; ++_i) \
;         __builtin_amdgcn_global_load_lds((const unsigned*)((const char*)(gbase) + (voff)[_i]), (LAS unsigned*)(lds + (bufoff) + ldsw + _i * 8192), 16, 0, 0); } while (0)
; #define PG8_LDA(dst, b, h) do { _Pragma("unroll") for (int m = 0; m < 4; ++m) _Pragma("unroll") for (int k = 0; k < 2; ++k) dst[m][k] = *(const LAS bf16x8*)(lds + PG8_SA(b, h) + aoff + m * 2048 + k * 1024); } while (0)
; #define PG8_LDB(dst, b, h) do { _Pragma("unroll") for (int n = 0; n < 2; ++n) _Pragma("unroll") for (int k = 0; k < 2; ++k) dst[n][k] = *(const LAS bf16x8*)(lds + PG8_SB(b, h) + boff + n * 2048 + k * 1024); } while (0)
; #define PG8_MMA(ai, bj, At, Bt) do { __builtin_amdgcn_s_setprio(1); _Pragma("unroll") for (int m = 0; m < 4; ++m) _Pragma("unroll") for (int n = 0; n < 2; ++n) _Pragma("unroll") for (int k = 0; k < 2; ++k) \
;         acc[ai][bj][m][n] = __builtin_amdgcn_mfma_f32_16x16x32_bf16(Bt[n][k], At[m][k], acc[ai][bj][m][n], 0, 0, 0); __builtin_amdgcn_s_setprio(0); } while (0)
; #define PG8_WAIT_V(n) asm volatile("s_waitcnt vmcnt(" #n ")" ::: "memory")
; #define PG8_WAIT_L(n) asm volatile("s_waitcnt lgkmcnt(" #n ")" ::: "memory")
; #define PG8_BAR __builtin_amdgcn_s_barrier()
; #define PG8_SCHED __builtin_amdgcn_sched_barrier(0)
; template <class Epi, class Sched>
; DI void gemm_phase(LAS unsigned char* lds, const Gemm g, const Sched& S, const Epi& E) {
;     ...
;             PG8_LDB(B0, 1, 0); PG8_LDB(B1, 1, 1); PG8_SCHED; PG8_LDA(At, 1, 0); PG8_STAGE(PG8_SA(0, 1), a2 + hstepA, voffA);
;             PG8_WAIT_V(8); PG8_WAIT_L(0); PG8_BAR; PG8_MMA(0, 0, At, B0); PG8_MMA(0, 1, At, B1); PG8_BAR; PG8_SCHED;
;             PG8_LDA(At, 1, 1); PG8_STAGE(PG8_SB(1, 0), b3, voffB); PG8_STAGE(PG8_SB(1, 1), b3 + hstepB, voffB); PG8_STAGE(PG8_SA(1, 0), a3, voffA);
;             PG8_WAIT_V(8); PG8_WAIT_L(0); PG8_BAR; PG8_MMA(1, 0, At, B0); PG8_MMA(1, 1, At, B1); PG8_BAR; PG8_SCHED;
	s_add_i32 s73, 0, 0x18000
	s_add_i32 s74, 0, 0x1c000
	v_add_u32_e32 v158, s73, v162
	v_add_u32_e32 v180, s74, v162
	ds_read_b128 v[146:149], v158
	ds_read_b128 v[150:153], v158 offset:1024
	ds_read_b128 v[154:157], v158 offset:2048
	ds_read_b128 v[158:161], v158 offset:3072
	ds_read_b128 v[168:171], v180
	ds_read_b128 v[172:175], v180 offset:1024
	ds_read_b128 v[176:179], v180 offset:2048
	ds_read_b128 v[180:183], v180 offset:3072
	s_add_u32 s48, s48, 0x20000
	s_addc_u32 s49, s49, 0
	s_mov_b32 m0, s55
	v_lshl_add_u64 v[226:227], s[48:49], 0, v[130:131]
	ds_read_b128 v[186:189], v167 offset:32768
	ds_read_b128 v[190:193], v167 offset:33792
	ds_read_b128 v[194:197], v167 offset:34816
	ds_read_b128 v[198:201], v167 offset:35840
	ds_read_b128 v[202:205], v167 offset:36864
	ds_read_b128 v[206:209], v167 offset:37888
	ds_read_b128 v[210:213], v167 offset:38912
	ds_read_b128 v[214:217], v167 offset:39936
	global_load_lds_dwordx4 v[226:227], off
	v_lshl_add_u64 v[226:227], s[48:49], 0, v[134:135]
	s_mov_b32 m0, s56
	s_nop 0
	global_load_lds_dwordx4 v[226:227], off
	s_waitcnt vmcnt(8)
	s_waitcnt lgkmcnt(0)
	s_barrier
	s_setprio 1
	v_mfma_f32_16x16x32_bf16 v[126:129], v[146:149], v[186:189], v[126:129]
	v_mfma_f32_16x16x32_bf16 v[122:125], v[154:157], v[186:189], v[122:125]
	v_mfma_f32_16x16x32_bf16 v[118:121], v[146:149], v[194:197], v[118:121]
	v_mfma_f32_16x16x32_bf16 v[114:117], v[154:157], v[194:197], v[114:117]
	v_mfma_f32_16x16x32_bf16 v[110:113], v[146:149], v[202:205], v[110:113]
	v_mfma_f32_16x16x32_bf16 v[106:109], v[154:157], v[202:205], v[106:109]
	v_mfma_f32_16x16x32_bf16 v[102:105], v[146:149], v[210:213], v[102:105]
	v_mfma_f32_16x16x32_bf16 v[98:101], v[154:157], v[210:213], v[98:101]
	v_mfma_f32_16x16x32_bf16 v[126:129], v[150:153], v[190:193], v[126:129]
	v_mfma_f32_16x16x32_bf16 v[122:125], v[158:161], v[190:193], v[122:125]
	v_mfma_f32_16x16x32_bf16 v[118:121], v[150:153], v[198:201], v[118:121]
	v_mfma_f32_16x16x32_bf16 v[114:117], v[158:161], v[198:201], v[114:117]
	v_mfma_f32_16x16x32_bf16 v[110:113], v[150:153], v[206:209], v[110:113]
	v_mfma_f32_16x16x32_bf16 v[106:109], v[158:161], v[206:209], v[106:109]
	v_mfma_f32_16x16x32_bf16 v[102:105], v[150:153], v[214:217], v[102:105]
	v_mfma_f32_16x16x32_bf16 v[98:101], v[158:161], v[214:217], v[98:101]
	v_mfma_f32_16x16x32_bf16 v[94:97], v[168:171], v[186:189], v[94:97]
	v_mfma_f32_16x16x32_bf16 v[90:93], v[176:179], v[186:189], v[90:93]
	v_mfma_f32_16x16x32_bf16 v[86:89], v[168:171], v[194:197], v[86:89]
	v_mfma_f32_16x16x32_bf16 v[82:85], v[176:179], v[194:197], v[82:85]
	v_mfma_f32_16x16x32_bf16 v[78:81], v[168:171], v[202:205], v[78:81]
	v_mfma_f32_16x16x32_bf16 v[74:77], v[176:179], v[202:205], v[74:77]
	v_mfma_f32_16x16x32_bf16 v[70:73], v[168:171], v[210:213], v[70:73]
	v_mfma_f32_16x16x32_bf16 v[66:69], v[176:179], v[210:213], v[66:69]
	v_mfma_f32_16x16x32_bf16 v[94:97], v[172:175], v[190:193], v[94:97]
	v_mfma_f32_16x16x32_bf16 v[90:93], v[180:183], v[190:193], v[90:93]
	v_mfma_f32_16x16x32_bf16 v[86:89], v[172:175], v[198:201], v[86:89]
	v_mfma_f32_16x16x32_bf16 v[82:85], v[180:183], v[198:201], v[82:85]
	v_mfma_f32_16x16x32_bf16 v[78:81], v[172:175], v[206:209], v[78:81]
	v_mfma_f32_16x16x32_bf16 v[74:77], v[180:183], v[206:209], v[74:77]
	v_mfma_f32_16x16x32_bf16 v[70:73], v[172:175], v[214:217], v[70:73]
	v_mfma_f32_16x16x32_bf16 v[66:69], v[180:183], v[214:217], v[66:69]
	s_setprio 0
	s_barrier
	s_add_i32 s48, s73, s52
	v_lshl_add_u64 v[218:219], v[218:219], 0, s[20:21]
	s_mov_b32 m0, s48
	ds_read_b128 v[186:189], v167 offset:49152
	ds_read_b128 v[190:193], v167 offset:50176
	ds_read_b128 v[194:197], v167 offset:51200
	ds_read_b128 v[198:201], v167 offset:52224
	ds_read_b128 v[202:205], v167 offset:53248
	ds_read_b128 v[206:209], v167 offset:54272
	ds_read_b128 v[210:213], v167 offset:55296
	ds_read_b128 v[214:217], v167 offset:56320
	global_load_lds_dwordx4 v[218:219], off
	s_add_i32 m0, s48, 0x2000
	s_add_u32 s46, s46, 0x20080
	v_lshl_add_u64 v[218:219], v[220:221], 0, s[20:21]
	s_addc_u32 s47, s47, 0
	s_add_i32 s48, s74, s52
	global_load_lds_dwordx4 v[218:219], off
	v_lshl_add_u64 v[218:219], s[46:47], 0, v[132:133]
	s_mov_b32 m0, s48
	s_nop 0
	global_load_lds_dwordx4 v[218:219], off
	v_lshl_add_u64 v[218:219], s[46:47], 0, v[136:137]
	s_add_i32 m0, s48, 0x2000
	s_nop 0
	global_load_lds_dwordx4 v[218:219], off
	v_lshl_add_u64 v[218:219], v[222:223], 0, s[20:21]
	s_mov_b32 m0, s61
	s_nop 0
	global_load_lds_dwordx4 v[218:219], off
	v_lshl_add_u64 v[218:219], v[224:225], 0, s[20:21]
	s_mov_b32 m0, s62
	s_nop 0
	global_load_lds_dwordx4 v[218:219], off
	s_waitcnt vmcnt(8)
	s_waitcnt lgkmcnt(0)
	s_nop 0
	s_barrier
	s_setprio 1
	v_mfma_f32_16x16x32_bf16 v[62:65], v[146:149], v[186:189], v[62:65]
	v_mfma_f32_16x16x32_bf16 v[58:61], v[154:157], v[186:189], v[58:61]
	v_mfma_f32_16x16x32_bf16 v[54:57], v[146:149], v[194:197], v[54:57]
	v_mfma_f32_16x16x32_bf16 v[50:53], v[154:157], v[194:197], v[50:53]
	v_mfma_f32_16x16x32_bf16 v[46:49], v[146:149], v[202:205], v[46:49]
	v_mfma_f32_16x16x32_bf16 v[42:45], v[154:157], v[202:205], v[42:45]
	v_mfma_f32_16x16x32_bf16 v[38:41], v[146:149], v[210:213], v[38:41]
	v_mfma_f32_16x16x32_bf16 v[34:37], v[154:157], v[210:213], v[34:37]
	v_mfma_f32_16x16x32_bf16 v[62:65], v[150:153], v[190:193], v[62:65]
	v_mfma_f32_16x16x32_bf16 v[58:61], v[158:161], v[190:193], v[58:61]
	v_mfma_f32_16x16x32_bf16 v[54:57], v[150:153], v[198:201], v[54:57]
	v_mfma_f32_16x16x32_bf16 v[50:53], v[158:161], v[198:201], v[50:53]
	v_mfma_f32_16x16x32_bf16 v[46:49], v[150:153], v[206:209], v[46:49]
	v_mfma_f32_16x16x32_bf16 v[42:45], v[158:161], v[206:209], v[42:45]
	v_mfma_f32_16x16x32_bf16 v[38:41], v[150:153], v[214:217], v[38:41]
	v_mfma_f32_16x16x32_bf16 v[34:37], v[158:161], v[214:217], v[34:37]
	v_mfma_f32_16x16x32_bf16 v[30:33], v[168:171], v[186:189], v[30:33]
	v_mfma_f32_16x16x32_bf16 v[26:29], v[176:179], v[186:189], v[26:29]
	v_mfma_f32_16x16x32_bf16 v[22:25], v[168:171], v[194:197], v[22:25]
	v_mfma_f32_16x16x32_bf16 v[18:21], v[176:179], v[194:197], v[18:21]
	v_mfma_f32_16x16x32_bf16 v[14:17], v[168:171], v[202:205], v[14:17]
	v_mfma_f32_16x16x32_bf16 v[10:13], v[176:179], v[202:205], v[10:13]
	v_mfma_f32_16x16x32_bf16 v[6:9], v[168:171], v[210:213], v[6:9]
	v_mfma_f32_16x16x32_bf16 v[2:5], v[176:179], v[210:213], v[2:5]
	v_mfma_f32_16x16x32_bf16 v[30:33], v[172:175], v[190:193], v[30:33]
	v_mfma_f32_16x16x32_bf16 v[26:29], v[180:183], v[190:193], v[26:29]
	v_mfma_f32_16x16x32_bf16 v[22:25], v[172:175], v[198:201], v[22:25]
	v_mfma_f32_16x16x32_bf16 v[18:21], v[180:183], v[198:201], v[18:21]
	v_mfma_f32_16x16x32_bf16 v[14:17], v[172:175], v[206:209], v[14:17]
	v_mfma_f32_16x16x32_bf16 v[10:13], v[180:183], v[206:209], v[10:13]
	v_mfma_f32_16x16x32_bf16 v[6:9], v[172:175], v[214:217], v[6:9]
	v_mfma_f32_16x16x32_bf16 v[2:5], v[180:183], v[214:217], v[2:5]
	s_setprio 0
	s_barrier
	s_add_i32 s72, s72, 2
	s_add_u32 s44, s44, 0x100
	s_addc_u32 s45, s45, 0
	s_add_u32 s70, s70, 0x100
	s_addc_u32 s71, s71, 0
	s_cmp_gt_u32 s72, 5
; #define PG8_STAGE(bufoff, gbase, voff) do { _Pragma("unroll") for (int _i = 0; _i < 2; ++_i) \
;         __builtin_amdgcn_global_load_lds((const unsigned*)((const char*)(gbase) + (voff)[_i]), (LAS unsigned*)(lds + (bufoff) + ldsw + _i * 8192), 16, 0, 0); } while (0)
; #define PG8_LDA(dst, b, h) do { _Pragma("unroll") for (int m = 0; m < 4; ++m) _Pragma("unroll") for (int k = 0; k < 2; ++k) dst[m][k] = *(const LAS bf16x8*)(lds + PG8_SA(b, h) + aoff + m * 2048 + k * 1024); } while (0)
; #define PG8_LDB(dst, b, h) do { _Pragma("unroll") for (int n = 0; n < 2; ++n) _Pragma("unroll") for (int k = 0; k < 2; ++k) dst[n][k] = *(const LAS bf16x8*)(lds + PG8_SB(b, h) + boff + n * 2048 + k * 1024); } while (0)
; #define PG8_MMA(ai, bj, At, Bt) do { __builtin_amdgcn_s_setprio(1); _Pragma("unroll") for (int m = 0; m < 4; ++m) _Pragma("unroll") for (int n = 0; n < 2; ++n) _Pragma("unroll") for (int k = 0; k < 2; ++k) \
;         acc[ai][bj][m][n] = __builtin_amdgcn_mfma_f32_16x16x32_bf16(Bt[n][k], At[m][k], acc[ai][bj][m][n], 0, 0, 0); __builtin_amdgcn_s_setprio(0); } while (0)
; #define PG8_WAIT_V(n) asm volatile("s_waitcnt vmcnt(" #n ")" ::: "memory")
; #define PG8_WAIT_L(n) asm volatile("s_waitcnt lgkmcnt(" #n ")" ::: "memory")
; #define PG8_BAR __builtin_amdgcn_s_barrier()
; #define PG8_SCHED __builtin_amdgcn_sched_barrier(0)
; template <class Epi, class Sched>
; DI void gemm_phase(LAS unsigned char* lds, const Gemm g, const Sched& S, const Epi& E) {
;     ...
;         for (int t = 0; t < nt; t += 2) {
;             const bool last = (t == nt - 2);
;             const char* a1 = cA + (size_t)(t + 1) * kstep;
;             const char* a2 = last ? nA : cA + (size_t)(t + 2) * kstep; const char* b2 = last ? nB : cB + (size_t)(t + 2) * kstep;
;             const char* a3 = a2 + kstep; const char* b3 = b2 + kstep;
;             PG8_LDB(B0, 0, 0); PG8_LDB(B1, 0, 1); PG8_SCHED; PG8_LDA(At, 0, 0); PG8_STAGE(PG8_SA(1, 1), a1 + hstepA, voffA);
;             PG8_WAIT_V(8); PG8_WAIT_L(0); PG8_BAR; PG8_MMA(0, 0, At, B0); PG8_MMA(0, 1, At, B1); PG8_BAR; PG8_SCHED;
;             PG8_LDA(At, 0, 1); PG8_STAGE(PG8_SB(0, 0), b2, voffB); PG8_STAGE(PG8_SB(0, 1), b2 + hstepB, voffB); PG8_STAGE(PG8_SA(0, 0), a2, voffA);
;             PG8_WAIT_V(8); PG8_WAIT_L(0); PG8_BAR; PG8_MMA(1, 0, At, B0); PG8_MMA(1, 1, At, B1); PG8_BAR; PG8_SCHED;
.LBB0_972:
	v_add_u32_e32 v158, s64, v162
	v_add_u32_e32 v180, s65, v162
	ds_read_b128 v[146:149], v158
	ds_read_b128 v[150:153], v158 offset:1024
	ds_read_b128 v[154:157], v158 offset:2048
	ds_read_b128 v[158:161], v158 offset:3072
	ds_read_b128 v[168:171], v180
	ds_read_b128 v[172:175], v180 offset:1024
	ds_read_b128 v[176:179], v180 offset:2048
	ds_read_b128 v[180:183], v180 offset:3072
	s_add_u32 s46, s44, 0xfffe0080
	s_addc_u32 s47, s45, -1
	s_cmp_eq_u32 s72, 4
	s_cselect_b32 s49, s39, s47
	s_cselect_b32 s48, s68, s46
	s_cselect_b32 s47, s37, s71
	s_cselect_b32 s46, s69, s70
	v_lshl_add_u64 v[218:219], s[44:45], 0, v[138:139]
	s_add_i32 m0, s53, 0xc000
	ds_read_b128 v[186:189], v167
	ds_read_b128 v[190:193], v167 offset:1024
	ds_read_b128 v[194:197], v167 offset:2048
	ds_read_b128 v[198:201], v167 offset:3072
	ds_read_b128 v[202:205], v167 offset:4096
	ds_read_b128 v[206:209], v167 offset:5120
	ds_read_b128 v[210:213], v167 offset:6144
	ds_read_b128 v[214:217], v167 offset:7168
	global_load_lds_dwordx4 v[218:219], off
	v_lshl_add_u64 v[218:219], s[44:45], 0, v[140:141]
	s_add_i32 m0, s53, 0xe000
	s_nop 0
	global_load_lds_dwordx4 v[218:219], off
	s_waitcnt vmcnt(8)
	s_waitcnt lgkmcnt(0)
	s_nop 0
	s_barrier
	s_setprio 1
	v_mfma_f32_16x16x32_bf16 v[126:129], v[146:149], v[186:189], v[126:129]
	v_mfma_f32_16x16x32_bf16 v[122:125], v[154:157], v[186:189], v[122:125]
	v_mfma_f32_16x16x32_bf16 v[118:121], v[146:149], v[194:197], v[118:121]
	v_mfma_f32_16x16x32_bf16 v[114:117], v[154:157], v[194:197], v[114:117]
	v_mfma_f32_16x16x32_bf16 v[110:113], v[146:149], v[202:205], v[110:113]
	v_mfma_f32_16x16x32_bf16 v[106:109], v[154:157], v[202:205], v[106:109]
	v_mfma_f32_16x16x32_bf16 v[102:105], v[146:149], v[210:213], v[102:105]
	v_mfma_f32_16x16x32_bf16 v[98:101], v[154:157], v[210:213], v[98:101]
	v_mfma_f32_16x16x32_bf16 v[126:129], v[150:153], v[190:193], v[126:129]
	v_mfma_f32_16x16x32_bf16 v[122:125], v[158:161], v[190:193], v[122:125]
	v_mfma_f32_16x16x32_bf16 v[118:121], v[150:153], v[198:201], v[118:121]
	v_mfma_f32_16x16x32_bf16 v[114:117], v[158:161], v[198:201], v[114:117]
	v_mfma_f32_16x16x32_bf16 v[110:113], v[150:153], v[206:209], v[110:113]
	v_mfma_f32_16x16x32_bf16 v[106:109], v[158:161], v[206:209], v[106:109]
	v_mfma_f32_16x16x32_bf16 v[102:105], v[150:153], v[214:217], v[102:105]
	v_mfma_f32_16x16x32_bf16 v[98:101], v[158:161], v[214:217], v[98:101]
	v_mfma_f32_16x16x32_bf16 v[94:97], v[168:171], v[186:189], v[94:97]
	v_mfma_f32_16x16x32_bf16 v[90:93], v[176:179], v[186:189], v[90:93]
	v_mfma_f32_16x16x32_bf16 v[86:89], v[168:171], v[194:197], v[86:89]
	v_mfma_f32_16x16x32_bf16 v[82:85], v[176:179], v[194:197], v[82:85]
	v_mfma_f32_16x16x32_bf16 v[78:81], v[168:171], v[202:205], v[78:81]
	v_mfma_f32_16x16x32_bf16 v[74:77], v[176:179], v[202:205], v[74:77]
	v_mfma_f32_16x16x32_bf16 v[70:73], v[168:171], v[210:213], v[70:73]
	v_mfma_f32_16x16x32_bf16 v[66:69], v[176:179], v[210:213], v[66:69]
	v_mfma_f32_16x16x32_bf16 v[94:97], v[172:175], v[190:193], v[94:97]
	v_mfma_f32_16x16x32_bf16 v[90:93], v[180:183], v[190:193], v[90:93]
	v_mfma_f32_16x16x32_bf16 v[86:89], v[172:175], v[198:201], v[86:89]
	v_mfma_f32_16x16x32_bf16 v[82:85], v[180:183], v[198:201], v[82:85]
	v_mfma_f32_16x16x32_bf16 v[78:81], v[172:175], v[206:209], v[78:81]
	v_mfma_f32_16x16x32_bf16 v[74:77], v[180:183], v[206:209], v[74:77]
	v_mfma_f32_16x16x32_bf16 v[70:73], v[172:175], v[214:217], v[70:73]
	v_mfma_f32_16x16x32_bf16 v[66:69], v[180:183], v[214:217], v[66:69]
	s_setprio 0
	s_barrier
	s_add_i32 s73, s64, s52
	v_lshl_add_u64 v[218:219], s[46:47], 0, v[132:133]
	s_mov_b32 m0, s73
	ds_read_b128 v[186:189], v167 offset:16384
	ds_read_b128 v[190:193], v167 offset:17408
	ds_read_b128 v[194:197], v167 offset:18432
	ds_read_b128 v[198:201], v167 offset:19456
	ds_read_b128 v[202:205], v167 offset:20480
	ds_read_b128 v[206:209], v167 offset:21504
	ds_read_b128 v[210:213], v167 offset:22528
	ds_read_b128 v[214:217], v167 offset:23552
	global_load_lds_dwordx4 v[218:219], off
	s_add_i32 m0, s73, 0x2000
	s_add_u32 s74, s46, 0x20000
	v_lshl_add_u64 v[220:221], s[46:47], 0, v[136:137]
	s_addc_u32 s75, s47, 0
	s_add_i32 s73, s65, s52
	global_load_lds_dwordx4 v[220:221], off
	v_lshl_add_u64 v[222:223], s[74:75], 0, v[132:133]
	s_mov_b32 m0, s73
	v_lshl_add_u64 v[224:225], s[48:49], 0, v[134:135]
	global_load_lds_dwordx4 v[222:223], off
	v_lshl_add_u64 v[222:223], s[74:75], 0, v[136:137]
	s_add_i32 m0, s73, 0x2000
	s_nop 0
	global_load_lds_dwordx4 v[222:223], off
	v_lshl_add_u64 v[222:223], s[48:49], 0, v[130:131]
	s_mov_b32 m0, s53
	s_nop 0
	global_load_lds_dwordx4 v[222:223], off
	s_mov_b32 m0, s54
	s_nop 0
	global_load_lds_dwordx4 v[224:225], off
	s_waitcnt vmcnt(8)
	s_waitcnt lgkmcnt(0)
	s_barrier
; #define PG8_STAGE(bufoff, gbase, voff) do { _Pragma("unroll") for (int _i = 0; _i < 2; ++_i) \
;         __builtin_amdgcn_global_load_lds((const unsigned*)((const char*)(gbase) + (voff)[_i]), (LAS unsigned*)(lds + (bufoff) + ldsw + _i * 8192), 16, 0, 0); } while (0)
; #define PG8_LDA(dst, b, h) do { _Pragma("unroll") for (int m = 0; m < 4; ++m) _Pragma("unroll") for (int k = 0; k < 2; ++k) dst[m][k] = *(const LAS bf16x8*)(lds + PG8_SA(b, h) + aoff + m * 2048 + k * 1024); } while (0)
; #define PG8_LDB(dst, b, h) do { _Pragma("unroll") for (int n = 0; n < 2; ++n) _Pragma("unroll") for (int k = 0; k < 2; ++k) dst[n][k] = *(const LAS bf16x8*)(lds + PG8_SB(b, h) + boff + n * 2048 + k * 1024); } while (0)
; #define PG8_MMA(ai, bj, At, Bt) do { __builtin_amdgcn_s_setprio(1); _Pragma("unroll") for (int m = 0; m < 4; ++m) _Pragma("unroll") for (int n = 0; n < 2; ++n) _Pragma("unroll") for (int k = 0; k < 2; ++k) \
;         acc[ai][bj][m][n] = __builtin_amdgcn_mfma_f32_16x16x32_bf16(Bt[n][k], At[m][k], acc[ai][bj][m][n], 0, 0, 0); __builtin_amdgcn_s_setprio(0); } while (0)
; #define PG8_WAIT_V(n) asm volatile("s_waitcnt vmcnt(" #n ")" ::: "memory")
; #define PG8_WAIT_L(n) asm volatile("s_waitcnt lgkmcnt(" #n ")" ::: "memory")
; #define PG8_BAR __builtin_amdgcn_s_barrier()
; #define PG8_SCHED __builtin_amdgcn_sched_barrier(0)
; template <class Epi, class Sched>
; DI void gemm_phase(LAS unsigned char* lds, const Gemm g, const Sched& S, const Epi& E) {
;     ...
;             PG8_WAIT_V(8); PG8_WAIT_L(0); PG8_BAR; PG8_MMA(1, 0, At, B0); PG8_MMA(1, 1, At, B1); PG8_BAR; PG8_SCHED;
;             PG8_LDB(B0, 1, 0); PG8_LDB(B1, 1, 1); PG8_SCHED; PG8_LDA(At, 1, 0); PG8_STAGE(PG8_SA(0, 1), a2 + hstepA, voffA);
;             PG8_WAIT_V(8); PG8_WAIT_L(0); PG8_BAR; PG8_MMA(0, 0, At, B0); PG8_MMA(0, 1, At, B1); PG8_BAR; PG8_SCHED;
	s_setprio 1
	v_mfma_f32_16x16x32_bf16 v[62:65], v[146:149], v[186:189], v[62:65]
	v_mfma_f32_16x16x32_bf16 v[58:61], v[154:157], v[186:189], v[58:61]
	v_mfma_f32_16x16x32_bf16 v[54:57], v[146:149], v[194:197], v[54:57]
	v_mfma_f32_16x16x32_bf16 v[50:53], v[154:157], v[194:197], v[50:53]
	v_mfma_f32_16x16x32_bf16 v[46:49], v[146:149], v[202:205], v[46:49]
	v_mfma_f32_16x16x32_bf16 v[42:45], v[154:157], v[202:205], v[42:45]
	v_mfma_f32_16x16x32_bf16 v[38:41], v[146:149], v[210:213], v[38:41]
	v_mfma_f32_16x16x32_bf16 v[34:37], v[154:157], v[210:213], v[34:37]
	v_mfma_f32_16x16x32_bf16 v[62:65], v[150:153], v[190:193], v[62:65]
	v_mfma_f32_16x16x32_bf16 v[58:61], v[158:161], v[190:193], v[58:61]
	v_mfma_f32_16x16x32_bf16 v[54:57], v[150:153], v[198:201], v[54:57]
	v_mfma_f32_16x16x32_bf16 v[50:53], v[158:161], v[198:201], v[50:53]
	v_mfma_f32_16x16x32_bf16 v[46:49], v[150:153], v[206:209], v[46:49]
	v_mfma_f32_16x16x32_bf16 v[42:45], v[158:161], v[206:209], v[42:45]
	v_mfma_f32_16x16x32_bf16 v[38:41], v[150:153], v[214:217], v[38:41]
	v_mfma_f32_16x16x32_bf16 v[34:37], v[158:161], v[214:217], v[34:37]
	v_mfma_f32_16x16x32_bf16 v[30:33], v[168:171], v[186:189], v[30:33]
	v_mfma_f32_16x16x32_bf16 v[26:29], v[176:179], v[186:189], v[26:29]
	v_mfma_f32_16x16x32_bf16 v[22:25], v[168:171], v[194:197], v[22:25]
	v_mfma_f32_16x16x32_bf16 v[18:21], v[176:179], v[194:197], v[18:21]
	v_mfma_f32_16x16x32_bf16 v[14:17], v[168:171], v[202:205], v[14:17]
	v_mfma_f32_16x16x32_bf16 v[10:13], v[176:179], v[202:205], v[10:13]
	v_mfma_f32_16x16x32_bf16 v[6:9], v[168:171], v[210:213], v[6:9]
	v_mfma_f32_16x16x32_bf16 v[2:5], v[176:179], v[210:213], v[2:5]
	v_mfma_f32_16x16x32_bf16 v[30:33], v[172:175], v[190:193], v[30:33]
	v_mfma_f32_16x16x32_bf16 v[26:29], v[180:183], v[190:193], v[26:29]
	v_mfma_f32_16x16x32_bf16 v[22:25], v[172:175], v[198:201], v[22:25]
	v_mfma_f32_16x16x32_bf16 v[18:21], v[180:183], v[198:201], v[18:21]
	v_mfma_f32_16x16x32_bf16 v[14:17], v[172:175], v[206:209], v[14:17]
	v_mfma_f32_16x16x32_bf16 v[10:13], v[180:183], v[206:209], v[10:13]
	v_mfma_f32_16x16x32_bf16 v[6:9], v[172:175], v[214:217], v[6:9]
	v_mfma_f32_16x16x32_bf16 v[2:5], v[180:183], v[214:217], v[2:5]
	s_setprio 0
	s_barrier
	s_add_i32 s73, 0, 0x18000
	s_add_i32 s74, 0, 0x1c000
	v_add_u32_e32 v158, s73, v162
	v_add_u32_e32 v180, s74, v162
	ds_read_b128 v[146:149], v158
	ds_read_b128 v[150:153], v158 offset:1024
	ds_read_b128 v[154:157], v158 offset:2048
	ds_read_b128 v[158:161], v158 offset:3072
	ds_read_b128 v[168:171], v180
	ds_read_b128 v[172:175], v180 offset:1024
	ds_read_b128 v[176:179], v180 offset:2048
	ds_read_b128 v[180:183], v180 offset:3072
	s_add_u32 s48, s48, 0x20000
	s_addc_u32 s49, s49, 0
	s_mov_b32 m0, s55
	v_lshl_add_u64 v[226:227], s[48:49], 0, v[130:131]
	ds_read_b128 v[186:189], v167 offset:32768
	ds_read_b128 v[190:193], v167 offset:33792
	ds_read_b128 v[194:197], v167 offset:34816
	ds_read_b128 v[198:201], v167 offset:35840
	ds_read_b128 v[202:205], v167 offset:36864
	ds_read_b128 v[206:209], v167 offset:37888
	ds_read_b128 v[210:213], v167 offset:38912
	ds_read_b128 v[214:217], v167 offset:39936
	global_load_lds_dwordx4 v[226:227], off
	v_lshl_add_u64 v[226:227], s[48:49], 0, v[134:135]
	s_mov_b32 m0, s56
	s_nop 0
	global_load_lds_dwordx4 v[226:227], off
	s_waitcnt vmcnt(8)
	s_waitcnt lgkmcnt(0)
	s_barrier
	s_setprio 1
	v_mfma_f32_16x16x32_bf16 v[126:129], v[146:149], v[186:189], v[126:129]
	v_mfma_f32_16x16x32_bf16 v[122:125], v[154:157], v[186:189], v[122:125]
	v_mfma_f32_16x16x32_bf16 v[118:121], v[146:149], v[194:197], v[118:121]
	v_mfma_f32_16x16x32_bf16 v[114:117], v[154:157], v[194:197], v[114:117]
	v_mfma_f32_16x16x32_bf16 v[110:113], v[146:149], v[202:205], v[110:113]
	v_mfma_f32_16x16x32_bf16 v[106:109], v[154:157], v[202:205], v[106:109]
	v_mfma_f32_16x16x32_bf16 v[102:105], v[146:149], v[210:213], v[102:105]
	v_mfma_f32_16x16x32_bf16 v[98:101], v[154:157], v[210:213], v[98:101]
	v_mfma_f32_16x16x32_bf16 v[126:129], v[150:153], v[190:193], v[126:129]
	v_mfma_f32_16x16x32_bf16 v[122:125], v[158:161], v[190:193], v[122:125]
	v_mfma_f32_16x16x32_bf16 v[118:121], v[150:153], v[198:201], v[118:121]
	v_mfma_f32_16x16x32_bf16 v[114:117], v[158:161], v[198:201], v[114:117]
	v_mfma_f32_16x16x32_bf16 v[110:113], v[150:153], v[206:209], v[110:113]
	v_mfma_f32_16x16x32_bf16 v[106:109], v[158:161], v[206:209], v[106:109]
	v_mfma_f32_16x16x32_bf16 v[102:105], v[150:153], v[214:217], v[102:105]
	v_mfma_f32_16x16x32_bf16 v[98:101], v[158:161], v[214:217], v[98:101]
	v_mfma_f32_16x16x32_bf16 v[94:97], v[168:171], v[186:189], v[94:97]
	v_mfma_f32_16x16x32_bf16 v[90:93], v[176:179], v[186:189], v[90:93]
	v_mfma_f32_16x16x32_bf16 v[86:89], v[168:171], v[194:197], v[86:89]
	v_mfma_f32_16x16x32_bf16 v[82:85], v[176:179], v[194:197], v[82:85]
	v_mfma_f32_16x16x32_bf16 v[78:81], v[168:171], v[202:205], v[78:81]
	v_mfma_f32_16x16x32_bf16 v[74:77], v[176:179], v[202:205], v[74:77]
	v_mfma_f32_16x16x32_bf16 v[70:73], v[168:171], v[210:213], v[70:73]
	v_mfma_f32_16x16x32_bf16 v[66:69], v[176:179], v[210:213], v[66:69]
	v_mfma_f32_16x16x32_bf16 v[94:97], v[172:175], v[190:193], v[94:97]
	v_mfma_f32_16x16x32_bf16 v[90:93], v[180:183], v[190:193], v[90:93]
	v_mfma_f32_16x16x32_bf16 v[86:89], v[172:175], v[198:201], v[86:89]
	v_mfma_f32_16x16x32_bf16 v[82:85], v[180:183], v[198:201], v[82:85]
	v_mfma_f32_16x16x32_bf16 v[78:81], v[172:175], v[206:209], v[78:81]
	v_mfma_f32_16x16x32_bf16 v[74:77], v[180:183], v[206:209], v[74:77]
	v_mfma_f32_16x16x32_bf16 v[70:73], v[172:175], v[214:217], v[70:73]
	v_mfma_f32_16x16x32_bf16 v[66:69], v[180:183], v[214:217], v[66:69]
	s_setprio 0
	s_barrier
; #define PG8_STAGE(bufoff, gbase, voff) do { _Pragma("unroll") for (int _i = 0; _i < 2; ++_i) \
;         __builtin_amdgcn_global_load_lds((const unsigned*)((const char*)(gbase) + (voff)[_i]), (LAS unsigned*)(lds + (bufoff) + ldsw + _i * 8192), 16, 0, 0); } while (0)
; #define PG8_LDA(dst, b, h) do { _Pragma("unroll") for (int m = 0; m < 4; ++m) _Pragma("unroll") for (int k = 0; k < 2; ++k) dst[m][k] = *(const LAS bf16x8*)(lds + PG8_SA(b, h) + aoff + m * 2048 + k * 1024); } while (0)
; #define PG8_MMA(ai, bj, At, Bt) do { __builtin_amdgcn_s_setprio(1); _Pragma("unroll") for (int m = 0; m < 4; ++m) _Pragma("unroll") for (int n = 0; n < 2; ++n) _Pragma("unroll") for (int k = 0; k < 2; ++k) \
;         acc[ai][bj][m][n] = __builtin_amdgcn_mfma_f32_16x16x32_bf16(Bt[n][k], At[m][k], acc[ai][bj][m][n], 0, 0, 0); __builtin_amdgcn_s_setprio(0); } while (0)
; #define PG8_WAIT_V(n) asm volatile("s_waitcnt vmcnt(" #n ")" ::: "memory")
; #define PG8_WAIT_L(n) asm volatile("s_waitcnt lgkmcnt(" #n ")" ::: "memory")
; #define PG8_BAR __builtin_amdgcn_s_barrier()
; #define PG8_SCHED __builtin_amdgcn_sched_barrier(0)
;     DI void pre(Pre& pr, const pg8::Unit& u, int wr, int fr) const { load_rows(pr, ssq, u, wr, fr); }
;     DI void pre(Pre& pr, const pg8::Unit& u, int wr, int fr) const { load_rows(pr, ssq, u, wr, fr); }
; template <class Epi, class Sched>
; DI void gemm_phase(LAS unsigned char* lds, const Gemm g, const Sched& S, const Epi& E) {
;     ...
;             PG8_LDA(At, 1, 1); PG8_STAGE(PG8_SB(1, 0), b3, voffB); PG8_STAGE(PG8_SB(1, 1), b3 + hstepB, voffB); PG8_STAGE(PG8_SA(1, 0), a3, voffA);
;             PG8_WAIT_V(8); PG8_WAIT_L(0); PG8_BAR; PG8_MMA(1, 0, At, B0); PG8_MMA(1, 1, At, B1); PG8_BAR; PG8_SCHED;
;         }
;         if (wr == 0) PG8_BAR;
;         E(acc, cur, wr, wc, fr, fq, pre);
;         if (!has_next) break;
	s_add_i32 s48, s73, s52
	v_lshl_add_u64 v[218:219], v[218:219], 0, s[20:21]
	s_mov_b32 m0, s48
	ds_read_b128 v[186:189], v167 offset:49152
	ds_read_b128 v[190:193], v167 offset:50176
	ds_read_b128 v[194:197], v167 offset:51200
	ds_read_b128 v[198:201], v167 offset:52224
	ds_read_b128 v[202:205], v167 offset:53248
	ds_read_b128 v[206:209], v167 offset:54272
	ds_read_b128 v[210:213], v167 offset:55296
	ds_read_b128 v[214:217], v167 offset:56320
	global_load_lds_dwordx4 v[218:219], off
	s_add_i32 m0, s48, 0x2000
	s_add_u32 s46, s46, 0x20080
	v_lshl_add_u64 v[218:219], v[220:221], 0, s[20:21]
	s_addc_u32 s47, s47, 0
	s_add_i32 s48, s74, s52
	global_load_lds_dwordx4 v[218:219], off
	v_lshl_add_u64 v[218:219], s[46:47], 0, v[132:133]
	s_mov_b32 m0, s48
	s_nop 0
	global_load_lds_dwordx4 v[218:219], off
	v_lshl_add_u64 v[218:219], s[46:47], 0, v[136:137]
	s_add_i32 m0, s48, 0x2000
	s_nop 0
	global_load_lds_dwordx4 v[218:219], off
	v_lshl_add_u64 v[218:219], v[222:223], 0, s[20:21]
	s_mov_b32 m0, s61
	s_nop 0
	global_load_lds_dwordx4 v[218:219], off
	v_lshl_add_u64 v[218:219], v[224:225], 0, s[20:21]
	s_mov_b32 m0, s62
	s_nop 0
	global_load_lds_dwordx4 v[218:219], off
	s_waitcnt vmcnt(8)
	s_waitcnt lgkmcnt(0)
	s_nop 0
	s_barrier
	s_setprio 1
	v_mfma_f32_16x16x32_bf16 v[62:65], v[146:149], v[186:189], v[62:65]
	v_mfma_f32_16x16x32_bf16 v[58:61], v[154:157], v[186:189], v[58:61]
	v_mfma_f32_16x16x32_bf16 v[54:57], v[146:149], v[194:197], v[54:57]
	v_mfma_f32_16x16x32_bf16 v[50:53], v[154:157], v[194:197], v[50:53]
	v_mfma_f32_16x16x32_bf16 v[46:49], v[146:149], v[202:205], v[46:49]
	v_mfma_f32_16x16x32_bf16 v[42:45], v[154:157], v[202:205], v[42:45]
	v_mfma_f32_16x16x32_bf16 v[38:41], v[146:149], v[210:213], v[38:41]
	v_mfma_f32_16x16x32_bf16 v[34:37], v[154:157], v[210:213], v[34:37]
	v_mfma_f32_16x16x32_bf16 v[62:65], v[150:153], v[190:193], v[62:65]
	v_mfma_f32_16x16x32_bf16 v[58:61], v[158:161], v[190:193], v[58:61]
	v_mfma_f32_16x16x32_bf16 v[54:57], v[150:153], v[198:201], v[54:57]
	v_mfma_f32_16x16x32_bf16 v[50:53], v[158:161], v[198:201], v[50:53]
	v_mfma_f32_16x16x32_bf16 v[46:49], v[150:153], v[206:209], v[46:49]
	v_mfma_f32_16x16x32_bf16 v[42:45], v[158:161], v[206:209], v[42:45]
	v_mfma_f32_16x16x32_bf16 v[38:41], v[150:153], v[214:217], v[38:41]
	v_mfma_f32_16x16x32_bf16 v[34:37], v[158:161], v[214:217], v[34:37]
	v_mfma_f32_16x16x32_bf16 v[30:33], v[168:171], v[186:189], v[30:33]
	v_mfma_f32_16x16x32_bf16 v[26:29], v[176:179], v[186:189], v[26:29]
	v_mfma_f32_16x16x32_bf16 v[22:25], v[168:171], v[194:197], v[22:25]
	v_mfma_f32_16x16x32_bf16 v[18:21], v[176:179], v[194:197], v[18:21]
	v_mfma_f32_16x16x32_bf16 v[14:17], v[168:171], v[202:205], v[14:17]
	v_mfma_f32_16x16x32_bf16 v[10:13], v[176:179], v[202:205], v[10:13]
	v_mfma_f32_16x16x32_bf16 v[6:9], v[168:171], v[210:213], v[6:9]
	v_mfma_f32_16x16x32_bf16 v[2:5], v[176:179], v[210:213], v[2:5]
	v_mfma_f32_16x16x32_bf16 v[30:33], v[172:175], v[190:193], v[30:33]
	v_mfma_f32_16x16x32_bf16 v[26:29], v[180:183], v[190:193], v[26:29]
	v_mfma_f32_16x16x32_bf16 v[22:25], v[172:175], v[198:201], v[22:25]
	v_mfma_f32_16x16x32_bf16 v[18:21], v[180:183], v[198:201], v[18:21]
	v_mfma_f32_16x16x32_bf16 v[14:17], v[172:175], v[206:209], v[14:17]
	v_mfma_f32_16x16x32_bf16 v[10:13], v[180:183], v[206:209], v[10:13]
	v_mfma_f32_16x16x32_bf16 v[6:9], v[172:175], v[214:217], v[6:9]
	v_mfma_f32_16x16x32_bf16 v[2:5], v[180:183], v[214:217], v[2:5]
	s_setprio 0
	s_barrier
	s_add_i32 s72, s72, 2
	s_add_u32 s44, s44, 0x100
	s_addc_u32 s45, s45, 0
	s_add_u32 s70, s70, 0x100
	s_addc_u32 s71, s71, 0
	s_cmp_gt_u32 s72, 5
	s_cbranch_scc0 .LBB0_972
	s_mov_b32 s99, 1
	s_and_b64 vcc, exec, s[34:35]
	s_cbranch_vccz .LBB0_975
	s_barrier

;     DI bool next(int i, Unit& u) const { if (i > 0 || c >= 64) return false; u.pm = c & 31; u.pn = 0; u.src = c >> 5; return true; }
; #define PG8_STAGE(bufoff, gbase, voff) do { _Pragma("unroll") for (int _i = 0; _i < 2; ++_i) \
;         __builtin_amdgcn_global_load_lds((const unsigned*)((const char*)(gbase) + (voff)[_i]), (LAS unsigned*)(lds + (bufoff) + ldsw + _i * 8192), 16, 0, 0); } while (0)
; #define PG8_LDA(dst, b, h) do { _Pragma("unroll") for (int m = 0; m < 4; ++m) _Pragma("unroll") for (int k = 0; k < 2; ++k) dst[m][k] = *(const LAS bf16x8*)(lds + PG8_SA(b, h) + aoff + m * 2048 + k * 1024); } while (0)
; #define PG8_LDB(dst, b, h) do { _Pragma("unroll") for (int n = 0; n < 2; ++n) _Pragma("unroll") for (int k = 0; k < 2; ++k) dst[n][k] = *(const LAS bf16x8*)(lds + PG8_SB(b, h) + boff + n * 2048 + k * 1024); } while (0)
; #define PG8_WAIT_V(n) asm volatile("s_waitcnt vmcnt(" #n ")" ::: "memory")
; #define PG8_WAIT_L(n) asm volatile("s_waitcnt lgkmcnt(" #n ")" ::: "memory")
; #define PG8_BAR __builtin_amdgcn_s_barrier()
; template <class Epi, class Sched>
; DI void gemm_phase(LAS unsigned char* lds, const Gemm g, const Sched& S, const Epi& E) {
;     ...
;     for (;;) {
;         const bool has_next = S.next(ui + 1, nxt);
;         E.pre(pre, cur, wr, fr);
;         const char* nA = has_next ? (const char*)(nxt.src ? g.A1 : g.A0) + (size_t)nxt.pm * tstepA : cA; const char* nB = has_next ? (const char*)(nxt.src ? g.B1 : g.B0) + (size_t)nxt.pn * tstepB : cB;
;         for (int t = 0; t < nt; t += 2) {
;             const bool last = (t == nt - 2);
;             const char* a1 = cA + (size_t)(t + 1) * kstep;
;             const char* a2 = last ? nA : cA + (size_t)(t + 2) * kstep; const char* b2 = last ? nB : cB + (size_t)(t + 2) * kstep;
;             const char* a3 = a2 + kstep; const char* b3 = b2 + kstep;
;             PG8_LDB(B0, 0, 0); PG8_LDB(B1, 0, 1); PG8_SCHED; PG8_LDA(At, 0, 0); PG8_STAGE(PG8_SA(1, 1), a1 + hstepA, voffA);
;             PG8_WAIT_V(8); PG8_WAIT_L(0); PG8_BAR; PG8_MMA(0, 0, At, B0); PG8_MMA(0, 1, At, B1); PG8_BAR; PG8_SCHED;
;             PG8_LDA(At, 0, 1); PG8_STAGE(PG8_SB(0, 0), b2, voffB); PG8_STAGE(PG8_SB(0, 1), b2 + hstepB, voffB); PG8_STAGE(PG8_SA(0, 0), a2, voffA);
;             PG8_WAIT_V(8); PG8_WAIT_L(0); PG8_BAR; PG8_MMA(1, 0, At, B0); PG8_MMA(1, 1, At, B1); PG8_BAR; PG8_SCHED;
.Lpk4_w1:
	s_waitcnt lgkmcnt(0)
	s_nop 0
	s_barrier
	s_setprio 1
	v_mfma_f32_16x16x32_bf16 v[126:129], v[146:149], v[186:189], 0
	v_mfma_f32_16x16x32_bf16 v[122:125], v[160:163], v[186:189], 0
	v_mfma_f32_16x16x32_bf16 v[110:113], v[146:149], v[194:197], 0
	v_mfma_f32_16x16x32_bf16 v[106:109], v[160:163], v[194:197], 0
	v_mfma_f32_16x16x32_bf16 v[94:97], v[146:149], v[202:205], 0
	v_mfma_f32_16x16x32_bf16 v[90:93], v[160:163], v[202:205], 0
	v_mfma_f32_16x16x32_bf16 v[78:81], v[146:149], v[210:213], 0
	v_mfma_f32_16x16x32_bf16 v[74:77], v[160:163], v[210:213], 0
	v_mfma_f32_16x16x32_bf16 v[126:129], v[156:159], v[190:193], v[126:129]
	v_mfma_f32_16x16x32_bf16 v[122:125], v[164:167], v[190:193], v[122:125]
	v_mfma_f32_16x16x32_bf16 v[110:113], v[156:159], v[198:201], v[110:113]
	v_mfma_f32_16x16x32_bf16 v[106:109], v[164:167], v[198:201], v[106:109]
	v_mfma_f32_16x16x32_bf16 v[94:97], v[156:159], v[206:209], v[94:97]
	v_mfma_f32_16x16x32_bf16 v[90:93], v[164:167], v[206:209], v[90:93]
	v_mfma_f32_16x16x32_bf16 v[78:81], v[156:159], v[214:217], v[78:81]
	v_mfma_f32_16x16x32_bf16 v[74:77], v[164:167], v[214:217], v[74:77]
	v_mfma_f32_16x16x32_bf16 v[118:121], v[168:171], v[186:189], 0
	v_mfma_f32_16x16x32_bf16 v[114:117], v[176:179], v[186:189], 0
	v_mfma_f32_16x16x32_bf16 v[102:105], v[168:171], v[194:197], 0
	v_mfma_f32_16x16x32_bf16 v[98:101], v[176:179], v[194:197], 0
	v_mfma_f32_16x16x32_bf16 v[86:89], v[168:171], v[202:205], 0
	v_mfma_f32_16x16x32_bf16 v[82:85], v[176:179], v[202:205], 0
	v_mfma_f32_16x16x32_bf16 v[70:73], v[168:171], v[210:213], 0
	v_mfma_f32_16x16x32_bf16 v[66:69], v[176:179], v[210:213], 0
	v_mfma_f32_16x16x32_bf16 v[118:121], v[172:175], v[190:193], v[118:121]
	v_mfma_f32_16x16x32_bf16 v[114:117], v[180:183], v[190:193], v[114:117]
	v_mfma_f32_16x16x32_bf16 v[102:105], v[172:175], v[198:201], v[102:105]
	v_mfma_f32_16x16x32_bf16 v[98:101], v[180:183], v[198:201], v[98:101]
	v_mfma_f32_16x16x32_bf16 v[86:89], v[172:175], v[206:209], v[86:89]
	v_mfma_f32_16x16x32_bf16 v[82:85], v[180:183], v[206:209], v[82:85]
	v_mfma_f32_16x16x32_bf16 v[70:73], v[172:175], v[214:217], v[70:73]
	v_mfma_f32_16x16x32_bf16 v[66:69], v[180:183], v[214:217], v[66:69]
	s_setprio 0
	s_barrier
	s_add_i32 s67, s61, s52
	v_lshl_add_u64 v[218:219], s[46:47], 0, v[132:133]
	s_mov_b32 m0, s67
	ds_read_b128 v[186:189], v154 offset:16384
	ds_read_b128 v[190:193], v154 offset:17408
	ds_read_b128 v[194:197], v154 offset:18432
	ds_read_b128 v[198:201], v154 offset:19456
	ds_read_b128 v[202:205], v154 offset:20480
	ds_read_b128 v[206:209], v154 offset:21504
	ds_read_b128 v[210:213], v154 offset:22528
	ds_read_b128 v[214:217], v154 offset:23552
	global_load_lds_dwordx4 v[218:219], off
	s_add_i32 m0, s67, 0x2000
	s_add_u32 s68, s46, 0x40000
	v_lshl_add_u64 v[220:221], s[46:47], 0, v[136:137]
	s_addc_u32 s69, s47, 0
	s_add_i32 s67, s62, s52
	global_load_lds_dwordx4 v[220:221], off
	v_lshl_add_u64 v[222:223], s[68:69], 0, v[132:133]
	s_mov_b32 m0, s67
	v_lshl_add_u64 v[224:225], s[48:49], 0, v[134:135]
	global_load_lds_dwordx4 v[222:223], off
	v_lshl_add_u64 v[222:223], s[68:69], 0, v[136:137]
	s_add_i32 m0, s67, 0x2000
	s_nop 0
	global_load_lds_dwordx4 v[222:223], off
	v_lshl_add_u64 v[222:223], s[48:49], 0, v[130:131]
	s_mov_b32 m0, s43
	s_nop 0
	global_load_lds_dwordx4 v[222:223], off
	s_mov_b32 m0, s53
	s_nop 0
	global_load_lds_dwordx4 v[224:225], off
	s_cmp_lg_u32 s99, 0
	s_cbranch_scc1 .Lpk4_w2
	s_waitcnt vmcnt(8)
.Lpk4_w2:
	s_mov_b32 s99, 0
	s_waitcnt lgkmcnt(0)
	s_nop 0
	s_barrier
	s_setprio 1
	v_mfma_f32_16x16x32_bf16 v[62:65], v[146:149], v[186:189], 0
	v_mfma_f32_16x16x32_bf16 v[58:61], v[160:163], v[186:189], 0
	v_mfma_f32_16x16x32_bf16 v[46:49], v[146:149], v[194:197], 0
	v_mfma_f32_16x16x32_bf16 v[42:45], v[160:163], v[194:197], 0
	v_mfma_f32_16x16x32_bf16 v[30:33], v[146:149], v[202:205], 0
	v_mfma_f32_16x16x32_bf16 v[26:29], v[160:163], v[202:205], 0
	v_mfma_f32_16x16x32_bf16 v[14:17], v[146:149], v[210:213], 0
	v_mfma_f32_16x16x32_bf16 v[10:13], v[160:163], v[210:213], 0
	v_mfma_f32_16x16x32_bf16 v[62:65], v[156:159], v[190:193], v[62:65]
	v_mfma_f32_16x16x32_bf16 v[58:61], v[164:167], v[190:193], v[58:61]
	v_mfma_f32_16x16x32_bf16 v[46:49], v[156:159], v[198:201], v[46:49]
	v_mfma_f32_16x16x32_bf16 v[42:45], v[164:167], v[198:201], v[42:45]
	v_mfma_f32_16x16x32_bf16 v[30:33], v[156:159], v[206:209], v[30:33]
	v_mfma_f32_16x16x32_bf16 v[26:29], v[164:167], v[206:209], v[26:29]
	v_mfma_f32_16x16x32_bf16 v[14:17], v[156:159], v[214:217], v[14:17]
	v_mfma_f32_16x16x32_bf16 v[10:13], v[164:167], v[214:217], v[10:13]
	v_mfma_f32_16x16x32_bf16 v[54:57], v[168:171], v[186:189], 0
	v_mfma_f32_16x16x32_bf16 v[50:53], v[176:179], v[186:189], 0
	v_mfma_f32_16x16x32_bf16 v[38:41], v[168:171], v[194:197], 0
	v_mfma_f32_16x16x32_bf16 v[34:37], v[176:179], v[194:197], 0
	v_mfma_f32_16x16x32_bf16 v[22:25], v[168:171], v[202:205], 0
	v_mfma_f32_16x16x32_bf16 v[18:21], v[176:179], v[202:205], 0
	v_mfma_f32_16x16x32_bf16 v[6:9], v[168:171], v[210:213], 0
	v_mfma_f32_16x16x32_bf16 v[2:5], v[176:179], v[210:213], 0
	v_mfma_f32_16x16x32_bf16 v[54:57], v[172:175], v[190:193], v[54:57]
	v_mfma_f32_16x16x32_bf16 v[50:53], v[180:183], v[190:193], v[50:53]
	v_mfma_f32_16x16x32_bf16 v[38:41], v[172:175], v[198:201], v[38:41]
	v_mfma_f32_16x16x32_bf16 v[34:37], v[180:183], v[198:201], v[34:37]
	v_mfma_f32_16x16x32_bf16 v[22:25], v[172:175], v[206:209], v[22:25]
	v_mfma_f32_16x16x32_bf16 v[18:21], v[180:183], v[206:209], v[18:21]
	v_mfma_f32_16x16x32_bf16 v[6:9], v[172:175], v[214:217], v[6:9]
	v_mfma_f32_16x16x32_bf16 v[2:5], v[180:183], v[214:217], v[2:5]
	s_setprio 0
	s_barrier
; #define PG8_STAGE(bufoff, gbase, voff) do { _Pragma("unroll") for (int _i = 0; _i < 2; ++_i) \
;         __builtin_amdgcn_global_load_lds((const unsigned*)((const char*)(gbase) + (voff)[_i]), (LAS unsigned*)(lds + (bufoff) + ldsw + _i * 8192), 16, 0, 0); } while (0)
; #define PG8_LDA(dst, b, h) do { _Pragma("unroll") for (int m = 0; m < 4; ++m) _Pragma("unroll") for (int k = 0; k < 2; ++k) dst[m][k] = *(const LAS bf16x8*)(lds + PG8_SA(b, h) + aoff + m * 2048 + k * 1024); } while (0)
; #define PG8_LDB(dst, b, h) do { _Pragma("unroll") for (int n = 0; n < 2; ++n) _Pragma("unroll") for (int k = 0; k < 2; ++k) dst[n][k] = *(const LAS bf16x8*)(lds + PG8_SB(b, h) + boff + n * 2048 + k * 1024); } while (0)
; #define PG8_MMA(ai, bj, At, Bt) do { __builtin_amdgcn_s_setprio(1); _Pragma("unroll") for (int m = 0; m < 4; ++m) _Pragma("unroll") for (int n = 0; n < 2; ++n) _Pragma("unroll") for (int k = 0; k < 2; ++k) \
;         acc[ai][bj][m][n] = __builtin_amdgcn_mfma_f32_16x16x32_bf16(Bt[n][k], At[m][k], acc[ai][bj][m][n], 0, 0, 0); __builtin_amdgcn_s_setprio(0); } while (0)
; #define PG8_WAIT_V(n) asm volatile("s_waitcnt vmcnt(" #n ")" ::: "memory")
; #define PG8_WAIT_L(n) asm volatile("s_waitcnt lgkmcnt(" #n ")" ::: "memory")
; #define PG8_BAR __builtin_amdgcn_s_barrier()
; #define PG8_SCHED __builtin_amdgcn_sched_barrier(0)
; template <class Epi, class Sched>
; DI void gemm_phase(LAS unsigned char* lds, const Gemm g, const Sched& S, const Epi& E) {
;     ...
;             PG8_LDB(B0, 1, 0); PG8_LDB(B1, 1, 1); PG8_SCHED; PG8_LDA(At, 1, 0); PG8_STAGE(PG8_SA(0, 1), a2 + hstepA, voffA);
;             PG8_WAIT_V(8); PG8_WAIT_L(0); PG8_BAR; PG8_MMA(0, 0, At, B0); PG8_MMA(0, 1, At, B1); PG8_BAR; PG8_SCHED;
;             PG8_LDA(At, 1, 1); PG8_STAGE(PG8_SB(1, 0), b3, voffB); PG8_STAGE(PG8_SB(1, 1), b3 + hstepB, voffB); PG8_STAGE(PG8_SA(1, 0), a3, voffA);
;             PG8_WAIT_V(8); PG8_WAIT_L(0); PG8_BAR; PG8_MMA(1, 0, At, B0); PG8_MMA(1, 1, At, B1); PG8_BAR; PG8_SCHED;
	s_add_i32 s67, 0, 0x18000
	s_add_i32 s68, 0, 0x1c000
	v_add_u32_e32 v164, s67, v150
	v_add_u32_e32 v180, s68, v150
	ds_read_b128 v[146:149], v164
	ds_read_b128 v[156:159], v164 offset:1024
	ds_read_b128 v[160:163], v164 offset:2048
	ds_read_b128 v[164:167], v164 offset:3072
	ds_read_b128 v[168:171], v180
	ds_read_b128 v[172:175], v180 offset:1024
	ds_read_b128 v[176:179], v180 offset:2048
	ds_read_b128 v[180:183], v180 offset:3072
	s_add_u32 s48, s48, 0x40000
	s_addc_u32 s49, s49, 0
	s_mov_b32 m0, s54
	v_lshl_add_u64 v[226:227], s[48:49], 0, v[130:131]
	ds_read_b128 v[186:189], v154 offset:32768
	ds_read_b128 v[190:193], v154 offset:33792
	ds_read_b128 v[194:197], v154 offset:34816
	ds_read_b128 v[198:201], v154 offset:35840
	ds_read_b128 v[202:205], v154 offset:36864
	ds_read_b128 v[206:209], v154 offset:37888
	ds_read_b128 v[210:213], v154 offset:38912
	ds_read_b128 v[214:217], v154 offset:39936
	global_load_lds_dwordx4 v[226:227], off
	v_lshl_add_u64 v[226:227], s[48:49], 0, v[134:135]
	s_mov_b32 m0, s55
	s_nop 0
	global_load_lds_dwordx4 v[226:227], off
	s_waitcnt vmcnt(8)
	s_waitcnt lgkmcnt(0)
	s_barrier
	s_setprio 1
	v_mfma_f32_16x16x32_bf16 v[126:129], v[146:149], v[186:189], v[126:129]
	v_mfma_f32_16x16x32_bf16 v[122:125], v[160:163], v[186:189], v[122:125]
	v_mfma_f32_16x16x32_bf16 v[110:113], v[146:149], v[194:197], v[110:113]
	v_mfma_f32_16x16x32_bf16 v[106:109], v[160:163], v[194:197], v[106:109]
	v_mfma_f32_16x16x32_bf16 v[94:97], v[146:149], v[202:205], v[94:97]
	v_mfma_f32_16x16x32_bf16 v[90:93], v[160:163], v[202:205], v[90:93]
	v_mfma_f32_16x16x32_bf16 v[78:81], v[146:149], v[210:213], v[78:81]
	v_mfma_f32_16x16x32_bf16 v[74:77], v[160:163], v[210:213], v[74:77]
	v_mfma_f32_16x16x32_bf16 v[126:129], v[156:159], v[190:193], v[126:129]
	v_mfma_f32_16x16x32_bf16 v[122:125], v[164:167], v[190:193], v[122:125]
	v_mfma_f32_16x16x32_bf16 v[110:113], v[156:159], v[198:201], v[110:113]
	v_mfma_f32_16x16x32_bf16 v[106:109], v[164:167], v[198:201], v[106:109]
	v_mfma_f32_16x16x32_bf16 v[94:97], v[156:159], v[206:209], v[94:97]
	v_mfma_f32_16x16x32_bf16 v[90:93], v[164:167], v[206:209], v[90:93]
	v_mfma_f32_16x16x32_bf16 v[78:81], v[156:159], v[214:217], v[78:81]
	v_mfma_f32_16x16x32_bf16 v[74:77], v[164:167], v[214:217], v[74:77]
	v_mfma_f32_16x16x32_bf16 v[118:121], v[168:171], v[186:189], v[118:121]
	v_mfma_f32_16x16x32_bf16 v[114:117], v[176:179], v[186:189], v[114:117]
	v_mfma_f32_16x16x32_bf16 v[102:105], v[168:171], v[194:197], v[102:105]
	v_mfma_f32_16x16x32_bf16 v[98:101], v[176:179], v[194:197], v[98:101]
	v_mfma_f32_16x16x32_bf16 v[86:89], v[168:171], v[202:205], v[86:89]
	v_mfma_f32_16x16x32_bf16 v[82:85], v[176:179], v[202:205], v[82:85]
	v_mfma_f32_16x16x32_bf16 v[70:73], v[168:171], v[210:213], v[70:73]
	v_mfma_f32_16x16x32_bf16 v[66:69], v[176:179], v[210:213], v[66:69]
	v_mfma_f32_16x16x32_bf16 v[118:121], v[172:175], v[190:193], v[118:121]
	v_mfma_f32_16x16x32_bf16 v[114:117], v[180:183], v[190:193], v[114:117]
	v_mfma_f32_16x16x32_bf16 v[102:105], v[172:175], v[198:201], v[102:105]
	v_mfma_f32_16x16x32_bf16 v[98:101], v[180:183], v[198:201], v[98:101]
	v_mfma_f32_16x16x32_bf16 v[86:89], v[172:175], v[206:209], v[86:89]
	v_mfma_f32_16x16x32_bf16 v[82:85], v[180:183], v[206:209], v[82:85]
	v_mfma_f32_16x16x32_bf16 v[70:73], v[172:175], v[214:217], v[70:73]
	v_mfma_f32_16x16x32_bf16 v[66:69], v[180:183], v[214:217], v[66:69]
	s_setprio 0
	s_barrier
	s_add_i32 s48, s67, s52
	v_lshl_add_u64 v[218:219], v[218:219], 0, s[16:17]
	s_mov_b32 m0, s48
	ds_read_b128 v[186:189], v154 offset:49152
	ds_read_b128 v[190:193], v154 offset:50176
	ds_read_b128 v[194:197], v154 offset:51200
	ds_read_b128 v[198:201], v154 offset:52224
	ds_read_b128 v[202:205], v154 offset:53248
	ds_read_b128 v[206:209], v154 offset:54272
	ds_read_b128 v[210:213], v154 offset:55296
	ds_read_b128 v[214:217], v154 offset:56320
	global_load_lds_dwordx4 v[218:219], off
	s_add_i32 m0, s48, 0x2000
	s_add_u32 s46, s46, 0x40080
	v_lshl_add_u64 v[218:219], v[220:221], 0, s[16:17]
	s_addc_u32 s47, s47, 0
	s_add_i32 s48, s68, s52
	global_load_lds_dwordx4 v[218:219], off
	v_lshl_add_u64 v[218:219], s[46:47], 0, v[132:133]
	s_mov_b32 m0, s48
	s_nop 0
	global_load_lds_dwordx4 v[218:219], off
	v_lshl_add_u64 v[218:219], s[46:47], 0, v[136:137]
	s_add_i32 m0, s48, 0x2000
	s_nop 0
	global_load_lds_dwordx4 v[218:219], off
	v_lshl_add_u64 v[218:219], v[222:223], 0, s[16:17]
	s_mov_b32 m0, s57
	s_nop 0
	global_load_lds_dwordx4 v[218:219], off
	v_lshl_add_u64 v[218:219], v[224:225], 0, s[16:17]
	s_mov_b32 m0, s58
	s_nop 0
	global_load_lds_dwordx4 v[218:219], off
	s_waitcnt vmcnt(8)
	s_waitcnt lgkmcnt(0)
	s_nop 0
	s_barrier
	s_setprio 1
	v_mfma_f32_16x16x32_bf16 v[62:65], v[146:149], v[186:189], v[62:65]
	v_mfma_f32_16x16x32_bf16 v[58:61], v[160:163], v[186:189], v[58:61]
	v_mfma_f32_16x16x32_bf16 v[46:49], v[146:149], v[194:197], v[46:49]
	v_mfma_f32_16x16x32_bf16 v[42:45], v[160:163], v[194:197], v[42:45]
	v_mfma_f32_16x16x32_bf16 v[30:33], v[146:149], v[202:205], v[30:33]
	v_mfma_f32_16x16x32_bf16 v[26:29], v[160:163], v[202:205], v[26:29]
	v_mfma_f32_16x16x32_bf16 v[14:17], v[146:149], v[210:213], v[14:17]
	v_mfma_f32_16x16x32_bf16 v[10:13], v[160:163], v[210:213], v[10:13]
	v_mfma_f32_16x16x32_bf16 v[62:65], v[156:159], v[190:193], v[62:65]
	v_mfma_f32_16x16x32_bf16 v[58:61], v[164:167], v[190:193], v[58:61]
	v_mfma_f32_16x16x32_bf16 v[46:49], v[156:159], v[198:201], v[46:49]
	v_mfma_f32_16x16x32_bf16 v[42:45], v[164:167], v[198:201], v[42:45]
	v_mfma_f32_16x16x32_bf16 v[30:33], v[156:159], v[206:209], v[30:33]
	v_mfma_f32_16x16x32_bf16 v[26:29], v[164:167], v[206:209], v[26:29]
	v_mfma_f32_16x16x32_bf16 v[14:17], v[156:159], v[214:217], v[14:17]
	v_mfma_f32_16x16x32_bf16 v[10:13], v[164:167], v[214:217], v[10:13]
	v_mfma_f32_16x16x32_bf16 v[54:57], v[168:171], v[186:189], v[54:57]
	v_mfma_f32_16x16x32_bf16 v[50:53], v[176:179], v[186:189], v[50:53]
	v_mfma_f32_16x16x32_bf16 v[38:41], v[168:171], v[194:197], v[38:41]
	v_mfma_f32_16x16x32_bf16 v[34:37], v[176:179], v[194:197], v[34:37]
	v_mfma_f32_16x16x32_bf16 v[22:25], v[168:171], v[202:205], v[22:25]
	v_mfma_f32_16x16x32_bf16 v[18:21], v[176:179], v[202:205], v[18:21]
	v_mfma_f32_16x16x32_bf16 v[6:9], v[168:171], v[210:213], v[6:9]
	v_mfma_f32_16x16x32_bf16 v[2:5], v[176:179], v[210:213], v[2:5]
	v_mfma_f32_16x16x32_bf16 v[54:57], v[172:175], v[190:193], v[54:57]
	v_mfma_f32_16x16x32_bf16 v[50:53], v[180:183], v[190:193], v[50:53]
	v_mfma_f32_16x16x32_bf16 v[38:41], v[172:175], v[198:201], v[38:41]
	v_mfma_f32_16x16x32_bf16 v[34:37], v[180:183], v[198:201], v[34:37]
	v_mfma_f32_16x16x32_bf16 v[22:25], v[172:175], v[206:209], v[22:25]
	v_mfma_f32_16x16x32_bf16 v[18:21], v[180:183], v[206:209], v[18:21]
	v_mfma_f32_16x16x32_bf16 v[6:9], v[172:175], v[214:217], v[6:9]
	v_mfma_f32_16x16x32_bf16 v[2:5], v[180:183], v[214:217], v[2:5]
	s_setprio 0
	s_barrier
	s_add_i32 s66, s66, 2
	s_add_u32 s44, s44, 0x100
	s_addc_u32 s45, s45, 0
	s_add_u32 s64, s64, 0x100
	s_addc_u32 s65, s65, 0
	s_cmp_gt_u32 s66, 13
; #define PG8_STAGE(bufoff, gbase, voff) do { _Pragma("unroll") for (int _i = 0; _i < 2; ++_i) \
;         __builtin_amdgcn_global_load_lds((const unsigned*)((const char*)(gbase) + (voff)[_i]), (LAS unsigned*)(lds + (bufoff) + ldsw + _i * 8192), 16, 0, 0); } while (0)
; #define PG8_LDA(dst, b, h) do { _Pragma("unroll") for (int m = 0; m < 4; ++m) _Pragma("unroll") for (int k = 0; k < 2; ++k) dst[m][k] = *(const LAS bf16x8*)(lds + PG8_SA(b, h) + aoff + m * 2048 + k * 1024); } while (0)
; #define PG8_LDB(dst, b, h) do { _Pragma("unroll") for (int n = 0; n < 2; ++n) _Pragma("unroll") for (int k = 0; k < 2; ++k) dst[n][k] = *(const LAS bf16x8*)(lds + PG8_SB(b, h) + boff + n * 2048 + k * 1024); } while (0)
; #define PG8_MMA(ai, bj, At, Bt) do { __builtin_amdgcn_s_setprio(1); _Pragma("unroll") for (int m = 0; m < 4; ++m) _Pragma("unroll") for (int n = 0; n < 2; ++n) _Pragma("unroll") for (int k = 0; k < 2; ++k) \
;         acc[ai][bj][m][n] = __builtin_amdgcn_mfma_f32_16x16x32_bf16(Bt[n][k], At[m][k], acc[ai][bj][m][n], 0, 0, 0); __builtin_amdgcn_s_setprio(0); } while (0)
; #define PG8_WAIT_V(n) asm volatile("s_waitcnt vmcnt(" #n ")" ::: "memory")
; #define PG8_WAIT_L(n) asm volatile("s_waitcnt lgkmcnt(" #n ")" ::: "memory")
; #define PG8_BAR __builtin_amdgcn_s_barrier()
; #define PG8_SCHED __builtin_amdgcn_sched_barrier(0)
; template <class Epi, class Sched>
; DI void gemm_phase(LAS unsigned char* lds, const Gemm g, const Sched& S, const Epi& E) {
;     ...
;         for (int t = 0; t < nt; t += 2) {
;             const bool last = (t == nt - 2);
;             const char* a1 = cA + (size_t)(t + 1) * kstep;
;             const char* a2 = last ? nA : cA + (size_t)(t + 2) * kstep; const char* b2 = last ? nB : cB + (size_t)(t + 2) * kstep;
;             const char* a3 = a2 + kstep; const char* b3 = b2 + kstep;
;             PG8_LDB(B0, 0, 0); PG8_LDB(B1, 0, 1); PG8_SCHED; PG8_LDA(At, 0, 0); PG8_STAGE(PG8_SA(1, 1), a1 + hstepA, voffA);
;             PG8_WAIT_V(8); PG8_WAIT_L(0); PG8_BAR; PG8_MMA(0, 0, At, B0); PG8_MMA(0, 1, At, B1); PG8_BAR; PG8_SCHED;
;             PG8_LDA(At, 0, 1); PG8_STAGE(PG8_SB(0, 0), b2, voffB); PG8_STAGE(PG8_SB(0, 1), b2 + hstepB, voffB); PG8_STAGE(PG8_SA(0, 0), a2, voffA);
;             PG8_WAIT_V(8); PG8_WAIT_L(0); PG8_BAR; PG8_MMA(1, 0, At, B0); PG8_MMA(1, 1, At, B1); PG8_BAR; PG8_SCHED;
.LBB0_1133:
	ds_read_b128 v[146:149], v152
	ds_read_b128 v[156:159], v152 offset:1024
	ds_read_b128 v[160:163], v152 offset:2048
	ds_read_b128 v[164:167], v152 offset:3072
	ds_read_b128 v[168:171], v153
	ds_read_b128 v[172:175], v153 offset:1024
	ds_read_b128 v[176:179], v153 offset:2048
	ds_read_b128 v[180:183], v153 offset:3072
	s_add_u32 s46, s44, 0xfffc0080
	s_addc_u32 s47, s45, -1
	s_cmp_eq_u32 s66, 12
	s_cselect_b32 s49, s35, s47
	s_cselect_b32 s48, s41, s46
	s_cselect_b32 s47, s21, s65
	s_cselect_b32 s46, s63, s64
	v_lshl_add_u64 v[218:219], s[44:45], 0, v[138:139]
	s_add_i32 m0, s43, 0xc000
	ds_read_b128 v[186:189], v154
	ds_read_b128 v[190:193], v154 offset:1024
	ds_read_b128 v[194:197], v154 offset:2048
	ds_read_b128 v[198:201], v154 offset:3072
	ds_read_b128 v[202:205], v154 offset:4096
	ds_read_b128 v[206:209], v154 offset:5120
	ds_read_b128 v[210:213], v154 offset:6144
	ds_read_b128 v[214:217], v154 offset:7168
	global_load_lds_dwordx4 v[218:219], off
	v_lshl_add_u64 v[218:219], s[44:45], 0, v[140:141]
	s_add_i32 m0, s43, 0xe000
	s_nop 0
	global_load_lds_dwordx4 v[218:219], off
	s_waitcnt vmcnt(8)
	s_waitcnt lgkmcnt(0)
	s_nop 0
	s_barrier
	s_setprio 1
	v_mfma_f32_16x16x32_bf16 v[126:129], v[146:149], v[186:189], v[126:129]
	v_mfma_f32_16x16x32_bf16 v[122:125], v[160:163], v[186:189], v[122:125]
	v_mfma_f32_16x16x32_bf16 v[110:113], v[146:149], v[194:197], v[110:113]
	v_mfma_f32_16x16x32_bf16 v[106:109], v[160:163], v[194:197], v[106:109]
	v_mfma_f32_16x16x32_bf16 v[94:97], v[146:149], v[202:205], v[94:97]
	v_mfma_f32_16x16x32_bf16 v[90:93], v[160:163], v[202:205], v[90:93]
	v_mfma_f32_16x16x32_bf16 v[78:81], v[146:149], v[210:213], v[78:81]
	v_mfma_f32_16x16x32_bf16 v[74:77], v[160:163], v[210:213], v[74:77]
	v_mfma_f32_16x16x32_bf16 v[126:129], v[156:159], v[190:193], v[126:129]
	v_mfma_f32_16x16x32_bf16 v[122:125], v[164:167], v[190:193], v[122:125]
	v_mfma_f32_16x16x32_bf16 v[110:113], v[156:159], v[198:201], v[110:113]
	v_mfma_f32_16x16x32_bf16 v[106:109], v[164:167], v[198:201], v[106:109]
	v_mfma_f32_16x16x32_bf16 v[94:97], v[156:159], v[206:209], v[94:97]
	v_mfma_f32_16x16x32_bf16 v[90:93], v[164:167], v[206:209], v[90:93]
	v_mfma_f32_16x16x32_bf16 v[78:81], v[156:159], v[214:217], v[78:81]
	v_mfma_f32_16x16x32_bf16 v[74:77], v[164:167], v[214:217], v[74:77]
	v_mfma_f32_16x16x32_bf16 v[118:121], v[168:171], v[186:189], v[118:121]
	v_mfma_f32_16x16x32_bf16 v[114:117], v[176:179], v[186:189], v[114:117]
	v_mfma_f32_16x16x32_bf16 v[102:105], v[168:171], v[194:197], v[102:105]
	v_mfma_f32_16x16x32_bf16 v[98:101], v[176:179], v[194:197], v[98:101]
	v_mfma_f32_16x16x32_bf16 v[86:89], v[168:171], v[202:205], v[86:89]
	v_mfma_f32_16x16x32_bf16 v[82:85], v[176:179], v[202:205], v[82:85]
	v_mfma_f32_16x16x32_bf16 v[70:73], v[168:171], v[210:213], v[70:73]
	v_mfma_f32_16x16x32_bf16 v[66:69], v[176:179], v[210:213], v[66:69]
	v_mfma_f32_16x16x32_bf16 v[118:121], v[172:175], v[190:193], v[118:121]
	v_mfma_f32_16x16x32_bf16 v[114:117], v[180:183], v[190:193], v[114:117]
	v_mfma_f32_16x16x32_bf16 v[102:105], v[172:175], v[198:201], v[102:105]
	v_mfma_f32_16x16x32_bf16 v[98:101], v[180:183], v[198:201], v[98:101]
	v_mfma_f32_16x16x32_bf16 v[86:89], v[172:175], v[206:209], v[86:89]
	v_mfma_f32_16x16x32_bf16 v[82:85], v[180:183], v[206:209], v[82:85]
	v_mfma_f32_16x16x32_bf16 v[70:73], v[172:175], v[214:217], v[70:73]
	v_mfma_f32_16x16x32_bf16 v[66:69], v[180:183], v[214:217], v[66:69]
	s_setprio 0
	s_barrier
	s_add_i32 s67, s61, s52
	v_lshl_add_u64 v[218:219], s[46:47], 0, v[132:133]
	s_mov_b32 m0, s67
	ds_read_b128 v[186:189], v154 offset:16384
	ds_read_b128 v[190:193], v154 offset:17408
	ds_read_b128 v[194:197], v154 offset:18432
	ds_read_b128 v[198:201], v154 offset:19456
	ds_read_b128 v[202:205], v154 offset:20480
	ds_read_b128 v[206:209], v154 offset:21504
	ds_read_b128 v[210:213], v154 offset:22528
	ds_read_b128 v[214:217], v154 offset:23552
	global_load_lds_dwordx4 v[218:219], off
	s_add_i32 m0, s67, 0x2000
	s_add_u32 s68, s46, 0x40000
	v_lshl_add_u64 v[220:221], s[46:47], 0, v[136:137]
	s_addc_u32 s69, s47, 0
	s_add_i32 s67, s62, s52
	global_load_lds_dwordx4 v[220:221], off
	v_lshl_add_u64 v[222:223], s[68:69], 0, v[132:133]
	s_mov_b32 m0, s67
	v_lshl_add_u64 v[224:225], s[48:49], 0, v[134:135]
	global_load_lds_dwordx4 v[222:223], off
	v_lshl_add_u64 v[222:223], s[68:69], 0, v[136:137]
	s_add_i32 m0, s67, 0x2000
	s_nop 0
	global_load_lds_dwordx4 v[222:223], off
	v_lshl_add_u64 v[222:223], s[48:49], 0, v[130:131]
	s_mov_b32 m0, s43
	s_nop 0
	global_load_lds_dwordx4 v[222:223], off
	s_mov_b32 m0, s53
	s_nop 0
	global_load_lds_dwordx4 v[224:225], off
	s_waitcnt vmcnt(8)
	s_waitcnt lgkmcnt(0)
	s_barrier
; #define PG8_STAGE(bufoff, gbase, voff) do { _Pragma("unroll") for (int _i = 0; _i < 2; ++_i) \
;         __builtin_amdgcn_global_load_lds((const unsigned*)((const char*)(gbase) + (voff)[_i]), (LAS unsigned*)(lds + (bufoff) + ldsw + _i * 8192), 16, 0, 0); } while (0)
; #define PG8_LDA(dst, b, h) do { _Pragma("unroll") for (int m = 0; m < 4; ++m) _Pragma("unroll") for (int k = 0; k < 2; ++k) dst[m][k] = *(const LAS bf16x8*)(lds + PG8_SA(b, h) + aoff + m * 2048 + k * 1024); } while (0)
; #define PG8_LDB(dst, b, h) do { _Pragma("unroll") for (int n = 0; n < 2; ++n) _Pragma("unroll") for (int k = 0; k < 2; ++k) dst[n][k] = *(const LAS bf16x8*)(lds + PG8_SB(b, h) + boff + n * 2048 + k * 1024); } while (0)
; #define PG8_MMA(ai, bj, At, Bt) do { __builtin_amdgcn_s_setprio(1); _Pragma("unroll") for (int m = 0; m < 4; ++m) _Pragma("unroll") for (int n = 0; n < 2; ++n) _Pragma("unroll") for (int k = 0; k < 2; ++k) \
;         acc[ai][bj][m][n] = __builtin_amdgcn_mfma_f32_16x16x32_bf16(Bt[n][k], At[m][k], acc[ai][bj][m][n], 0, 0, 0); __builtin_amdgcn_s_setprio(0); } while (0)
; #define PG8_WAIT_V(n) asm volatile("s_waitcnt vmcnt(" #n ")" ::: "memory")
; #define PG8_WAIT_L(n) asm volatile("s_waitcnt lgkmcnt(" #n ")" ::: "memory")
; #define PG8_BAR __builtin_amdgcn_s_barrier()
; #define PG8_SCHED __builtin_amdgcn_sched_barrier(0)
; template <class Epi, class Sched>
; DI void gemm_phase(LAS unsigned char* lds, const Gemm g, const Sched& S, const Epi& E) {
;     ...
;             PG8_WAIT_V(8); PG8_WAIT_L(0); PG8_BAR; PG8_MMA(1, 0, At, B0); PG8_MMA(1, 1, At, B1); PG8_BAR; PG8_SCHED;
;             PG8_LDB(B0, 1, 0); PG8_LDB(B1, 1, 1); PG8_SCHED; PG8_LDA(At, 1, 0); PG8_STAGE(PG8_SA(0, 1), a2 + hstepA, voffA);
;             PG8_WAIT_V(8); PG8_WAIT_L(0); PG8_BAR; PG8_MMA(0, 0, At, B0); PG8_MMA(0, 1, At, B1); PG8_BAR; PG8_SCHED;
	s_setprio 1
	v_mfma_f32_16x16x32_bf16 v[62:65], v[146:149], v[186:189], v[62:65]
	v_mfma_f32_16x16x32_bf16 v[58:61], v[160:163], v[186:189], v[58:61]
	v_mfma_f32_16x16x32_bf16 v[46:49], v[146:149], v[194:197], v[46:49]
	v_mfma_f32_16x16x32_bf16 v[42:45], v[160:163], v[194:197], v[42:45]
	v_mfma_f32_16x16x32_bf16 v[30:33], v[146:149], v[202:205], v[30:33]
	v_mfma_f32_16x16x32_bf16 v[26:29], v[160:163], v[202:205], v[26:29]
	v_mfma_f32_16x16x32_bf16 v[14:17], v[146:149], v[210:213], v[14:17]
	v_mfma_f32_16x16x32_bf16 v[10:13], v[160:163], v[210:213], v[10:13]
	v_mfma_f32_16x16x32_bf16 v[62:65], v[156:159], v[190:193], v[62:65]
	v_mfma_f32_16x16x32_bf16 v[58:61], v[164:167], v[190:193], v[58:61]
	v_mfma_f32_16x16x32_bf16 v[46:49], v[156:159], v[198:201], v[46:49]
	v_mfma_f32_16x16x32_bf16 v[42:45], v[164:167], v[198:201], v[42:45]
	v_mfma_f32_16x16x32_bf16 v[30:33], v[156:159], v[206:209], v[30:33]
	v_mfma_f32_16x16x32_bf16 v[26:29], v[164:167], v[206:209], v[26:29]
	v_mfma_f32_16x16x32_bf16 v[14:17], v[156:159], v[214:217], v[14:17]
	v_mfma_f32_16x16x32_bf16 v[10:13], v[164:167], v[214:217], v[10:13]
	v_mfma_f32_16x16x32_bf16 v[54:57], v[168:171], v[186:189], v[54:57]
	v_mfma_f32_16x16x32_bf16 v[50:53], v[176:179], v[186:189], v[50:53]
	v_mfma_f32_16x16x32_bf16 v[38:41], v[168:171], v[194:197], v[38:41]
	v_mfma_f32_16x16x32_bf16 v[34:37], v[176:179], v[194:197], v[34:37]
	v_mfma_f32_16x16x32_bf16 v[22:25], v[168:171], v[202:205], v[22:25]
	v_mfma_f32_16x16x32_bf16 v[18:21], v[176:179], v[202:205], v[18:21]
	v_mfma_f32_16x16x32_bf16 v[6:9], v[168:171], v[210:213], v[6:9]
	v_mfma_f32_16x16x32_bf16 v[2:5], v[176:179], v[210:213], v[2:5]
	v_mfma_f32_16x16x32_bf16 v[54:57], v[172:175], v[190:193], v[54:57]
	v_mfma_f32_16x16x32_bf16 v[50:53], v[180:183], v[190:193], v[50:53]
	v_mfma_f32_16x16x32_bf16 v[38:41], v[172:175], v[198:201], v[38:41]
	v_mfma_f32_16x16x32_bf16 v[34:37], v[180:183], v[198:201], v[34:37]
	v_mfma_f32_16x16x32_bf16 v[22:25], v[172:175], v[206:209], v[22:25]
	v_mfma_f32_16x16x32_bf16 v[18:21], v[180:183], v[206:209], v[18:21]
	v_mfma_f32_16x16x32_bf16 v[6:9], v[172:175], v[214:217], v[6:9]
	v_mfma_f32_16x16x32_bf16 v[2:5], v[180:183], v[214:217], v[2:5]
	s_setprio 0
	s_barrier
	s_add_i32 s67, 0, 0x18000
	s_add_i32 s68, 0, 0x1c000
	v_add_u32_e32 v164, s67, v150
	v_add_u32_e32 v180, s68, v150
	ds_read_b128 v[146:149], v164
	ds_read_b128 v[156:159], v164 offset:1024
	ds_read_b128 v[160:163], v164 offset:2048
	ds_read_b128 v[164:167], v164 offset:3072
	ds_read_b128 v[168:171], v180
	ds_read_b128 v[172:175], v180 offset:1024
	ds_read_b128 v[176:179], v180 offset:2048
	ds_read_b128 v[180:183], v180 offset:3072
	s_add_u32 s48, s48, 0x40000
	s_addc_u32 s49, s49, 0
	s_mov_b32 m0, s54
	v_lshl_add_u64 v[226:227], s[48:49], 0, v[130:131]
	ds_read_b128 v[186:189], v154 offset:32768
	ds_read_b128 v[190:193], v154 offset:33792
	ds_read_b128 v[194:197], v154 offset:34816
	ds_read_b128 v[198:201], v154 offset:35840
	ds_read_b128 v[202:205], v154 offset:36864
	ds_read_b128 v[206:209], v154 offset:37888
	ds_read_b128 v[210:213], v154 offset:38912
	ds_read_b128 v[214:217], v154 offset:39936
	global_load_lds_dwordx4 v[226:227], off
	v_lshl_add_u64 v[226:227], s[48:49], 0, v[134:135]
	s_mov_b32 m0, s55
	s_nop 0
	global_load_lds_dwordx4 v[226:227], off
	s_waitcnt vmcnt(8)
	s_waitcnt lgkmcnt(0)
	s_barrier
	s_setprio 1
	v_mfma_f32_16x16x32_bf16 v[126:129], v[146:149], v[186:189], v[126:129]
	v_mfma_f32_16x16x32_bf16 v[122:125], v[160:163], v[186:189], v[122:125]
	v_mfma_f32_16x16x32_bf16 v[110:113], v[146:149], v[194:197], v[110:113]
	v_mfma_f32_16x16x32_bf16 v[106:109], v[160:163], v[194:197], v[106:109]
	v_mfma_f32_16x16x32_bf16 v[94:97], v[146:149], v[202:205], v[94:97]
	v_mfma_f32_16x16x32_bf16 v[90:93], v[160:163], v[202:205], v[90:93]
	v_mfma_f32_16x16x32_bf16 v[78:81], v[146:149], v[210:213], v[78:81]
	v_mfma_f32_16x16x32_bf16 v[74:77], v[160:163], v[210:213], v[74:77]
	v_mfma_f32_16x16x32_bf16 v[126:129], v[156:159], v[190:193], v[126:129]
	v_mfma_f32_16x16x32_bf16 v[122:125], v[164:167], v[190:193], v[122:125]
	v_mfma_f32_16x16x32_bf16 v[110:113], v[156:159], v[198:201], v[110:113]
	v_mfma_f32_16x16x32_bf16 v[106:109], v[164:167], v[198:201], v[106:109]
	v_mfma_f32_16x16x32_bf16 v[94:97], v[156:159], v[206:209], v[94:97]
	v_mfma_f32_16x16x32_bf16 v[90:93], v[164:167], v[206:209], v[90:93]
	v_mfma_f32_16x16x32_bf16 v[78:81], v[156:159], v[214:217], v[78:81]
	v_mfma_f32_16x16x32_bf16 v[74:77], v[164:167], v[214:217], v[74:77]
	v_mfma_f32_16x16x32_bf16 v[118:121], v[168:171], v[186:189], v[118:121]
	v_mfma_f32_16x16x32_bf16 v[114:117], v[176:179], v[186:189], v[114:117]
	v_mfma_f32_16x16x32_bf16 v[102:105], v[168:171], v[194:197], v[102:105]
	v_mfma_f32_16x16x32_bf16 v[98:101], v[176:179], v[194:197], v[98:101]
	v_mfma_f32_16x16x32_bf16 v[86:89], v[168:171], v[202:205], v[86:89]
	v_mfma_f32_16x16x32_bf16 v[82:85], v[176:179], v[202:205], v[82:85]
	v_mfma_f32_16x16x32_bf16 v[70:73], v[168:171], v[210:213], v[70:73]
	v_mfma_f32_16x16x32_bf16 v[66:69], v[176:179], v[210:213], v[66:69]
	v_mfma_f32_16x16x32_bf16 v[118:121], v[172:175], v[190:193], v[118:121]
	v_mfma_f32_16x16x32_bf16 v[114:117], v[180:183], v[190:193], v[114:117]
	v_mfma_f32_16x16x32_bf16 v[102:105], v[172:175], v[198:201], v[102:105]
	v_mfma_f32_16x16x32_bf16 v[98:101], v[180:183], v[198:201], v[98:101]
	v_mfma_f32_16x16x32_bf16 v[86:89], v[172:175], v[206:209], v[86:89]
	v_mfma_f32_16x16x32_bf16 v[82:85], v[180:183], v[206:209], v[82:85]
	v_mfma_f32_16x16x32_bf16 v[70:73], v[172:175], v[214:217], v[70:73]
	v_mfma_f32_16x16x32_bf16 v[66:69], v[180:183], v[214:217], v[66:69]
	s_setprio 0
	s_barrier
; #define PG8_STAGE(bufoff, gbase, voff) do { _Pragma("unroll") for (int _i = 0; _i < 2; ++_i) \
;         __builtin_amdgcn_global_load_lds((const unsigned*)((const char*)(gbase) + (voff)[_i]), (LAS unsigned*)(lds + (bufoff) + ldsw + _i * 8192), 16, 0, 0); } while (0)
; #define PG8_LDA(dst, b, h) do { _Pragma("unroll") for (int m = 0; m < 4; ++m) _Pragma("unroll") for (int k = 0; k < 2; ++k) dst[m][k] = *(const LAS bf16x8*)(lds + PG8_SA(b, h) + aoff + m * 2048 + k * 1024); } while (0)
; #define PG8_MMA(ai, bj, At, Bt) do { __builtin_amdgcn_s_setprio(1); _Pragma("unroll") for (int m = 0; m < 4; ++m) _Pragma("unroll") for (int n = 0; n < 2; ++n) _Pragma("unroll") for (int k = 0; k < 2; ++k) \
;         acc[ai][bj][m][n] = __builtin_amdgcn_mfma_f32_16x16x32_bf16(Bt[n][k], At[m][k], acc[ai][bj][m][n], 0, 0, 0); __builtin_amdgcn_s_setprio(0); } while (0)
; #define PG8_WAIT_V(n) asm volatile("s_waitcnt vmcnt(" #n ")" ::: "memory")
; #define PG8_WAIT_L(n) asm volatile("s_waitcnt lgkmcnt(" #n ")" ::: "memory")
; #define PG8_BAR __builtin_amdgcn_s_barrier()
; #define PG8_SCHED __builtin_amdgcn_sched_barrier(0)
;     DI void pre(Pre& pr, const pg8::Unit& u, int wr, int fr) const { load_rows(pr, ssq, u, wr, fr); }
;     DI void pre(Pre& pr, const pg8::Unit& u, int wr, int fr) const { load_rows(pr, ssq, u, wr, fr); }
; template <class Epi, class Sched>
; DI void gemm_phase(LAS unsigned char* lds, const Gemm g, const Sched& S, const Epi& E) {
;     ...
;             PG8_LDA(At, 1, 1); PG8_STAGE(PG8_SB(1, 0), b3, voffB); PG8_STAGE(PG8_SB(1, 1), b3 + hstepB, voffB); PG8_STAGE(PG8_SA(1, 0), a3, voffA);
;             PG8_WAIT_V(8); PG8_WAIT_L(0); PG8_BAR; PG8_MMA(1, 0, At, B0); PG8_MMA(1, 1, At, B1); PG8_BAR; PG8_SCHED;
;         }
;         if (wr == 0) PG8_BAR;
;         E(acc, cur, wr, wc, fr, fq, pre);
;         if (!has_next) break;
	s_add_i32 s48, s67, s52
	v_lshl_add_u64 v[218:219], v[218:219], 0, s[16:17]
	s_mov_b32 m0, s48
	ds_read_b128 v[186:189], v154 offset:49152
	ds_read_b128 v[190:193], v154 offset:50176
	ds_read_b128 v[194:197], v154 offset:51200
	ds_read_b128 v[198:201], v154 offset:52224
	ds_read_b128 v[202:205], v154 offset:53248
	ds_read_b128 v[206:209], v154 offset:54272
	ds_read_b128 v[210:213], v154 offset:55296
	ds_read_b128 v[214:217], v154 offset:56320
	global_load_lds_dwordx4 v[218:219], off
	s_add_i32 m0, s48, 0x2000
	s_add_u32 s46, s46, 0x40080
	v_lshl_add_u64 v[218:219], v[220:221], 0, s[16:17]
	s_addc_u32 s47, s47, 0
	s_add_i32 s48, s68, s52
	global_load_lds_dwordx4 v[218:219], off
	v_lshl_add_u64 v[218:219], s[46:47], 0, v[132:133]
	s_mov_b32 m0, s48
	s_nop 0
	global_load_lds_dwordx4 v[218:219], off
	v_lshl_add_u64 v[218:219], s[46:47], 0, v[136:137]
	s_add_i32 m0, s48, 0x2000
	s_nop 0
	global_load_lds_dwordx4 v[218:219], off
	v_lshl_add_u64 v[218:219], v[222:223], 0, s[16:17]
	s_mov_b32 m0, s57
	s_nop 0
	global_load_lds_dwordx4 v[218:219], off
	v_lshl_add_u64 v[218:219], v[224:225], 0, s[16:17]
	s_mov_b32 m0, s58
	s_nop 0
	global_load_lds_dwordx4 v[218:219], off
	s_waitcnt vmcnt(8)
	s_waitcnt lgkmcnt(0)
	s_nop 0
	s_barrier
	s_setprio 1
	v_mfma_f32_16x16x32_bf16 v[62:65], v[146:149], v[186:189], v[62:65]
	v_mfma_f32_16x16x32_bf16 v[58:61], v[160:163], v[186:189], v[58:61]
	v_mfma_f32_16x16x32_bf16 v[46:49], v[146:149], v[194:197], v[46:49]
	v_mfma_f32_16x16x32_bf16 v[42:45], v[160:163], v[194:197], v[42:45]
	v_mfma_f32_16x16x32_bf16 v[30:33], v[146:149], v[202:205], v[30:33]
	v_mfma_f32_16x16x32_bf16 v[26:29], v[160:163], v[202:205], v[26:29]
	v_mfma_f32_16x16x32_bf16 v[14:17], v[146:149], v[210:213], v[14:17]
	v_mfma_f32_16x16x32_bf16 v[10:13], v[160:163], v[210:213], v[10:13]
	v_mfma_f32_16x16x32_bf16 v[62:65], v[156:159], v[190:193], v[62:65]
	v_mfma_f32_16x16x32_bf16 v[58:61], v[164:167], v[190:193], v[58:61]
	v_mfma_f32_16x16x32_bf16 v[46:49], v[156:159], v[198:201], v[46:49]
	v_mfma_f32_16x16x32_bf16 v[42:45], v[164:167], v[198:201], v[42:45]
	v_mfma_f32_16x16x32_bf16 v[30:33], v[156:159], v[206:209], v[30:33]
	v_mfma_f32_16x16x32_bf16 v[26:29], v[164:167], v[206:209], v[26:29]
	v_mfma_f32_16x16x32_bf16 v[14:17], v[156:159], v[214:217], v[14:17]
	v_mfma_f32_16x16x32_bf16 v[10:13], v[164:167], v[214:217], v[10:13]
	v_mfma_f32_16x16x32_bf16 v[54:57], v[168:171], v[186:189], v[54:57]
	v_mfma_f32_16x16x32_bf16 v[50:53], v[176:179], v[186:189], v[50:53]
	v_mfma_f32_16x16x32_bf16 v[38:41], v[168:171], v[194:197], v[38:41]
	v_mfma_f32_16x16x32_bf16 v[34:37], v[176:179], v[194:197], v[34:37]
	v_mfma_f32_16x16x32_bf16 v[22:25], v[168:171], v[202:205], v[22:25]
	v_mfma_f32_16x16x32_bf16 v[18:21], v[176:179], v[202:205], v[18:21]
	v_mfma_f32_16x16x32_bf16 v[6:9], v[168:171], v[210:213], v[6:9]
	v_mfma_f32_16x16x32_bf16 v[2:5], v[176:179], v[210:213], v[2:5]
	v_mfma_f32_16x16x32_bf16 v[54:57], v[172:175], v[190:193], v[54:57]
	v_mfma_f32_16x16x32_bf16 v[50:53], v[180:183], v[190:193], v[50:53]
	v_mfma_f32_16x16x32_bf16 v[38:41], v[172:175], v[198:201], v[38:41]
	v_mfma_f32_16x16x32_bf16 v[34:37], v[180:183], v[198:201], v[34:37]
	v_mfma_f32_16x16x32_bf16 v[22:25], v[172:175], v[206:209], v[22:25]
	v_mfma_f32_16x16x32_bf16 v[18:21], v[180:183], v[206:209], v[18:21]
	v_mfma_f32_16x16x32_bf16 v[6:9], v[172:175], v[214:217], v[6:9]
	v_mfma_f32_16x16x32_bf16 v[2:5], v[180:183], v[214:217], v[2:5]
	s_setprio 0
	s_barrier
	s_add_i32 s66, s66, 2
	s_add_u32 s44, s44, 0x100
	s_addc_u32 s45, s45, 0
	s_add_u32 s64, s64, 0x100
	s_addc_u32 s65, s65, 0
	s_cmp_gt_u32 s66, 13
	s_cbranch_scc0 .LBB0_1133
	s_mov_b32 s99, 1
	s_and_b64 vcc, exec, s[18:19]
	s_cbranch_vccz .LBB0_1136
	s_barrier

;     DI bool next(int i, Unit& u) const { if (i > 0 || c >= 64) return false; u.pm = c & 31; u.pn = 0; u.src = c >> 5; return true; }
; #define PG8_STAGE(bufoff, gbase, voff) do { _Pragma("unroll") for (int _i = 0; _i < 2; ++_i) \
;         __builtin_amdgcn_global_load_lds((const unsigned*)((const char*)(gbase) + (voff)[_i]), (LAS unsigned*)(lds + (bufoff) + ldsw + _i * 8192), 16, 0, 0); } while (0)
; #define PG8_LDA(dst, b, h) do { _Pragma("unroll") for (int m = 0; m < 4; ++m) _Pragma("unroll") for (int k = 0; k < 2; ++k) dst[m][k] = *(const LAS bf16x8*)(lds + PG8_SA(b, h) + aoff + m * 2048 + k * 1024); } while (0)
; #define PG8_LDB(dst, b, h) do { _Pragma("unroll") for (int n = 0; n < 2; ++n) _Pragma("unroll") for (int k = 0; k < 2; ++k) dst[n][k] = *(const LAS bf16x8*)(lds + PG8_SB(b, h) + boff + n * 2048 + k * 1024); } while (0)
; template <class Epi, class Sched>
; DI void gemm_phase(LAS unsigned char* lds, const Gemm g, const Sched& S, const Epi& E) {
;     ...
;     for (;;) {
;         const bool has_next = S.next(ui + 1, nxt);
;         E.pre(pre, cur, wr, fr);
;         const char* nA = has_next ? (const char*)(nxt.src ? g.A1 : g.A0) + (size_t)nxt.pm * tstepA : cA; const char* nB = has_next ? (const char*)(nxt.src ? g.B1 : g.B0) + (size_t)nxt.pn * tstepB : cB;
;         for (int t = 0; t < nt; t += 2) {
;             const bool last = (t == nt - 2);
;             const char* a1 = cA + (size_t)(t + 1) * kstep;
;             const char* a2 = last ? nA : cA + (size_t)(t + 2) * kstep; const char* b2 = last ? nB : cB + (size_t)(t + 2) * kstep;
;             const char* a3 = a2 + kstep; const char* b3 = b2 + kstep;
;             PG8_LDB(B0, 0, 0); PG8_LDB(B1, 0, 1); PG8_SCHED; PG8_LDA(At, 0, 0); PG8_STAGE(PG8_SA(1, 1), a1 + hstepA, voffA);
;             PG8_WAIT_V(8); PG8_WAIT_L(0); PG8_BAR; PG8_MMA(0, 0, At, B0); PG8_MMA(0, 1, At, B1); PG8_BAR; PG8_SCHED;
;             PG8_LDA(At, 0, 1); PG8_STAGE(PG8_SB(0, 0), b2, voffB); PG8_STAGE(PG8_SB(0, 1), b2 + hstepB, voffB); PG8_STAGE(PG8_SA(0, 0), a2, voffA);
;             PG8_WAIT_V(8); PG8_WAIT_L(0); PG8_BAR; PG8_MMA(1, 0, At, B0); PG8_MMA(1, 1, At, B1); PG8_BAR; PG8_SCHED;
;             PG8_LDB(B0, 1, 0); PG8_LDB(B1, 1, 1); PG8_SCHED; PG8_LDA(At, 1, 0); PG8_STAGE(PG8_SA(0, 1), a2 + hstepA, voffA);
;             PG8_WAIT_V(8); PG8_WAIT_L(0); PG8_BAR; PG8_MMA(0, 0, At, B0); PG8_MMA(0, 1, At, B1); PG8_BAR; PG8_SCHED;
.Lpk5_w2:
	s_mov_b32 s99, 0
	s_waitcnt lgkmcnt(0)
	s_nop 0
	s_barrier
	s_setprio 1
	v_mfma_f32_16x16x32_bf16 v[62:65], v[166:169], v[202:205], 0
	v_mfma_f32_16x16x32_bf16 v[54:57], v[174:177], v[202:205], 0
	v_mfma_f32_16x16x32_bf16 v[46:49], v[166:169], v[210:213], 0
	v_mfma_f32_16x16x32_bf16 v[38:41], v[174:177], v[210:213], 0
	v_mfma_f32_16x16x32_bf16 v[30:33], v[166:169], v[218:221], 0
	v_mfma_f32_16x16x32_bf16 v[22:25], v[174:177], v[218:221], 0
	v_mfma_f32_16x16x32_bf16 v[14:17], v[166:169], v[226:229], 0
	v_mfma_f32_16x16x32_bf16 v[6:9], v[174:177], v[226:229], 0
	v_mfma_f32_16x16x32_bf16 v[62:65], v[170:173], v[206:209], v[62:65]
	v_mfma_f32_16x16x32_bf16 v[54:57], v[178:181], v[206:209], v[54:57]
	v_mfma_f32_16x16x32_bf16 v[46:49], v[170:173], v[214:217], v[46:49]
	v_mfma_f32_16x16x32_bf16 v[38:41], v[178:181], v[214:217], v[38:41]
	v_mfma_f32_16x16x32_bf16 v[30:33], v[170:173], v[222:225], v[30:33]
	v_mfma_f32_16x16x32_bf16 v[22:25], v[178:181], v[222:225], v[22:25]
	v_mfma_f32_16x16x32_bf16 v[14:17], v[170:173], v[230:233], v[14:17]
	v_mfma_f32_16x16x32_bf16 v[6:9], v[178:181], v[230:233], v[6:9]
	v_mfma_f32_16x16x32_bf16 v[58:61], v[186:189], v[202:205], 0
	v_mfma_f32_16x16x32_bf16 v[50:53], v[194:197], v[202:205], 0
	v_mfma_f32_16x16x32_bf16 v[42:45], v[186:189], v[210:213], 0
	v_mfma_f32_16x16x32_bf16 v[34:37], v[194:197], v[210:213], 0
	v_mfma_f32_16x16x32_bf16 v[26:29], v[186:189], v[218:221], 0
	v_mfma_f32_16x16x32_bf16 v[18:21], v[194:197], v[218:221], 0
	v_mfma_f32_16x16x32_bf16 v[10:13], v[186:189], v[226:229], 0
	v_mfma_f32_16x16x32_bf16 v[2:5], v[194:197], v[226:229], 0
	v_mfma_f32_16x16x32_bf16 v[58:61], v[190:193], v[206:209], v[58:61]
	v_mfma_f32_16x16x32_bf16 v[50:53], v[198:201], v[206:209], v[50:53]
	v_mfma_f32_16x16x32_bf16 v[42:45], v[190:193], v[214:217], v[42:45]
	v_mfma_f32_16x16x32_bf16 v[34:37], v[198:201], v[214:217], v[34:37]
	v_mfma_f32_16x16x32_bf16 v[26:29], v[190:193], v[222:225], v[26:29]
	v_mfma_f32_16x16x32_bf16 v[18:21], v[198:201], v[222:225], v[18:21]
	v_mfma_f32_16x16x32_bf16 v[10:13], v[190:193], v[230:233], v[10:13]
	v_mfma_f32_16x16x32_bf16 v[2:5], v[198:201], v[230:233], v[2:5]
	s_setprio 0
	s_barrier
	s_add_i32 s66, 0, 0x18000
	v_add_u32_e32 v165, s66, v156
	s_add_i32 s67, 0, 0x1c000
	ds_read_b128 v[166:169], v165
	ds_read_b128 v[170:173], v165 offset:1024
	ds_read_b128 v[174:177], v165 offset:2048
	ds_read_b128 v[178:181], v165 offset:3072
	v_add_u32_e32 v165, s67, v156
	ds_read_b128 v[186:189], v165
	ds_read_b128 v[190:193], v165 offset:1024
	ds_read_b128 v[194:197], v165 offset:2048
	ds_read_b128 v[198:201], v165 offset:3072
	s_add_u32 s44, s44, 0x40000
	s_addc_u32 s45, s45, 0
	s_mov_b32 m0, s51
	v_lshl_add_u64 v[240:241], s[44:45], 0, v[136:137]
	ds_read_b128 v[202:205], v158 offset:32768
	ds_read_b128 v[206:209], v158 offset:33792
	ds_read_b128 v[210:213], v158 offset:34816
	ds_read_b128 v[214:217], v158 offset:35840
	ds_read_b128 v[218:221], v158 offset:36864
	ds_read_b128 v[222:225], v158 offset:37888
	ds_read_b128 v[226:229], v158 offset:38912
	ds_read_b128 v[230:233], v158 offset:39936
	global_load_lds_dwordx4 v[240:241], off
	v_lshl_add_u64 v[240:241], s[44:45], 0, v[132:133]
	s_mov_b32 m0, s52
	s_nop 0
	global_load_lds_dwordx4 v[240:241], off
	s_waitcnt vmcnt(8)
	s_waitcnt lgkmcnt(0)
	s_barrier
	s_setprio 1
	v_mfma_f32_16x16x32_bf16 v[126:129], v[166:169], v[202:205], v[126:129]
	v_mfma_f32_16x16x32_bf16 v[118:121], v[174:177], v[202:205], v[118:121]
	v_mfma_f32_16x16x32_bf16 v[110:113], v[166:169], v[210:213], v[110:113]
	v_mfma_f32_16x16x32_bf16 v[102:105], v[174:177], v[210:213], v[102:105]
	v_mfma_f32_16x16x32_bf16 v[94:97], v[166:169], v[218:221], v[94:97]
	v_mfma_f32_16x16x32_bf16 v[86:89], v[174:177], v[218:221], v[86:89]
	v_mfma_f32_16x16x32_bf16 v[78:81], v[166:169], v[226:229], v[78:81]
	v_mfma_f32_16x16x32_bf16 v[70:73], v[174:177], v[226:229], v[70:73]
	v_mfma_f32_16x16x32_bf16 v[126:129], v[170:173], v[206:209], v[126:129]
	v_mfma_f32_16x16x32_bf16 v[118:121], v[178:181], v[206:209], v[118:121]
	v_mfma_f32_16x16x32_bf16 v[110:113], v[170:173], v[214:217], v[110:113]
	v_mfma_f32_16x16x32_bf16 v[102:105], v[178:181], v[214:217], v[102:105]
	v_mfma_f32_16x16x32_bf16 v[94:97], v[170:173], v[222:225], v[94:97]
	v_mfma_f32_16x16x32_bf16 v[86:89], v[178:181], v[222:225], v[86:89]
	v_mfma_f32_16x16x32_bf16 v[78:81], v[170:173], v[230:233], v[78:81]
	v_mfma_f32_16x16x32_bf16 v[70:73], v[178:181], v[230:233], v[70:73]
	v_mfma_f32_16x16x32_bf16 v[122:125], v[186:189], v[202:205], v[122:125]
	v_mfma_f32_16x16x32_bf16 v[114:117], v[194:197], v[202:205], v[114:117]
	v_mfma_f32_16x16x32_bf16 v[106:109], v[186:189], v[210:213], v[106:109]
	v_mfma_f32_16x16x32_bf16 v[98:101], v[194:197], v[210:213], v[98:101]
	v_mfma_f32_16x16x32_bf16 v[90:93], v[186:189], v[218:221], v[90:93]
	v_mfma_f32_16x16x32_bf16 v[82:85], v[194:197], v[218:221], v[82:85]
	v_mfma_f32_16x16x32_bf16 v[74:77], v[186:189], v[226:229], v[74:77]
	v_mfma_f32_16x16x32_bf16 v[66:69], v[194:197], v[226:229], v[66:69]
	v_mfma_f32_16x16x32_bf16 v[122:125], v[190:193], v[206:209], v[122:125]
	v_mfma_f32_16x16x32_bf16 v[114:117], v[198:201], v[206:209], v[114:117]
	v_mfma_f32_16x16x32_bf16 v[106:109], v[190:193], v[214:217], v[106:109]
	v_mfma_f32_16x16x32_bf16 v[98:101], v[198:201], v[214:217], v[98:101]
	v_mfma_f32_16x16x32_bf16 v[90:93], v[190:193], v[222:225], v[90:93]
	v_mfma_f32_16x16x32_bf16 v[82:85], v[198:201], v[222:225], v[82:85]
	v_mfma_f32_16x16x32_bf16 v[74:77], v[190:193], v[230:233], v[74:77]
	v_mfma_f32_16x16x32_bf16 v[66:69], v[198:201], v[230:233], v[66:69]
	s_setprio 0
	s_barrier
; #define PG8_STAGE(bufoff, gbase, voff) do { _Pragma("unroll") for (int _i = 0; _i < 2; ++_i) \
;         __builtin_amdgcn_global_load_lds((const unsigned*)((const char*)(gbase) + (voff)[_i]), (LAS unsigned*)(lds + (bufoff) + ldsw + _i * 8192), 16, 0, 0); } while (0)
; #define PG8_LDA(dst, b, h) do { _Pragma("unroll") for (int m = 0; m < 4; ++m) _Pragma("unroll") for (int k = 0; k < 2; ++k) dst[m][k] = *(const LAS bf16x8*)(lds + PG8_SA(b, h) + aoff + m * 2048 + k * 1024); } while (0)
; #define PG8_LDB(dst, b, h) do { _Pragma("unroll") for (int n = 0; n < 2; ++n) _Pragma("unroll") for (int k = 0; k < 2; ++k) dst[n][k] = *(const LAS bf16x8*)(lds + PG8_SB(b, h) + boff + n * 2048 + k * 1024); } while (0)
; #define PG8_MMA(ai, bj, At, Bt) do { __builtin_amdgcn_s_setprio(1); _Pragma("unroll") for (int m = 0; m < 4; ++m) _Pragma("unroll") for (int n = 0; n < 2; ++n) _Pragma("unroll") for (int k = 0; k < 2; ++k) \
;         acc[ai][bj][m][n] = __builtin_amdgcn_mfma_f32_16x16x32_bf16(Bt[n][k], At[m][k], acc[ai][bj][m][n], 0, 0, 0); __builtin_amdgcn_s_setprio(0); } while (0)
; #define PG8_WAIT_V(n) asm volatile("s_waitcnt vmcnt(" #n ")" ::: "memory")
; #define PG8_WAIT_L(n) asm volatile("s_waitcnt lgkmcnt(" #n ")" ::: "memory")
; template <class Epi, class Sched>
; DI void gemm_phase(LAS unsigned char* lds, const Gemm g, const Sched& S, const Epi& E) {
;     ...
;         for (int t = 0; t < nt; t += 2) {
;             const bool last = (t == nt - 2);
;             const char* a1 = cA + (size_t)(t + 1) * kstep;
;             const char* a2 = last ? nA : cA + (size_t)(t + 2) * kstep; const char* b2 = last ? nB : cB + (size_t)(t + 2) * kstep;
;             const char* a3 = a2 + kstep; const char* b3 = b2 + kstep;
;             PG8_LDB(B0, 0, 0); PG8_LDB(B1, 0, 1); PG8_SCHED; PG8_LDA(At, 0, 0); PG8_STAGE(PG8_SA(1, 1), a1 + hstepA, voffA);
;             PG8_WAIT_V(8); PG8_WAIT_L(0); PG8_BAR; PG8_MMA(0, 0, At, B0); PG8_MMA(0, 1, At, B1); PG8_BAR; PG8_SCHED;
;             PG8_LDA(At, 0, 1); PG8_STAGE(PG8_SB(0, 0), b2, voffB); PG8_STAGE(PG8_SB(0, 1), b2 + hstepB, voffB); PG8_STAGE(PG8_SA(0, 0), a2, voffA);
;     ...
;             PG8_LDA(At, 1, 1); PG8_STAGE(PG8_SB(1, 0), b3, voffB); PG8_STAGE(PG8_SB(1, 1), b3 + hstepB, voffB); PG8_STAGE(PG8_SA(1, 0), a3, voffA);
;             PG8_WAIT_V(8); PG8_WAIT_L(0); PG8_BAR; PG8_MMA(1, 0, At, B0); PG8_MMA(1, 1, At, B1); PG8_BAR; PG8_SCHED;
	s_add_i32 s44, s66, s46
	v_lshl_add_u64 v[182:183], v[182:183], 0, s[16:17]
	s_mov_b32 m0, s44
	ds_read_b128 v[202:205], v158 offset:49152
	ds_read_b128 v[206:209], v158 offset:50176
	ds_read_b128 v[210:213], v158 offset:51200
	ds_read_b128 v[214:217], v158 offset:52224
	ds_read_b128 v[218:221], v158 offset:53248
	ds_read_b128 v[222:225], v158 offset:54272
	ds_read_b128 v[226:229], v158 offset:55296
	ds_read_b128 v[230:233], v158 offset:56320
	global_load_lds_dwordx4 v[182:183], off
	s_add_i32 m0, s44, 0x2000
	s_add_u32 s42, s42, 0x40080
	v_lshl_add_u64 v[182:183], v[234:235], 0, s[16:17]
	s_addc_u32 s43, s43, 0
	s_add_i32 s44, s67, s46
	global_load_lds_dwordx4 v[182:183], off
	v_lshl_add_u64 v[182:183], s[42:43], 0, v[134:135]
	s_mov_b32 m0, s44
	s_nop 0
	global_load_lds_dwordx4 v[182:183], off
	v_lshl_add_u64 v[182:183], s[42:43], 0, v[130:131]
	s_add_i32 m0, s44, 0x2000
	s_nop 0
	global_load_lds_dwordx4 v[182:183], off
	v_lshl_add_u64 v[182:183], v[236:237], 0, s[16:17]
	s_mov_b32 m0, s54
	s_nop 0
	global_load_lds_dwordx4 v[182:183], off
	v_lshl_add_u64 v[182:183], v[238:239], 0, s[16:17]
	s_mov_b32 m0, s55
	s_nop 0
	global_load_lds_dwordx4 v[182:183], off
	s_waitcnt vmcnt(8)
	s_waitcnt lgkmcnt(0)
	s_nop 0
	s_barrier
	s_setprio 1
	v_mfma_f32_16x16x32_bf16 v[62:65], v[166:169], v[202:205], v[62:65]
	v_mfma_f32_16x16x32_bf16 v[54:57], v[174:177], v[202:205], v[54:57]
	v_mfma_f32_16x16x32_bf16 v[46:49], v[166:169], v[210:213], v[46:49]
	v_mfma_f32_16x16x32_bf16 v[38:41], v[174:177], v[210:213], v[38:41]
	v_mfma_f32_16x16x32_bf16 v[30:33], v[166:169], v[218:221], v[30:33]
	v_mfma_f32_16x16x32_bf16 v[22:25], v[174:177], v[218:221], v[22:25]
	v_mfma_f32_16x16x32_bf16 v[14:17], v[166:169], v[226:229], v[14:17]
	v_mfma_f32_16x16x32_bf16 v[6:9], v[174:177], v[226:229], v[6:9]
	v_mfma_f32_16x16x32_bf16 v[62:65], v[170:173], v[206:209], v[62:65]
	v_mfma_f32_16x16x32_bf16 v[54:57], v[178:181], v[206:209], v[54:57]
	v_mfma_f32_16x16x32_bf16 v[46:49], v[170:173], v[214:217], v[46:49]
	v_mfma_f32_16x16x32_bf16 v[38:41], v[178:181], v[214:217], v[38:41]
	v_mfma_f32_16x16x32_bf16 v[30:33], v[170:173], v[222:225], v[30:33]
	v_mfma_f32_16x16x32_bf16 v[22:25], v[178:181], v[222:225], v[22:25]
	v_mfma_f32_16x16x32_bf16 v[14:17], v[170:173], v[230:233], v[14:17]
	v_mfma_f32_16x16x32_bf16 v[6:9], v[178:181], v[230:233], v[6:9]
	v_mfma_f32_16x16x32_bf16 v[58:61], v[186:189], v[202:205], v[58:61]
	v_mfma_f32_16x16x32_bf16 v[50:53], v[194:197], v[202:205], v[50:53]
	v_mfma_f32_16x16x32_bf16 v[42:45], v[186:189], v[210:213], v[42:45]
	v_mfma_f32_16x16x32_bf16 v[34:37], v[194:197], v[210:213], v[34:37]
	v_mfma_f32_16x16x32_bf16 v[26:29], v[186:189], v[218:221], v[26:29]
	v_mfma_f32_16x16x32_bf16 v[18:21], v[194:197], v[218:221], v[18:21]
	v_mfma_f32_16x16x32_bf16 v[10:13], v[186:189], v[226:229], v[10:13]
	v_mfma_f32_16x16x32_bf16 v[2:5], v[194:197], v[226:229], v[2:5]
	v_mfma_f32_16x16x32_bf16 v[58:61], v[190:193], v[206:209], v[58:61]
	v_mfma_f32_16x16x32_bf16 v[50:53], v[198:201], v[206:209], v[50:53]
	v_mfma_f32_16x16x32_bf16 v[42:45], v[190:193], v[214:217], v[42:45]
	v_mfma_f32_16x16x32_bf16 v[34:37], v[198:201], v[214:217], v[34:37]
	v_mfma_f32_16x16x32_bf16 v[26:29], v[190:193], v[222:225], v[26:29]
	v_mfma_f32_16x16x32_bf16 v[18:21], v[198:201], v[222:225], v[18:21]
	v_mfma_f32_16x16x32_bf16 v[10:13], v[190:193], v[230:233], v[10:13]
	v_mfma_f32_16x16x32_bf16 v[2:5], v[198:201], v[230:233], v[2:5]
	s_setprio 0
	s_barrier
	s_add_i32 s65, s65, 2
	s_add_u32 s40, s40, 0x100
	s_addc_u32 s41, s41, 0
	s_add_u32 s63, s63, 0x100
	s_addc_u32 s64, s64, 0
	s_cmp_gt_u32 s65, 13
.LBB0_1234:
	ds_read_b128 v[166:169], v160
	ds_read_b128 v[170:173], v160 offset:1024
	ds_read_b128 v[174:177], v160 offset:2048
	ds_read_b128 v[178:181], v160 offset:3072
	ds_read_b128 v[186:189], v161
	ds_read_b128 v[190:193], v161 offset:1024
	ds_read_b128 v[194:197], v161 offset:2048
	ds_read_b128 v[198:201], v161 offset:3072
	s_add_u32 s42, s40, 0xfffc0080
	s_addc_u32 s43, s41, -1
	s_cmp_eq_u32 s65, 12
	s_cselect_b32 s45, s35, s43
	s_cselect_b32 s44, s61, s42
	s_cselect_b32 s43, s21, s64
	s_cselect_b32 s42, s62, s63
	v_lshl_add_u64 v[182:183], s[40:41], 0, v[138:139]
	s_add_i32 m0, s49, 0xc000
	ds_read_b128 v[202:205], v158
	ds_read_b128 v[206:209], v158 offset:1024
	ds_read_b128 v[210:213], v158 offset:2048
	ds_read_b128 v[214:217], v158 offset:3072
	ds_read_b128 v[218:221], v158 offset:4096
	ds_read_b128 v[222:225], v158 offset:5120
	ds_read_b128 v[226:229], v158 offset:6144
	ds_read_b128 v[230:233], v158 offset:7168
	global_load_lds_dwordx4 v[182:183], off
	v_lshl_add_u64 v[182:183], s[40:41], 0, v[140:141]
	s_add_i32 m0, s49, 0xe000
	s_nop 0
	global_load_lds_dwordx4 v[182:183], off
	s_waitcnt vmcnt(8)
	s_waitcnt lgkmcnt(0)
	s_nop 0
	s_barrier
; #define PG8_STAGE(bufoff, gbase, voff) do { _Pragma("unroll") for (int _i = 0; _i < 2; ++_i) \
;         __builtin_amdgcn_global_load_lds((const unsigned*)((const char*)(gbase) + (voff)[_i]), (LAS unsigned*)(lds + (bufoff) + ldsw + _i * 8192), 16, 0, 0); } while (0)
; #define PG8_LDA(dst, b, h) do { _Pragma("unroll") for (int m = 0; m < 4; ++m) _Pragma("unroll") for (int k = 0; k < 2; ++k) dst[m][k] = *(const LAS bf16x8*)(lds + PG8_SA(b, h) + aoff + m * 2048 + k * 1024); } while (0)
; #define PG8_MMA(ai, bj, At, Bt) do { __builtin_amdgcn_s_setprio(1); _Pragma("unroll") for (int m = 0; m < 4; ++m) _Pragma("unroll") for (int n = 0; n < 2; ++n) _Pragma("unroll") for (int k = 0; k < 2; ++k) \
;         acc[ai][bj][m][n] = __builtin_amdgcn_mfma_f32_16x16x32_bf16(Bt[n][k], At[m][k], acc[ai][bj][m][n], 0, 0, 0); __builtin_amdgcn_s_setprio(0); } while (0)
; #define PG8_WAIT_V(n) asm volatile("s_waitcnt vmcnt(" #n ")" ::: "memory")
; #define PG8_WAIT_L(n) asm volatile("s_waitcnt lgkmcnt(" #n ")" ::: "memory")
; #define PG8_BAR __builtin_amdgcn_s_barrier()
; #define PG8_SCHED __builtin_amdgcn_sched_barrier(0)
; template <class Epi, class Sched>
; DI void gemm_phase(LAS unsigned char* lds, const Gemm g, const Sched& S, const Epi& E) {
;     ...
;             PG8_WAIT_V(8); PG8_WAIT_L(0); PG8_BAR; PG8_MMA(0, 0, At, B0); PG8_MMA(0, 1, At, B1); PG8_BAR; PG8_SCHED;
;             PG8_LDA(At, 0, 1); PG8_STAGE(PG8_SB(0, 0), b2, voffB); PG8_STAGE(PG8_SB(0, 1), b2 + hstepB, voffB); PG8_STAGE(PG8_SA(0, 0), a2, voffA);
;             PG8_WAIT_V(8); PG8_WAIT_L(0); PG8_BAR; PG8_MMA(1, 0, At, B0); PG8_MMA(1, 1, At, B1); PG8_BAR; PG8_SCHED;
	s_setprio 1
	v_mfma_f32_16x16x32_bf16 v[126:129], v[166:169], v[202:205], v[126:129]
	v_mfma_f32_16x16x32_bf16 v[118:121], v[174:177], v[202:205], v[118:121]
	v_mfma_f32_16x16x32_bf16 v[110:113], v[166:169], v[210:213], v[110:113]
	v_mfma_f32_16x16x32_bf16 v[102:105], v[174:177], v[210:213], v[102:105]
	v_mfma_f32_16x16x32_bf16 v[94:97], v[166:169], v[218:221], v[94:97]
	v_mfma_f32_16x16x32_bf16 v[86:89], v[174:177], v[218:221], v[86:89]
	v_mfma_f32_16x16x32_bf16 v[78:81], v[166:169], v[226:229], v[78:81]
	v_mfma_f32_16x16x32_bf16 v[70:73], v[174:177], v[226:229], v[70:73]
	v_mfma_f32_16x16x32_bf16 v[126:129], v[170:173], v[206:209], v[126:129]
	v_mfma_f32_16x16x32_bf16 v[118:121], v[178:181], v[206:209], v[118:121]
	v_mfma_f32_16x16x32_bf16 v[110:113], v[170:173], v[214:217], v[110:113]
	v_mfma_f32_16x16x32_bf16 v[102:105], v[178:181], v[214:217], v[102:105]
	v_mfma_f32_16x16x32_bf16 v[94:97], v[170:173], v[222:225], v[94:97]
	v_mfma_f32_16x16x32_bf16 v[86:89], v[178:181], v[222:225], v[86:89]
	v_mfma_f32_16x16x32_bf16 v[78:81], v[170:173], v[230:233], v[78:81]
	v_mfma_f32_16x16x32_bf16 v[70:73], v[178:181], v[230:233], v[70:73]
	v_mfma_f32_16x16x32_bf16 v[122:125], v[186:189], v[202:205], v[122:125]
	v_mfma_f32_16x16x32_bf16 v[114:117], v[194:197], v[202:205], v[114:117]
	v_mfma_f32_16x16x32_bf16 v[106:109], v[186:189], v[210:213], v[106:109]
	v_mfma_f32_16x16x32_bf16 v[98:101], v[194:197], v[210:213], v[98:101]
	v_mfma_f32_16x16x32_bf16 v[90:93], v[186:189], v[218:221], v[90:93]
	v_mfma_f32_16x16x32_bf16 v[82:85], v[194:197], v[218:221], v[82:85]
	v_mfma_f32_16x16x32_bf16 v[74:77], v[186:189], v[226:229], v[74:77]
	v_mfma_f32_16x16x32_bf16 v[66:69], v[194:197], v[226:229], v[66:69]
	v_mfma_f32_16x16x32_bf16 v[122:125], v[190:193], v[206:209], v[122:125]
	v_mfma_f32_16x16x32_bf16 v[114:117], v[198:201], v[206:209], v[114:117]
	v_mfma_f32_16x16x32_bf16 v[106:109], v[190:193], v[214:217], v[106:109]
	v_mfma_f32_16x16x32_bf16 v[98:101], v[198:201], v[214:217], v[98:101]
	v_mfma_f32_16x16x32_bf16 v[90:93], v[190:193], v[222:225], v[90:93]
	v_mfma_f32_16x16x32_bf16 v[82:85], v[198:201], v[222:225], v[82:85]
	v_mfma_f32_16x16x32_bf16 v[74:77], v[190:193], v[230:233], v[74:77]
	v_mfma_f32_16x16x32_bf16 v[66:69], v[198:201], v[230:233], v[66:69]
	s_setprio 0
	s_barrier
	s_add_i32 s66, s57, s46
	v_lshl_add_u64 v[182:183], s[42:43], 0, v[134:135]
	s_mov_b32 m0, s66
	ds_read_b128 v[202:205], v158 offset:16384
	ds_read_b128 v[206:209], v158 offset:17408
	ds_read_b128 v[210:213], v158 offset:18432
	ds_read_b128 v[214:217], v158 offset:19456
	ds_read_b128 v[218:221], v158 offset:20480
	ds_read_b128 v[222:225], v158 offset:21504
	ds_read_b128 v[226:229], v158 offset:22528
	ds_read_b128 v[230:233], v158 offset:23552
	global_load_lds_dwordx4 v[182:183], off
	s_add_i32 m0, s66, 0x2000
	s_add_u32 s66, s42, 0x40000
	v_lshl_add_u64 v[234:235], s[42:43], 0, v[130:131]
	s_addc_u32 s67, s43, 0
	s_add_i32 s68, s58, s46
	global_load_lds_dwordx4 v[234:235], off
	v_lshl_add_u64 v[236:237], s[66:67], 0, v[134:135]
	s_mov_b32 m0, s68
	v_lshl_add_u64 v[238:239], s[44:45], 0, v[132:133]
	global_load_lds_dwordx4 v[236:237], off
	v_lshl_add_u64 v[236:237], s[66:67], 0, v[130:131]
	s_add_i32 m0, s68, 0x2000
	s_nop 0
	global_load_lds_dwordx4 v[236:237], off
	v_lshl_add_u64 v[236:237], s[44:45], 0, v[136:137]
	s_mov_b32 m0, s49
	s_nop 0
	global_load_lds_dwordx4 v[236:237], off
	s_mov_b32 m0, s50
	s_nop 0
	global_load_lds_dwordx4 v[238:239], off
	s_waitcnt vmcnt(8)
	s_waitcnt lgkmcnt(0)
	s_barrier
	s_setprio 1
	v_mfma_f32_16x16x32_bf16 v[62:65], v[166:169], v[202:205], v[62:65]
	v_mfma_f32_16x16x32_bf16 v[54:57], v[174:177], v[202:205], v[54:57]
	v_mfma_f32_16x16x32_bf16 v[46:49], v[166:169], v[210:213], v[46:49]
	v_mfma_f32_16x16x32_bf16 v[38:41], v[174:177], v[210:213], v[38:41]
	v_mfma_f32_16x16x32_bf16 v[30:33], v[166:169], v[218:221], v[30:33]
	v_mfma_f32_16x16x32_bf16 v[22:25], v[174:177], v[218:221], v[22:25]
	v_mfma_f32_16x16x32_bf16 v[14:17], v[166:169], v[226:229], v[14:17]
	v_mfma_f32_16x16x32_bf16 v[6:9], v[174:177], v[226:229], v[6:9]
	v_mfma_f32_16x16x32_bf16 v[62:65], v[170:173], v[206:209], v[62:65]
	v_mfma_f32_16x16x32_bf16 v[54:57], v[178:181], v[206:209], v[54:57]
	v_mfma_f32_16x16x32_bf16 v[46:49], v[170:173], v[214:217], v[46:49]
	v_mfma_f32_16x16x32_bf16 v[38:41], v[178:181], v[214:217], v[38:41]
	v_mfma_f32_16x16x32_bf16 v[30:33], v[170:173], v[222:225], v[30:33]
	v_mfma_f32_16x16x32_bf16 v[22:25], v[178:181], v[222:225], v[22:25]
	v_mfma_f32_16x16x32_bf16 v[14:17], v[170:173], v[230:233], v[14:17]
	v_mfma_f32_16x16x32_bf16 v[6:9], v[178:181], v[230:233], v[6:9]
	v_mfma_f32_16x16x32_bf16 v[58:61], v[186:189], v[202:205], v[58:61]
	v_mfma_f32_16x16x32_bf16 v[50:53], v[194:197], v[202:205], v[50:53]
	v_mfma_f32_16x16x32_bf16 v[42:45], v[186:189], v[210:213], v[42:45]
	v_mfma_f32_16x16x32_bf16 v[34:37], v[194:197], v[210:213], v[34:37]
	v_mfma_f32_16x16x32_bf16 v[26:29], v[186:189], v[218:221], v[26:29]
	v_mfma_f32_16x16x32_bf16 v[18:21], v[194:197], v[218:221], v[18:21]
	v_mfma_f32_16x16x32_bf16 v[10:13], v[186:189], v[226:229], v[10:13]
	v_mfma_f32_16x16x32_bf16 v[2:5], v[194:197], v[226:229], v[2:5]
	v_mfma_f32_16x16x32_bf16 v[58:61], v[190:193], v[206:209], v[58:61]
	v_mfma_f32_16x16x32_bf16 v[50:53], v[198:201], v[206:209], v[50:53]
	v_mfma_f32_16x16x32_bf16 v[42:45], v[190:193], v[214:217], v[42:45]
	v_mfma_f32_16x16x32_bf16 v[34:37], v[198:201], v[214:217], v[34:37]
	v_mfma_f32_16x16x32_bf16 v[26:29], v[190:193], v[222:225], v[26:29]
	v_mfma_f32_16x16x32_bf16 v[18:21], v[198:201], v[222:225], v[18:21]
	v_mfma_f32_16x16x32_bf16 v[10:13], v[190:193], v[230:233], v[10:13]
	v_mfma_f32_16x16x32_bf16 v[2:5], v[198:201], v[230:233], v[2:5]
	s_setprio 0
	s_barrier
; #define PG8_STAGE(bufoff, gbase, voff) do { _Pragma("unroll") for (int _i = 0; _i < 2; ++_i) \
;         __builtin_amdgcn_global_load_lds((const unsigned*)((const char*)(gbase) + (voff)[_i]), (LAS unsigned*)(lds + (bufoff) + ldsw + _i * 8192), 16, 0, 0); } while (0)
; #define PG8_LDA(dst, b, h) do { _Pragma("unroll") for (int m = 0; m < 4; ++m) _Pragma("unroll") for (int k = 0; k < 2; ++k) dst[m][k] = *(const LAS bf16x8*)(lds + PG8_SA(b, h) + aoff + m * 2048 + k * 1024); } while (0)
; #define PG8_LDB(dst, b, h) do { _Pragma("unroll") for (int n = 0; n < 2; ++n) _Pragma("unroll") for (int k = 0; k < 2; ++k) dst[n][k] = *(const LAS bf16x8*)(lds + PG8_SB(b, h) + boff + n * 2048 + k * 1024); } while (0)
; #define PG8_MMA(ai, bj, At, Bt) do { __builtin_amdgcn_s_setprio(1); _Pragma("unroll") for (int m = 0; m < 4; ++m) _Pragma("unroll") for (int n = 0; n < 2; ++n) _Pragma("unroll") for (int k = 0; k < 2; ++k) \
;         acc[ai][bj][m][n] = __builtin_amdgcn_mfma_f32_16x16x32_bf16(Bt[n][k], At[m][k], acc[ai][bj][m][n], 0, 0, 0); __builtin_amdgcn_s_setprio(0); } while (0)
; #define PG8_WAIT_V(n) asm volatile("s_waitcnt vmcnt(" #n ")" ::: "memory")
; #define PG8_WAIT_L(n) asm volatile("s_waitcnt lgkmcnt(" #n ")" ::: "memory")
; #define PG8_BAR __builtin_amdgcn_s_barrier()
; #define PG8_SCHED __builtin_amdgcn_sched_barrier(0)
; template <class Epi, class Sched>
; DI void gemm_phase(LAS unsigned char* lds, const Gemm g, const Sched& S, const Epi& E) {
;     ...
;             PG8_LDB(B0, 1, 0); PG8_LDB(B1, 1, 1); PG8_SCHED; PG8_LDA(At, 1, 0); PG8_STAGE(PG8_SA(0, 1), a2 + hstepA, voffA);
;             PG8_WAIT_V(8); PG8_WAIT_L(0); PG8_BAR; PG8_MMA(0, 0, At, B0); PG8_MMA(0, 1, At, B1); PG8_BAR; PG8_SCHED;
	s_add_i32 s66, 0, 0x18000
	v_add_u32_e32 v165, s66, v156
	s_add_i32 s67, 0, 0x1c000
	ds_read_b128 v[166:169], v165
	ds_read_b128 v[170:173], v165 offset:1024
	ds_read_b128 v[174:177], v165 offset:2048
	ds_read_b128 v[178:181], v165 offset:3072
	v_add_u32_e32 v165, s67, v156
	ds_read_b128 v[186:189], v165
	ds_read_b128 v[190:193], v165 offset:1024
	ds_read_b128 v[194:197], v165 offset:2048
	ds_read_b128 v[198:201], v165 offset:3072
	s_add_u32 s44, s44, 0x40000
	s_addc_u32 s45, s45, 0
	s_mov_b32 m0, s51
	v_lshl_add_u64 v[240:241], s[44:45], 0, v[136:137]
	ds_read_b128 v[202:205], v158 offset:32768
	ds_read_b128 v[206:209], v158 offset:33792
	ds_read_b128 v[210:213], v158 offset:34816
	ds_read_b128 v[214:217], v158 offset:35840
	ds_read_b128 v[218:221], v158 offset:36864
	ds_read_b128 v[222:225], v158 offset:37888
	ds_read_b128 v[226:229], v158 offset:38912
	ds_read_b128 v[230:233], v158 offset:39936
	global_load_lds_dwordx4 v[240:241], off
	v_lshl_add_u64 v[240:241], s[44:45], 0, v[132:133]
	s_mov_b32 m0, s52
	s_nop 0
	global_load_lds_dwordx4 v[240:241], off
	s_waitcnt vmcnt(8)
	s_waitcnt lgkmcnt(0)
	s_barrier
	s_setprio 1
	v_mfma_f32_16x16x32_bf16 v[126:129], v[166:169], v[202:205], v[126:129]
	v_mfma_f32_16x16x32_bf16 v[118:121], v[174:177], v[202:205], v[118:121]
	v_mfma_f32_16x16x32_bf16 v[110:113], v[166:169], v[210:213], v[110:113]
	v_mfma_f32_16x16x32_bf16 v[102:105], v[174:177], v[210:213], v[102:105]
	v_mfma_f32_16x16x32_bf16 v[94:97], v[166:169], v[218:221], v[94:97]
	v_mfma_f32_16x16x32_bf16 v[86:89], v[174:177], v[218:221], v[86:89]
	v_mfma_f32_16x16x32_bf16 v[78:81], v[166:169], v[226:229], v[78:81]
	v_mfma_f32_16x16x32_bf16 v[70:73], v[174:177], v[226:229], v[70:73]
	v_mfma_f32_16x16x32_bf16 v[126:129], v[170:173], v[206:209], v[126:129]
	v_mfma_f32_16x16x32_bf16 v[118:121], v[178:181], v[206:209], v[118:121]
	v_mfma_f32_16x16x32_bf16 v[110:113], v[170:173], v[214:217], v[110:113]
	v_mfma_f32_16x16x32_bf16 v[102:105], v[178:181], v[214:217], v[102:105]
	v_mfma_f32_16x16x32_bf16 v[94:97], v[170:173], v[222:225], v[94:97]
	v_mfma_f32_16x16x32_bf16 v[86:89], v[178:181], v[222:225], v[86:89]
	v_mfma_f32_16x16x32_bf16 v[78:81], v[170:173], v[230:233], v[78:81]
	v_mfma_f32_16x16x32_bf16 v[70:73], v[178:181], v[230:233], v[70:73]
	v_mfma_f32_16x16x32_bf16 v[122:125], v[186:189], v[202:205], v[122:125]
	v_mfma_f32_16x16x32_bf16 v[114:117], v[194:197], v[202:205], v[114:117]
	v_mfma_f32_16x16x32_bf16 v[106:109], v[186:189], v[210:213], v[106:109]
	v_mfma_f32_16x16x32_bf16 v[98:101], v[194:197], v[210:213], v[98:101]
	v_mfma_f32_16x16x32_bf16 v[90:93], v[186:189], v[218:221], v[90:93]
	v_mfma_f32_16x16x32_bf16 v[82:85], v[194:197], v[218:221], v[82:85]
	v_mfma_f32_16x16x32_bf16 v[74:77], v[186:189], v[226:229], v[74:77]
	v_mfma_f32_16x16x32_bf16 v[66:69], v[194:197], v[226:229], v[66:69]
	v_mfma_f32_16x16x32_bf16 v[122:125], v[190:193], v[206:209], v[122:125]
	v_mfma_f32_16x16x32_bf16 v[114:117], v[198:201], v[206:209], v[114:117]
	v_mfma_f32_16x16x32_bf16 v[106:109], v[190:193], v[214:217], v[106:109]
	v_mfma_f32_16x16x32_bf16 v[98:101], v[198:201], v[214:217], v[98:101]
	v_mfma_f32_16x16x32_bf16 v[90:93], v[190:193], v[222:225], v[90:93]
	v_mfma_f32_16x16x32_bf16 v[82:85], v[198:201], v[222:225], v[82:85]
	v_mfma_f32_16x16x32_bf16 v[74:77], v[190:193], v[230:233], v[74:77]
	v_mfma_f32_16x16x32_bf16 v[66:69], v[198:201], v[230:233], v[66:69]
	s_setprio 0
	s_barrier
; #define PG8_STAGE(bufoff, gbase, voff) do { _Pragma("unroll") for (int _i = 0; _i < 2; ++_i) \
;         __builtin_amdgcn_global_load_lds((const unsigned*)((const char*)(gbase) + (voff)[_i]), (LAS unsigned*)(lds + (bufoff) + ldsw + _i * 8192), 16, 0, 0); } while (0)
; #define PG8_LDA(dst, b, h) do { _Pragma("unroll") for (int m = 0; m < 4; ++m) _Pragma("unroll") for (int k = 0; k < 2; ++k) dst[m][k] = *(const LAS bf16x8*)(lds + PG8_SA(b, h) + aoff + m * 2048 + k * 1024); } while (0)
; #define PG8_MMA(ai, bj, At, Bt) do { __builtin_amdgcn_s_setprio(1); _Pragma("unroll") for (int m = 0; m < 4; ++m) _Pragma("unroll") for (int n = 0; n < 2; ++n) _Pragma("unroll") for (int k = 0; k < 2; ++k) \
;         acc[ai][bj][m][n] = __builtin_amdgcn_mfma_f32_16x16x32_bf16(Bt[n][k], At[m][k], acc[ai][bj][m][n], 0, 0, 0); __builtin_amdgcn_s_setprio(0); } while (0)
; #define PG8_WAIT_V(n) asm volatile("s_waitcnt vmcnt(" #n ")" ::: "memory")
; #define PG8_WAIT_L(n) asm volatile("s_waitcnt lgkmcnt(" #n ")" ::: "memory")
; #define PG8_BAR __builtin_amdgcn_s_barrier()
; #define PG8_SCHED __builtin_amdgcn_sched_barrier(0)
;     DI void pre(Pre& pr, const pg8::Unit& u, int wr, int fr) const { load_rows(pr, ssq, u, wr, fr); }
;     DI void pre(Pre& pr, const pg8::Unit& u, int wr, int fr) const { load_rows(pr, ssq, u, wr, fr); }
; template <class Epi, class Sched>
; DI void gemm_phase(LAS unsigned char* lds, const Gemm g, const Sched& S, const Epi& E) {
;     ...
;             PG8_LDA(At, 1, 1); PG8_STAGE(PG8_SB(1, 0), b3, voffB); PG8_STAGE(PG8_SB(1, 1), b3 + hstepB, voffB); PG8_STAGE(PG8_SA(1, 0), a3, voffA);
;             PG8_WAIT_V(8); PG8_WAIT_L(0); PG8_BAR; PG8_MMA(1, 0, At, B0); PG8_MMA(1, 1, At, B1); PG8_BAR; PG8_SCHED;
;         }
;         if (wr == 0) PG8_BAR;
;         E(acc, cur, wr, wc, fr, fq, pre);
;         if (!has_next) break;
	s_add_i32 s44, s66, s46
	v_lshl_add_u64 v[182:183], v[182:183], 0, s[16:17]
	s_mov_b32 m0, s44
	ds_read_b128 v[202:205], v158 offset:49152
	ds_read_b128 v[206:209], v158 offset:50176
	ds_read_b128 v[210:213], v158 offset:51200
	ds_read_b128 v[214:217], v158 offset:52224
	ds_read_b128 v[218:221], v158 offset:53248
	ds_read_b128 v[222:225], v158 offset:54272
	ds_read_b128 v[226:229], v158 offset:55296
	ds_read_b128 v[230:233], v158 offset:56320
	global_load_lds_dwordx4 v[182:183], off
	s_add_i32 m0, s44, 0x2000
	s_add_u32 s42, s42, 0x40080
	v_lshl_add_u64 v[182:183], v[234:235], 0, s[16:17]
	s_addc_u32 s43, s43, 0
	s_add_i32 s44, s67, s46
	global_load_lds_dwordx4 v[182:183], off
	v_lshl_add_u64 v[182:183], s[42:43], 0, v[134:135]
	s_mov_b32 m0, s44
	s_nop 0
	global_load_lds_dwordx4 v[182:183], off
	v_lshl_add_u64 v[182:183], s[42:43], 0, v[130:131]
	s_add_i32 m0, s44, 0x2000
	s_nop 0
	global_load_lds_dwordx4 v[182:183], off
	v_lshl_add_u64 v[182:183], v[236:237], 0, s[16:17]
	s_mov_b32 m0, s54
	s_nop 0
	global_load_lds_dwordx4 v[182:183], off
	v_lshl_add_u64 v[182:183], v[238:239], 0, s[16:17]
	s_mov_b32 m0, s55
	s_nop 0
	global_load_lds_dwordx4 v[182:183], off
	s_waitcnt vmcnt(8)
	s_waitcnt lgkmcnt(0)
	s_nop 0
	s_barrier
	s_setprio 1
	v_mfma_f32_16x16x32_bf16 v[62:65], v[166:169], v[202:205], v[62:65]
	v_mfma_f32_16x16x32_bf16 v[54:57], v[174:177], v[202:205], v[54:57]
	v_mfma_f32_16x16x32_bf16 v[46:49], v[166:169], v[210:213], v[46:49]
	v_mfma_f32_16x16x32_bf16 v[38:41], v[174:177], v[210:213], v[38:41]
	v_mfma_f32_16x16x32_bf16 v[30:33], v[166:169], v[218:221], v[30:33]
	v_mfma_f32_16x16x32_bf16 v[22:25], v[174:177], v[218:221], v[22:25]
	v_mfma_f32_16x16x32_bf16 v[14:17], v[166:169], v[226:229], v[14:17]
	v_mfma_f32_16x16x32_bf16 v[6:9], v[174:177], v[226:229], v[6:9]
	v_mfma_f32_16x16x32_bf16 v[62:65], v[170:173], v[206:209], v[62:65]
	v_mfma_f32_16x16x32_bf16 v[54:57], v[178:181], v[206:209], v[54:57]
	v_mfma_f32_16x16x32_bf16 v[46:49], v[170:173], v[214:217], v[46:49]
	v_mfma_f32_16x16x32_bf16 v[38:41], v[178:181], v[214:217], v[38:41]
	v_mfma_f32_16x16x32_bf16 v[30:33], v[170:173], v[222:225], v[30:33]
	v_mfma_f32_16x16x32_bf16 v[22:25], v[178:181], v[222:225], v[22:25]
	v_mfma_f32_16x16x32_bf16 v[14:17], v[170:173], v[230:233], v[14:17]
	v_mfma_f32_16x16x32_bf16 v[6:9], v[178:181], v[230:233], v[6:9]
	v_mfma_f32_16x16x32_bf16 v[58:61], v[186:189], v[202:205], v[58:61]
	v_mfma_f32_16x16x32_bf16 v[50:53], v[194:197], v[202:205], v[50:53]
	v_mfma_f32_16x16x32_bf16 v[42:45], v[186:189], v[210:213], v[42:45]
	v_mfma_f32_16x16x32_bf16 v[34:37], v[194:197], v[210:213], v[34:37]
	v_mfma_f32_16x16x32_bf16 v[26:29], v[186:189], v[218:221], v[26:29]
	v_mfma_f32_16x16x32_bf16 v[18:21], v[194:197], v[218:221], v[18:21]
	v_mfma_f32_16x16x32_bf16 v[10:13], v[186:189], v[226:229], v[10:13]
	v_mfma_f32_16x16x32_bf16 v[2:5], v[194:197], v[226:229], v[2:5]
	v_mfma_f32_16x16x32_bf16 v[58:61], v[190:193], v[206:209], v[58:61]
	v_mfma_f32_16x16x32_bf16 v[50:53], v[198:201], v[206:209], v[50:53]
	v_mfma_f32_16x16x32_bf16 v[42:45], v[190:193], v[214:217], v[42:45]
	v_mfma_f32_16x16x32_bf16 v[34:37], v[198:201], v[214:217], v[34:37]
	v_mfma_f32_16x16x32_bf16 v[26:29], v[190:193], v[222:225], v[26:29]
	v_mfma_f32_16x16x32_bf16 v[18:21], v[198:201], v[222:225], v[18:21]
	v_mfma_f32_16x16x32_bf16 v[10:13], v[190:193], v[230:233], v[10:13]
	v_mfma_f32_16x16x32_bf16 v[2:5], v[198:201], v[230:233], v[2:5]
	s_setprio 0
	s_barrier
	s_add_i32 s65, s65, 2
	s_add_u32 s40, s40, 0x100
	s_addc_u32 s41, s41, 0
	s_add_u32 s63, s63, 0x100
	s_addc_u32 s64, s64, 0
	s_cmp_gt_u32 s65, 13
	s_cbranch_scc0 .LBB0_1234
	s_mov_b32 s99, 1
	s_and_b64 vcc, exec, s[18:19]
	s_cbranch_vccz .LBB0_1237
	s_barrier

;     DI bool next(int i, Unit& u) const { if (i > 0 || c >= 64) return false; u.pm = c & 31; u.pn = 0; u.src = c >> 5; return true; }
; #define PG8_STAGE(bufoff, gbase, voff) do { _Pragma("unroll") for (int _i = 0; _i < 2; ++_i) \
;         __builtin_amdgcn_global_load_lds((const unsigned*)((const char*)(gbase) + (voff)[_i]), (LAS unsigned*)(lds + (bufoff) + ldsw + _i * 8192), 16, 0, 0); } while (0)
; #define PG8_LDA(dst, b, h) do { _Pragma("unroll") for (int m = 0; m < 4; ++m) _Pragma("unroll") for (int k = 0; k < 2; ++k) dst[m][k] = *(const LAS bf16x8*)(lds + PG8_SA(b, h) + aoff + m * 2048 + k * 1024); } while (0)
; #define PG8_LDB(dst, b, h) do { _Pragma("unroll") for (int n = 0; n < 2; ++n) _Pragma("unroll") for (int k = 0; k < 2; ++k) dst[n][k] = *(const LAS bf16x8*)(lds + PG8_SB(b, h) + boff + n * 2048 + k * 1024); } while (0)
; #define PG8_WAIT_V(n) asm volatile("s_waitcnt vmcnt(" #n ")" ::: "memory")
; #define PG8_WAIT_L(n) asm volatile("s_waitcnt lgkmcnt(" #n ")" ::: "memory")
; #define PG8_BAR __builtin_amdgcn_s_barrier()
; template <class Epi, class Sched>
; DI void gemm_phase(LAS unsigned char* lds, const Gemm g, const Sched& S, const Epi& E) {
;     ...
;     for (;;) {
;         const bool has_next = S.next(ui + 1, nxt);
;         E.pre(pre, cur, wr, fr);
;         const char* nA = has_next ? (const char*)(nxt.src ? g.A1 : g.A0) + (size_t)nxt.pm * tstepA : cA; const char* nB = has_next ? (const char*)(nxt.src ? g.B1 : g.B0) + (size_t)nxt.pn * tstepB : cB;
;         for (int t = 0; t < nt; t += 2) {
;             const bool last = (t == nt - 2);
;             const char* a1 = cA + (size_t)(t + 1) * kstep;
;             const char* a2 = last ? nA : cA + (size_t)(t + 2) * kstep; const char* b2 = last ? nB : cB + (size_t)(t + 2) * kstep;
;             const char* a3 = a2 + kstep; const char* b3 = b2 + kstep;
;             PG8_LDB(B0, 0, 0); PG8_LDB(B1, 0, 1); PG8_SCHED; PG8_LDA(At, 0, 0); PG8_STAGE(PG8_SA(1, 1), a1 + hstepA, voffA);
;             PG8_WAIT_V(8); PG8_WAIT_L(0); PG8_BAR; PG8_MMA(0, 0, At, B0); PG8_MMA(0, 1, At, B1); PG8_BAR; PG8_SCHED;
;             PG8_LDA(At, 0, 1); PG8_STAGE(PG8_SB(0, 0), b2, voffB); PG8_STAGE(PG8_SB(0, 1), b2 + hstepB, voffB); PG8_STAGE(PG8_SA(0, 0), a2, voffA);
;             PG8_WAIT_V(8); PG8_WAIT_L(0); PG8_BAR; PG8_MMA(1, 0, At, B0); PG8_MMA(1, 1, At, B1); PG8_BAR; PG8_SCHED;
.Lpk6_w1:
	s_waitcnt lgkmcnt(0)
	s_nop 0
	s_barrier
	s_setprio 1
	v_mfma_f32_16x16x32_bf16 v[124:127], v[144:147], v[182:185], 0
	v_mfma_f32_16x16x32_bf16 v[120:123], v[158:161], v[182:185], 0
	v_mfma_f32_16x16x32_bf16 v[108:111], v[144:147], v[190:193], 0
	v_mfma_f32_16x16x32_bf16 v[104:107], v[158:161], v[190:193], 0
	v_mfma_f32_16x16x32_bf16 v[92:95], v[144:147], v[198:201], 0
	v_mfma_f32_16x16x32_bf16 v[88:91], v[158:161], v[198:201], 0
	v_mfma_f32_16x16x32_bf16 v[76:79], v[144:147], v[206:209], 0
	v_mfma_f32_16x16x32_bf16 v[72:75], v[158:161], v[206:209], 0
	v_mfma_f32_16x16x32_bf16 v[124:127], v[154:157], v[186:189], v[124:127]
	v_mfma_f32_16x16x32_bf16 v[120:123], v[162:165], v[186:189], v[120:123]
	v_mfma_f32_16x16x32_bf16 v[108:111], v[154:157], v[194:197], v[108:111]
	v_mfma_f32_16x16x32_bf16 v[104:107], v[162:165], v[194:197], v[104:107]
	v_mfma_f32_16x16x32_bf16 v[92:95], v[154:157], v[202:205], v[92:95]
	v_mfma_f32_16x16x32_bf16 v[88:91], v[162:165], v[202:205], v[88:91]
	v_mfma_f32_16x16x32_bf16 v[76:79], v[154:157], v[210:213], v[76:79]
	v_mfma_f32_16x16x32_bf16 v[72:75], v[162:165], v[210:213], v[72:75]
	v_mfma_f32_16x16x32_bf16 v[116:119], v[166:169], v[182:185], 0
	v_mfma_f32_16x16x32_bf16 v[112:115], v[174:177], v[182:185], 0
	v_mfma_f32_16x16x32_bf16 v[100:103], v[166:169], v[190:193], 0
	v_mfma_f32_16x16x32_bf16 v[96:99], v[174:177], v[190:193], 0
	v_mfma_f32_16x16x32_bf16 v[84:87], v[166:169], v[198:201], 0
	v_mfma_f32_16x16x32_bf16 v[80:83], v[174:177], v[198:201], 0
	v_mfma_f32_16x16x32_bf16 v[68:71], v[166:169], v[206:209], 0
	v_mfma_f32_16x16x32_bf16 v[64:67], v[174:177], v[206:209], 0
	v_mfma_f32_16x16x32_bf16 v[116:119], v[170:173], v[186:189], v[116:119]
	v_mfma_f32_16x16x32_bf16 v[112:115], v[178:181], v[186:189], v[112:115]
	v_mfma_f32_16x16x32_bf16 v[100:103], v[170:173], v[194:197], v[100:103]
	v_mfma_f32_16x16x32_bf16 v[96:99], v[178:181], v[194:197], v[96:99]
	v_mfma_f32_16x16x32_bf16 v[84:87], v[170:173], v[202:205], v[84:87]
	v_mfma_f32_16x16x32_bf16 v[80:83], v[178:181], v[202:205], v[80:83]
	v_mfma_f32_16x16x32_bf16 v[68:71], v[170:173], v[210:213], v[68:71]
	v_mfma_f32_16x16x32_bf16 v[64:67], v[178:181], v[210:213], v[64:67]
	s_setprio 0
	s_barrier
	s_add_i32 s48, s39, s27
	v_lshl_add_u64 v[214:215], s[18:19], 0, v[130:131]
	s_mov_b32 m0, s48
	ds_read_b128 v[182:185], v153 offset:16384
	ds_read_b128 v[186:189], v153 offset:17408
	ds_read_b128 v[190:193], v153 offset:18432
	ds_read_b128 v[194:197], v153 offset:19456
	ds_read_b128 v[198:201], v153 offset:20480
	ds_read_b128 v[202:205], v153 offset:21504
	ds_read_b128 v[206:209], v153 offset:22528
	ds_read_b128 v[210:213], v153 offset:23552
	global_load_lds_dwordx4 v[214:215], off
	s_add_i32 m0, s48, 0x2000
	s_add_u32 s48, s18, 0xb0000
	v_lshl_add_u64 v[216:217], s[18:19], 0, v[134:135]
	s_addc_u32 s49, s19, 0
	s_add_i32 s50, s40, s27
	global_load_lds_dwordx4 v[216:217], off
	v_lshl_add_u64 v[218:219], s[48:49], 0, v[130:131]
	s_mov_b32 m0, s50
	v_lshl_add_u64 v[220:221], s[20:21], 0, v[132:133]
	global_load_lds_dwordx4 v[218:219], off
	v_lshl_add_u64 v[218:219], s[48:49], 0, v[134:135]
	s_add_i32 m0, s50, 0x2000
	s_nop 0
	global_load_lds_dwordx4 v[218:219], off
	v_lshl_add_u64 v[218:219], s[20:21], 0, v[128:129]
	s_mov_b32 m0, s28
	s_nop 0
	global_load_lds_dwordx4 v[218:219], off
	s_mov_b32 m0, s29
	s_nop 0
	global_load_lds_dwordx4 v[220:221], off
	s_cmp_lg_u32 s99, 0
	s_cbranch_scc1 .Lpk6_w2
	s_waitcnt vmcnt(8)
.Lpk6_w2:
	s_mov_b32 s99, 0
	s_waitcnt lgkmcnt(0)
	s_nop 0
	s_barrier
	s_setprio 1
	v_mfma_f32_16x16x32_bf16 v[60:63], v[144:147], v[182:185], 0
	v_mfma_f32_16x16x32_bf16 v[56:59], v[158:161], v[182:185], 0
	v_mfma_f32_16x16x32_bf16 v[44:47], v[144:147], v[190:193], 0
	v_mfma_f32_16x16x32_bf16 v[40:43], v[158:161], v[190:193], 0
	v_mfma_f32_16x16x32_bf16 v[28:31], v[144:147], v[198:201], 0
	v_mfma_f32_16x16x32_bf16 v[24:27], v[158:161], v[198:201], 0
	v_mfma_f32_16x16x32_bf16 v[12:15], v[144:147], v[206:209], 0
	v_mfma_f32_16x16x32_bf16 v[8:11], v[158:161], v[206:209], 0
	v_mfma_f32_16x16x32_bf16 v[60:63], v[154:157], v[186:189], v[60:63]
	v_mfma_f32_16x16x32_bf16 v[56:59], v[162:165], v[186:189], v[56:59]
	v_mfma_f32_16x16x32_bf16 v[44:47], v[154:157], v[194:197], v[44:47]
	v_mfma_f32_16x16x32_bf16 v[40:43], v[162:165], v[194:197], v[40:43]
	v_mfma_f32_16x16x32_bf16 v[28:31], v[154:157], v[202:205], v[28:31]
	v_mfma_f32_16x16x32_bf16 v[24:27], v[162:165], v[202:205], v[24:27]
	v_mfma_f32_16x16x32_bf16 v[12:15], v[154:157], v[210:213], v[12:15]
	v_mfma_f32_16x16x32_bf16 v[8:11], v[162:165], v[210:213], v[8:11]
	v_mfma_f32_16x16x32_bf16 v[52:55], v[166:169], v[182:185], 0
	v_mfma_f32_16x16x32_bf16 v[48:51], v[174:177], v[182:185], 0
	v_mfma_f32_16x16x32_bf16 v[36:39], v[166:169], v[190:193], 0
	v_mfma_f32_16x16x32_bf16 v[32:35], v[174:177], v[190:193], 0
	v_mfma_f32_16x16x32_bf16 v[20:23], v[166:169], v[198:201], 0
	v_mfma_f32_16x16x32_bf16 v[16:19], v[174:177], v[198:201], 0
	v_mfma_f32_16x16x32_bf16 v[4:7], v[166:169], v[206:209], 0
	v_mfma_f32_16x16x32_bf16 v[0:3], v[174:177], v[206:209], 0
	v_mfma_f32_16x16x32_bf16 v[52:55], v[170:173], v[186:189], v[52:55]
	v_mfma_f32_16x16x32_bf16 v[48:51], v[178:181], v[186:189], v[48:51]
	v_mfma_f32_16x16x32_bf16 v[36:39], v[170:173], v[194:197], v[36:39]
	v_mfma_f32_16x16x32_bf16 v[32:35], v[178:181], v[194:197], v[32:35]
	v_mfma_f32_16x16x32_bf16 v[20:23], v[170:173], v[202:205], v[20:23]
	v_mfma_f32_16x16x32_bf16 v[16:19], v[178:181], v[202:205], v[16:19]
	v_mfma_f32_16x16x32_bf16 v[4:7], v[170:173], v[210:213], v[4:7]
	v_mfma_f32_16x16x32_bf16 v[0:3], v[178:181], v[210:213], v[0:3]
	s_setprio 0
	s_barrier
; #define PG8_STAGE(bufoff, gbase, voff) do { _Pragma("unroll") for (int _i = 0; _i < 2; ++_i) \
;         __builtin_amdgcn_global_load_lds((const unsigned*)((const char*)(gbase) + (voff)[_i]), (LAS unsigned*)(lds + (bufoff) + ldsw + _i * 8192), 16, 0, 0); } while (0)
; #define PG8_LDA(dst, b, h) do { _Pragma("unroll") for (int m = 0; m < 4; ++m) _Pragma("unroll") for (int k = 0; k < 2; ++k) dst[m][k] = *(const LAS bf16x8*)(lds + PG8_SA(b, h) + aoff + m * 2048 + k * 1024); } while (0)
; #define PG8_LDB(dst, b, h) do { _Pragma("unroll") for (int n = 0; n < 2; ++n) _Pragma("unroll") for (int k = 0; k < 2; ++k) dst[n][k] = *(const LAS bf16x8*)(lds + PG8_SB(b, h) + boff + n * 2048 + k * 1024); } while (0)
; #define PG8_MMA(ai, bj, At, Bt) do { __builtin_amdgcn_s_setprio(1); _Pragma("unroll") for (int m = 0; m < 4; ++m) _Pragma("unroll") for (int n = 0; n < 2; ++n) _Pragma("unroll") for (int k = 0; k < 2; ++k) \
;         acc[ai][bj][m][n] = __builtin_amdgcn_mfma_f32_16x16x32_bf16(Bt[n][k], At[m][k], acc[ai][bj][m][n], 0, 0, 0); __builtin_amdgcn_s_setprio(0); } while (0)
; #define PG8_WAIT_V(n) asm volatile("s_waitcnt vmcnt(" #n ")" ::: "memory")
; #define PG8_WAIT_L(n) asm volatile("s_waitcnt lgkmcnt(" #n ")" ::: "memory")
; #define PG8_BAR __builtin_amdgcn_s_barrier()
; #define PG8_SCHED __builtin_amdgcn_sched_barrier(0)
; template <class Epi, class Sched>
; DI void gemm_phase(LAS unsigned char* lds, const Gemm g, const Sched& S, const Epi& E) {
;     ...
;         for (int t = 0; t < nt; t += 2) {
;     ...
;             PG8_LDB(B0, 1, 0); PG8_LDB(B1, 1, 1); PG8_SCHED; PG8_LDA(At, 1, 0); PG8_STAGE(PG8_SA(0, 1), a2 + hstepA, voffA);
;             PG8_WAIT_V(8); PG8_WAIT_L(0); PG8_BAR; PG8_MMA(0, 0, At, B0); PG8_MMA(0, 1, At, B1); PG8_BAR; PG8_SCHED;
;             PG8_LDA(At, 1, 1); PG8_STAGE(PG8_SB(1, 0), b3, voffB); PG8_STAGE(PG8_SB(1, 1), b3 + hstepB, voffB); PG8_STAGE(PG8_SA(1, 0), a3, voffA);
;             PG8_WAIT_V(8); PG8_WAIT_L(0); PG8_BAR; PG8_MMA(1, 0, At, B0); PG8_MMA(1, 1, At, B1); PG8_BAR; PG8_SCHED;
	s_add_i32 s48, 0, 0x18000
	s_add_i32 s49, 0, 0x1c000
	v_add_u32_e32 v162, s48, v149
	v_add_u32_e32 v178, s49, v149
	ds_read_b128 v[144:147], v162
	ds_read_b128 v[154:157], v162 offset:1024
	ds_read_b128 v[158:161], v162 offset:2048
	ds_read_b128 v[162:165], v162 offset:3072
	ds_read_b128 v[166:169], v178
	ds_read_b128 v[170:173], v178 offset:1024
	ds_read_b128 v[174:177], v178 offset:2048
	ds_read_b128 v[178:181], v178 offset:3072
	s_add_u32 s20, s20, 0xb0000
	s_addc_u32 s21, s21, 0
	s_mov_b32 m0, s33
	v_lshl_add_u64 v[222:223], s[20:21], 0, v[128:129]
	ds_read_b128 v[182:185], v153 offset:32768
	ds_read_b128 v[186:189], v153 offset:33792
	ds_read_b128 v[190:193], v153 offset:34816
	ds_read_b128 v[194:197], v153 offset:35840
	ds_read_b128 v[198:201], v153 offset:36864
	ds_read_b128 v[202:205], v153 offset:37888
	ds_read_b128 v[206:209], v153 offset:38912
	ds_read_b128 v[210:213], v153 offset:39936
	global_load_lds_dwordx4 v[222:223], off
	v_lshl_add_u64 v[222:223], s[20:21], 0, v[132:133]
	s_mov_b32 m0, s34
	s_nop 0
	global_load_lds_dwordx4 v[222:223], off
	s_waitcnt vmcnt(8)
	s_waitcnt lgkmcnt(0)
	s_barrier
	s_setprio 1
	v_mfma_f32_16x16x32_bf16 v[124:127], v[144:147], v[182:185], v[124:127]
	v_mfma_f32_16x16x32_bf16 v[120:123], v[158:161], v[182:185], v[120:123]
	v_mfma_f32_16x16x32_bf16 v[108:111], v[144:147], v[190:193], v[108:111]
	v_mfma_f32_16x16x32_bf16 v[104:107], v[158:161], v[190:193], v[104:107]
	v_mfma_f32_16x16x32_bf16 v[92:95], v[144:147], v[198:201], v[92:95]
	v_mfma_f32_16x16x32_bf16 v[88:91], v[158:161], v[198:201], v[88:91]
	v_mfma_f32_16x16x32_bf16 v[76:79], v[144:147], v[206:209], v[76:79]
	v_mfma_f32_16x16x32_bf16 v[72:75], v[158:161], v[206:209], v[72:75]
	v_mfma_f32_16x16x32_bf16 v[124:127], v[154:157], v[186:189], v[124:127]
	v_mfma_f32_16x16x32_bf16 v[120:123], v[162:165], v[186:189], v[120:123]
	v_mfma_f32_16x16x32_bf16 v[108:111], v[154:157], v[194:197], v[108:111]
	v_mfma_f32_16x16x32_bf16 v[104:107], v[162:165], v[194:197], v[104:107]
	v_mfma_f32_16x16x32_bf16 v[92:95], v[154:157], v[202:205], v[92:95]
	v_mfma_f32_16x16x32_bf16 v[88:91], v[162:165], v[202:205], v[88:91]
	v_mfma_f32_16x16x32_bf16 v[76:79], v[154:157], v[210:213], v[76:79]
	v_mfma_f32_16x16x32_bf16 v[72:75], v[162:165], v[210:213], v[72:75]
	v_mfma_f32_16x16x32_bf16 v[116:119], v[166:169], v[182:185], v[116:119]
	v_mfma_f32_16x16x32_bf16 v[112:115], v[174:177], v[182:185], v[112:115]
	v_mfma_f32_16x16x32_bf16 v[100:103], v[166:169], v[190:193], v[100:103]
	v_mfma_f32_16x16x32_bf16 v[96:99], v[174:177], v[190:193], v[96:99]
	v_mfma_f32_16x16x32_bf16 v[84:87], v[166:169], v[198:201], v[84:87]
	v_mfma_f32_16x16x32_bf16 v[80:83], v[174:177], v[198:201], v[80:83]
	v_mfma_f32_16x16x32_bf16 v[68:71], v[166:169], v[206:209], v[68:71]
	v_mfma_f32_16x16x32_bf16 v[64:67], v[174:177], v[206:209], v[64:67]
	v_mfma_f32_16x16x32_bf16 v[116:119], v[170:173], v[186:189], v[116:119]
	v_mfma_f32_16x16x32_bf16 v[112:115], v[178:181], v[186:189], v[112:115]
	v_mfma_f32_16x16x32_bf16 v[100:103], v[170:173], v[194:197], v[100:103]
	v_mfma_f32_16x16x32_bf16 v[96:99], v[178:181], v[194:197], v[96:99]
	v_mfma_f32_16x16x32_bf16 v[84:87], v[170:173], v[202:205], v[84:87]
	v_mfma_f32_16x16x32_bf16 v[80:83], v[178:181], v[202:205], v[80:83]
	v_mfma_f32_16x16x32_bf16 v[68:71], v[170:173], v[210:213], v[68:71]
	v_mfma_f32_16x16x32_bf16 v[64:67], v[178:181], v[210:213], v[64:67]
	s_setprio 0
	s_barrier
	s_add_i32 s20, s48, s27
	v_lshl_add_u64 v[214:215], v[214:215], 0, s[10:11]
	s_mov_b32 m0, s20
	ds_read_b128 v[182:185], v153 offset:49152
	ds_read_b128 v[186:189], v153 offset:50176
	ds_read_b128 v[190:193], v153 offset:51200
	ds_read_b128 v[194:197], v153 offset:52224
	ds_read_b128 v[198:201], v153 offset:53248
	ds_read_b128 v[202:205], v153 offset:54272
	ds_read_b128 v[206:209], v153 offset:55296
	ds_read_b128 v[210:213], v153 offset:56320
	global_load_lds_dwordx4 v[214:215], off
	s_add_i32 m0, s20, 0x2000
	s_add_u32 s18, s18, 0xb0080
	v_lshl_add_u64 v[214:215], v[216:217], 0, s[10:11]
	s_addc_u32 s19, s19, 0
	s_add_i32 s20, s49, s27
	global_load_lds_dwordx4 v[214:215], off
	v_lshl_add_u64 v[214:215], s[18:19], 0, v[130:131]
	s_mov_b32 m0, s20
	s_nop 0
	global_load_lds_dwordx4 v[214:215], off
	v_lshl_add_u64 v[214:215], s[18:19], 0, v[134:135]
	s_add_i32 m0, s20, 0x2000
	s_nop 0
	global_load_lds_dwordx4 v[214:215], off
	v_lshl_add_u64 v[214:215], v[218:219], 0, s[10:11]
	s_mov_b32 m0, s36
	s_nop 0
	global_load_lds_dwordx4 v[214:215], off
	v_lshl_add_u64 v[214:215], v[220:221], 0, s[10:11]
	s_mov_b32 m0, s37
	s_nop 0
	global_load_lds_dwordx4 v[214:215], off
	s_waitcnt vmcnt(8)
	s_waitcnt lgkmcnt(0)
	s_nop 0
	s_barrier
	s_setprio 1
	v_mfma_f32_16x16x32_bf16 v[60:63], v[144:147], v[182:185], v[60:63]
	v_mfma_f32_16x16x32_bf16 v[56:59], v[158:161], v[182:185], v[56:59]
	v_mfma_f32_16x16x32_bf16 v[44:47], v[144:147], v[190:193], v[44:47]
	v_mfma_f32_16x16x32_bf16 v[40:43], v[158:161], v[190:193], v[40:43]
	v_mfma_f32_16x16x32_bf16 v[28:31], v[144:147], v[198:201], v[28:31]
	v_mfma_f32_16x16x32_bf16 v[24:27], v[158:161], v[198:201], v[24:27]
	v_mfma_f32_16x16x32_bf16 v[12:15], v[144:147], v[206:209], v[12:15]
	v_mfma_f32_16x16x32_bf16 v[8:11], v[158:161], v[206:209], v[8:11]
	v_mfma_f32_16x16x32_bf16 v[60:63], v[154:157], v[186:189], v[60:63]
	v_mfma_f32_16x16x32_bf16 v[56:59], v[162:165], v[186:189], v[56:59]
	v_mfma_f32_16x16x32_bf16 v[44:47], v[154:157], v[194:197], v[44:47]
	v_mfma_f32_16x16x32_bf16 v[40:43], v[162:165], v[194:197], v[40:43]
	v_mfma_f32_16x16x32_bf16 v[28:31], v[154:157], v[202:205], v[28:31]
	v_mfma_f32_16x16x32_bf16 v[24:27], v[162:165], v[202:205], v[24:27]
	v_mfma_f32_16x16x32_bf16 v[12:15], v[154:157], v[210:213], v[12:15]
	v_mfma_f32_16x16x32_bf16 v[8:11], v[162:165], v[210:213], v[8:11]
	v_mfma_f32_16x16x32_bf16 v[52:55], v[166:169], v[182:185], v[52:55]
	v_mfma_f32_16x16x32_bf16 v[48:51], v[174:177], v[182:185], v[48:51]
	v_mfma_f32_16x16x32_bf16 v[36:39], v[166:169], v[190:193], v[36:39]
	v_mfma_f32_16x16x32_bf16 v[32:35], v[174:177], v[190:193], v[32:35]
	v_mfma_f32_16x16x32_bf16 v[20:23], v[166:169], v[198:201], v[20:23]
	v_mfma_f32_16x16x32_bf16 v[16:19], v[174:177], v[198:201], v[16:19]
	v_mfma_f32_16x16x32_bf16 v[4:7], v[166:169], v[206:209], v[4:7]
	v_mfma_f32_16x16x32_bf16 v[0:3], v[174:177], v[206:209], v[0:3]
	v_mfma_f32_16x16x32_bf16 v[52:55], v[170:173], v[186:189], v[52:55]
	v_mfma_f32_16x16x32_bf16 v[48:51], v[178:181], v[186:189], v[48:51]
	v_mfma_f32_16x16x32_bf16 v[36:39], v[170:173], v[194:197], v[36:39]
	v_mfma_f32_16x16x32_bf16 v[32:35], v[178:181], v[194:197], v[32:35]
	v_mfma_f32_16x16x32_bf16 v[20:23], v[170:173], v[202:205], v[20:23]
	v_mfma_f32_16x16x32_bf16 v[16:19], v[178:181], v[202:205], v[16:19]
	v_mfma_f32_16x16x32_bf16 v[4:7], v[170:173], v[210:213], v[4:7]
	v_mfma_f32_16x16x32_bf16 v[0:3], v[178:181], v[210:213], v[0:3]
	s_setprio 0
	s_barrier
	s_add_i32 s47, s47, 2
	s_add_u32 s16, s16, 0x100
	s_addc_u32 s17, s17, 0
	s_add_u32 s45, s45, 0x100
	s_addc_u32 s46, s46, 0
	s_cmp_gt_u32 s47, 41
; #define PG8_STAGE(bufoff, gbase, voff) do { _Pragma("unroll") for (int _i = 0; _i < 2; ++_i) \
;         __builtin_amdgcn_global_load_lds((const unsigned*)((const char*)(gbase) + (voff)[_i]), (LAS unsigned*)(lds + (bufoff) + ldsw + _i * 8192), 16, 0, 0); } while (0)
; #define PG8_LDA(dst, b, h) do { _Pragma("unroll") for (int m = 0; m < 4; ++m) _Pragma("unroll") for (int k = 0; k < 2; ++k) dst[m][k] = *(const LAS bf16x8*)(lds + PG8_SA(b, h) + aoff + m * 2048 + k * 1024); } while (0)
; #define PG8_LDB(dst, b, h) do { _Pragma("unroll") for (int n = 0; n < 2; ++n) _Pragma("unroll") for (int k = 0; k < 2; ++k) dst[n][k] = *(const LAS bf16x8*)(lds + PG8_SB(b, h) + boff + n * 2048 + k * 1024); } while (0)
; #define PG8_MMA(ai, bj, At, Bt) do { __builtin_amdgcn_s_setprio(1); _Pragma("unroll") for (int m = 0; m < 4; ++m) _Pragma("unroll") for (int n = 0; n < 2; ++n) _Pragma("unroll") for (int k = 0; k < 2; ++k) \
;         acc[ai][bj][m][n] = __builtin_amdgcn_mfma_f32_16x16x32_bf16(Bt[n][k], At[m][k], acc[ai][bj][m][n], 0, 0, 0); __builtin_amdgcn_s_setprio(0); } while (0)
; #define PG8_WAIT_V(n) asm volatile("s_waitcnt vmcnt(" #n ")" ::: "memory")
; #define PG8_WAIT_L(n) asm volatile("s_waitcnt lgkmcnt(" #n ")" ::: "memory")
; #define PG8_BAR __builtin_amdgcn_s_barrier()
; #define PG8_SCHED __builtin_amdgcn_sched_barrier(0)
; template <class Epi, class Sched>
; DI void gemm_phase(LAS unsigned char* lds, const Gemm g, const Sched& S, const Epi& E) {
;     ...
;         for (int t = 0; t < nt; t += 2) {
;             const bool last = (t == nt - 2);
;             const char* a1 = cA + (size_t)(t + 1) * kstep;
;             const char* a2 = last ? nA : cA + (size_t)(t + 2) * kstep; const char* b2 = last ? nB : cB + (size_t)(t + 2) * kstep;
;             const char* a3 = a2 + kstep; const char* b3 = b2 + kstep;
;             PG8_LDB(B0, 0, 0); PG8_LDB(B1, 0, 1); PG8_SCHED; PG8_LDA(At, 0, 0); PG8_STAGE(PG8_SA(1, 1), a1 + hstepA, voffA);
;             PG8_WAIT_V(8); PG8_WAIT_L(0); PG8_BAR; PG8_MMA(0, 0, At, B0); PG8_MMA(0, 1, At, B1); PG8_BAR; PG8_SCHED;
;             PG8_LDA(At, 0, 1); PG8_STAGE(PG8_SB(0, 0), b2, voffB); PG8_STAGE(PG8_SB(0, 1), b2 + hstepB, voffB); PG8_STAGE(PG8_SA(0, 0), a2, voffA);
;             PG8_WAIT_V(8); PG8_WAIT_L(0); PG8_BAR; PG8_MMA(1, 0, At, B0); PG8_MMA(1, 1, At, B1); PG8_BAR; PG8_SCHED;
.LBB0_1331:
	ds_read_b128 v[144:147], v151
	ds_read_b128 v[154:157], v151 offset:1024
	ds_read_b128 v[158:161], v151 offset:2048
	ds_read_b128 v[162:165], v151 offset:3072
	ds_read_b128 v[166:169], v152
	ds_read_b128 v[170:173], v152 offset:1024
	ds_read_b128 v[174:177], v152 offset:2048
	ds_read_b128 v[178:181], v152 offset:3072
	s_add_u32 s18, s16, 0xfff50080
	s_addc_u32 s19, s17, -1
	s_cmp_eq_u32 s47, 40
	s_cselect_b32 s21, s5, s19
	s_cselect_b32 s20, s4, s18
	s_cselect_b32 s19, s15, s46
	s_cselect_b32 s18, s14, s45
	v_lshl_add_u64 v[214:215], s[16:17], 0, v[136:137]
	s_add_i32 m0, s28, 0xc000
	ds_read_b128 v[182:185], v153
	ds_read_b128 v[186:189], v153 offset:1024
	ds_read_b128 v[190:193], v153 offset:2048
	ds_read_b128 v[194:197], v153 offset:3072
	ds_read_b128 v[198:201], v153 offset:4096
	ds_read_b128 v[202:205], v153 offset:5120
	ds_read_b128 v[206:209], v153 offset:6144
	ds_read_b128 v[210:213], v153 offset:7168
	global_load_lds_dwordx4 v[214:215], off
	v_lshl_add_u64 v[214:215], s[16:17], 0, v[138:139]
	s_add_i32 m0, s28, 0xe000
	s_nop 0
	global_load_lds_dwordx4 v[214:215], off
	s_waitcnt vmcnt(8)
	s_waitcnt lgkmcnt(0)
	s_nop 0
	s_barrier
	s_setprio 1
	v_mfma_f32_16x16x32_bf16 v[124:127], v[144:147], v[182:185], v[124:127]
	v_mfma_f32_16x16x32_bf16 v[120:123], v[158:161], v[182:185], v[120:123]
	v_mfma_f32_16x16x32_bf16 v[108:111], v[144:147], v[190:193], v[108:111]
	v_mfma_f32_16x16x32_bf16 v[104:107], v[158:161], v[190:193], v[104:107]
	v_mfma_f32_16x16x32_bf16 v[92:95], v[144:147], v[198:201], v[92:95]
	v_mfma_f32_16x16x32_bf16 v[88:91], v[158:161], v[198:201], v[88:91]
	v_mfma_f32_16x16x32_bf16 v[76:79], v[144:147], v[206:209], v[76:79]
	v_mfma_f32_16x16x32_bf16 v[72:75], v[158:161], v[206:209], v[72:75]
	v_mfma_f32_16x16x32_bf16 v[124:127], v[154:157], v[186:189], v[124:127]
	v_mfma_f32_16x16x32_bf16 v[120:123], v[162:165], v[186:189], v[120:123]
	v_mfma_f32_16x16x32_bf16 v[108:111], v[154:157], v[194:197], v[108:111]
	v_mfma_f32_16x16x32_bf16 v[104:107], v[162:165], v[194:197], v[104:107]
	v_mfma_f32_16x16x32_bf16 v[92:95], v[154:157], v[202:205], v[92:95]
	v_mfma_f32_16x16x32_bf16 v[88:91], v[162:165], v[202:205], v[88:91]
	v_mfma_f32_16x16x32_bf16 v[76:79], v[154:157], v[210:213], v[76:79]
	v_mfma_f32_16x16x32_bf16 v[72:75], v[162:165], v[210:213], v[72:75]
	v_mfma_f32_16x16x32_bf16 v[116:119], v[166:169], v[182:185], v[116:119]
	v_mfma_f32_16x16x32_bf16 v[112:115], v[174:177], v[182:185], v[112:115]
	v_mfma_f32_16x16x32_bf16 v[100:103], v[166:169], v[190:193], v[100:103]
	v_mfma_f32_16x16x32_bf16 v[96:99], v[174:177], v[190:193], v[96:99]
	v_mfma_f32_16x16x32_bf16 v[84:87], v[166:169], v[198:201], v[84:87]
	v_mfma_f32_16x16x32_bf16 v[80:83], v[174:177], v[198:201], v[80:83]
	v_mfma_f32_16x16x32_bf16 v[68:71], v[166:169], v[206:209], v[68:71]
	v_mfma_f32_16x16x32_bf16 v[64:67], v[174:177], v[206:209], v[64:67]
	v_mfma_f32_16x16x32_bf16 v[116:119], v[170:173], v[186:189], v[116:119]
	v_mfma_f32_16x16x32_bf16 v[112:115], v[178:181], v[186:189], v[112:115]
	v_mfma_f32_16x16x32_bf16 v[100:103], v[170:173], v[194:197], v[100:103]
	v_mfma_f32_16x16x32_bf16 v[96:99], v[178:181], v[194:197], v[96:99]
	v_mfma_f32_16x16x32_bf16 v[84:87], v[170:173], v[202:205], v[84:87]
	v_mfma_f32_16x16x32_bf16 v[80:83], v[178:181], v[202:205], v[80:83]
	v_mfma_f32_16x16x32_bf16 v[68:71], v[170:173], v[210:213], v[68:71]
	v_mfma_f32_16x16x32_bf16 v[64:67], v[178:181], v[210:213], v[64:67]
	s_setprio 0
	s_barrier
	s_add_i32 s48, s39, s27
	v_lshl_add_u64 v[214:215], s[18:19], 0, v[130:131]
	s_mov_b32 m0, s48
	ds_read_b128 v[182:185], v153 offset:16384
	ds_read_b128 v[186:189], v153 offset:17408
	ds_read_b128 v[190:193], v153 offset:18432
	ds_read_b128 v[194:197], v153 offset:19456
	ds_read_b128 v[198:201], v153 offset:20480
	ds_read_b128 v[202:205], v153 offset:21504
	ds_read_b128 v[206:209], v153 offset:22528
	ds_read_b128 v[210:213], v153 offset:23552
	global_load_lds_dwordx4 v[214:215], off
	s_add_i32 m0, s48, 0x2000
	s_add_u32 s48, s18, 0xb0000
	v_lshl_add_u64 v[216:217], s[18:19], 0, v[134:135]
	s_addc_u32 s49, s19, 0
	s_add_i32 s50, s40, s27
	global_load_lds_dwordx4 v[216:217], off
	v_lshl_add_u64 v[218:219], s[48:49], 0, v[130:131]
	s_mov_b32 m0, s50
	v_lshl_add_u64 v[220:221], s[20:21], 0, v[132:133]
	global_load_lds_dwordx4 v[218:219], off
	v_lshl_add_u64 v[218:219], s[48:49], 0, v[134:135]
	s_add_i32 m0, s50, 0x2000
	s_nop 0
	global_load_lds_dwordx4 v[218:219], off
	v_lshl_add_u64 v[218:219], s[20:21], 0, v[128:129]
	s_mov_b32 m0, s28
	s_nop 0
	global_load_lds_dwordx4 v[218:219], off
	s_mov_b32 m0, s29
	s_nop 0
	global_load_lds_dwordx4 v[220:221], off
	s_waitcnt vmcnt(8)
	s_waitcnt lgkmcnt(0)
	s_barrier
; #define PG8_STAGE(bufoff, gbase, voff) do { _Pragma("unroll") for (int _i = 0; _i < 2; ++_i) \
;         __builtin_amdgcn_global_load_lds((const unsigned*)((const char*)(gbase) + (voff)[_i]), (LAS unsigned*)(lds + (bufoff) + ldsw + _i * 8192), 16, 0, 0); } while (0)
; #define PG8_LDA(dst, b, h) do { _Pragma("unroll") for (int m = 0; m < 4; ++m) _Pragma("unroll") for (int k = 0; k < 2; ++k) dst[m][k] = *(const LAS bf16x8*)(lds + PG8_SA(b, h) + aoff + m * 2048 + k * 1024); } while (0)
; #define PG8_LDB(dst, b, h) do { _Pragma("unroll") for (int n = 0; n < 2; ++n) _Pragma("unroll") for (int k = 0; k < 2; ++k) dst[n][k] = *(const LAS bf16x8*)(lds + PG8_SB(b, h) + boff + n * 2048 + k * 1024); } while (0)
; #define PG8_MMA(ai, bj, At, Bt) do { __builtin_amdgcn_s_setprio(1); _Pragma("unroll") for (int m = 0; m < 4; ++m) _Pragma("unroll") for (int n = 0; n < 2; ++n) _Pragma("unroll") for (int k = 0; k < 2; ++k) \
;         acc[ai][bj][m][n] = __builtin_amdgcn_mfma_f32_16x16x32_bf16(Bt[n][k], At[m][k], acc[ai][bj][m][n], 0, 0, 0); __builtin_amdgcn_s_setprio(0); } while (0)
; #define PG8_WAIT_V(n) asm volatile("s_waitcnt vmcnt(" #n ")" ::: "memory")
; #define PG8_WAIT_L(n) asm volatile("s_waitcnt lgkmcnt(" #n ")" ::: "memory")
; #define PG8_BAR __builtin_amdgcn_s_barrier()
; #define PG8_SCHED __builtin_amdgcn_sched_barrier(0)
; template <class Epi, class Sched>
; DI void gemm_phase(LAS unsigned char* lds, const Gemm g, const Sched& S, const Epi& E) {
;     ...
;             PG8_WAIT_V(8); PG8_WAIT_L(0); PG8_BAR; PG8_MMA(1, 0, At, B0); PG8_MMA(1, 1, At, B1); PG8_BAR; PG8_SCHED;
;             PG8_LDB(B0, 1, 0); PG8_LDB(B1, 1, 1); PG8_SCHED; PG8_LDA(At, 1, 0); PG8_STAGE(PG8_SA(0, 1), a2 + hstepA, voffA);
;             PG8_WAIT_V(8); PG8_WAIT_L(0); PG8_BAR; PG8_MMA(0, 0, At, B0); PG8_MMA(0, 1, At, B1); PG8_BAR; PG8_SCHED;
	s_setprio 1
	v_mfma_f32_16x16x32_bf16 v[60:63], v[144:147], v[182:185], v[60:63]
	v_mfma_f32_16x16x32_bf16 v[56:59], v[158:161], v[182:185], v[56:59]
	v_mfma_f32_16x16x32_bf16 v[44:47], v[144:147], v[190:193], v[44:47]
	v_mfma_f32_16x16x32_bf16 v[40:43], v[158:161], v[190:193], v[40:43]
	v_mfma_f32_16x16x32_bf16 v[28:31], v[144:147], v[198:201], v[28:31]
	v_mfma_f32_16x16x32_bf16 v[24:27], v[158:161], v[198:201], v[24:27]
	v_mfma_f32_16x16x32_bf16 v[12:15], v[144:147], v[206:209], v[12:15]
	v_mfma_f32_16x16x32_bf16 v[8:11], v[158:161], v[206:209], v[8:11]
	v_mfma_f32_16x16x32_bf16 v[60:63], v[154:157], v[186:189], v[60:63]
	v_mfma_f32_16x16x32_bf16 v[56:59], v[162:165], v[186:189], v[56:59]
	v_mfma_f32_16x16x32_bf16 v[44:47], v[154:157], v[194:197], v[44:47]
	v_mfma_f32_16x16x32_bf16 v[40:43], v[162:165], v[194:197], v[40:43]
	v_mfma_f32_16x16x32_bf16 v[28:31], v[154:157], v[202:205], v[28:31]
	v_mfma_f32_16x16x32_bf16 v[24:27], v[162:165], v[202:205], v[24:27]
	v_mfma_f32_16x16x32_bf16 v[12:15], v[154:157], v[210:213], v[12:15]
	v_mfma_f32_16x16x32_bf16 v[8:11], v[162:165], v[210:213], v[8:11]
	v_mfma_f32_16x16x32_bf16 v[52:55], v[166:169], v[182:185], v[52:55]
	v_mfma_f32_16x16x32_bf16 v[48:51], v[174:177], v[182:185], v[48:51]
	v_mfma_f32_16x16x32_bf16 v[36:39], v[166:169], v[190:193], v[36:39]
	v_mfma_f32_16x16x32_bf16 v[32:35], v[174:177], v[190:193], v[32:35]
	v_mfma_f32_16x16x32_bf16 v[20:23], v[166:169], v[198:201], v[20:23]
	v_mfma_f32_16x16x32_bf16 v[16:19], v[174:177], v[198:201], v[16:19]
	v_mfma_f32_16x16x32_bf16 v[4:7], v[166:169], v[206:209], v[4:7]
	v_mfma_f32_16x16x32_bf16 v[0:3], v[174:177], v[206:209], v[0:3]
	v_mfma_f32_16x16x32_bf16 v[52:55], v[170:173], v[186:189], v[52:55]
	v_mfma_f32_16x16x32_bf16 v[48:51], v[178:181], v[186:189], v[48:51]
	v_mfma_f32_16x16x32_bf16 v[36:39], v[170:173], v[194:197], v[36:39]
	v_mfma_f32_16x16x32_bf16 v[32:35], v[178:181], v[194:197], v[32:35]
	v_mfma_f32_16x16x32_bf16 v[20:23], v[170:173], v[202:205], v[20:23]
	v_mfma_f32_16x16x32_bf16 v[16:19], v[178:181], v[202:205], v[16:19]
	v_mfma_f32_16x16x32_bf16 v[4:7], v[170:173], v[210:213], v[4:7]
	v_mfma_f32_16x16x32_bf16 v[0:3], v[178:181], v[210:213], v[0:3]
	s_setprio 0
	s_barrier
	s_add_i32 s48, 0, 0x18000
	s_add_i32 s49, 0, 0x1c000
	v_add_u32_e32 v162, s48, v149
	v_add_u32_e32 v178, s49, v149
	ds_read_b128 v[144:147], v162
	ds_read_b128 v[154:157], v162 offset:1024
	ds_read_b128 v[158:161], v162 offset:2048
	ds_read_b128 v[162:165], v162 offset:3072
	ds_read_b128 v[166:169], v178
	ds_read_b128 v[170:173], v178 offset:1024
	ds_read_b128 v[174:177], v178 offset:2048
	ds_read_b128 v[178:181], v178 offset:3072
	s_add_u32 s20, s20, 0xb0000
	s_addc_u32 s21, s21, 0
	s_mov_b32 m0, s33
	v_lshl_add_u64 v[222:223], s[20:21], 0, v[128:129]
	ds_read_b128 v[182:185], v153 offset:32768
	ds_read_b128 v[186:189], v153 offset:33792
	ds_read_b128 v[190:193], v153 offset:34816
	ds_read_b128 v[194:197], v153 offset:35840
	ds_read_b128 v[198:201], v153 offset:36864
	ds_read_b128 v[202:205], v153 offset:37888
	ds_read_b128 v[206:209], v153 offset:38912
	ds_read_b128 v[210:213], v153 offset:39936
	global_load_lds_dwordx4 v[222:223], off
	v_lshl_add_u64 v[222:223], s[20:21], 0, v[132:133]
	s_mov_b32 m0, s34
	s_nop 0
	global_load_lds_dwordx4 v[222:223], off
	s_waitcnt vmcnt(8)
	s_waitcnt lgkmcnt(0)
	s_barrier
	s_setprio 1
	v_mfma_f32_16x16x32_bf16 v[124:127], v[144:147], v[182:185], v[124:127]
	v_mfma_f32_16x16x32_bf16 v[120:123], v[158:161], v[182:185], v[120:123]
	v_mfma_f32_16x16x32_bf16 v[108:111], v[144:147], v[190:193], v[108:111]
	v_mfma_f32_16x16x32_bf16 v[104:107], v[158:161], v[190:193], v[104:107]
	v_mfma_f32_16x16x32_bf16 v[92:95], v[144:147], v[198:201], v[92:95]
	v_mfma_f32_16x16x32_bf16 v[88:91], v[158:161], v[198:201], v[88:91]
	v_mfma_f32_16x16x32_bf16 v[76:79], v[144:147], v[206:209], v[76:79]
	v_mfma_f32_16x16x32_bf16 v[72:75], v[158:161], v[206:209], v[72:75]
	v_mfma_f32_16x16x32_bf16 v[124:127], v[154:157], v[186:189], v[124:127]
	v_mfma_f32_16x16x32_bf16 v[120:123], v[162:165], v[186:189], v[120:123]
	v_mfma_f32_16x16x32_bf16 v[108:111], v[154:157], v[194:197], v[108:111]
	v_mfma_f32_16x16x32_bf16 v[104:107], v[162:165], v[194:197], v[104:107]
	v_mfma_f32_16x16x32_bf16 v[92:95], v[154:157], v[202:205], v[92:95]
	v_mfma_f32_16x16x32_bf16 v[88:91], v[162:165], v[202:205], v[88:91]
	v_mfma_f32_16x16x32_bf16 v[76:79], v[154:157], v[210:213], v[76:79]
	v_mfma_f32_16x16x32_bf16 v[72:75], v[162:165], v[210:213], v[72:75]
	v_mfma_f32_16x16x32_bf16 v[116:119], v[166:169], v[182:185], v[116:119]
	v_mfma_f32_16x16x32_bf16 v[112:115], v[174:177], v[182:185], v[112:115]
	v_mfma_f32_16x16x32_bf16 v[100:103], v[166:169], v[190:193], v[100:103]
	v_mfma_f32_16x16x32_bf16 v[96:99], v[174:177], v[190:193], v[96:99]
	v_mfma_f32_16x16x32_bf16 v[84:87], v[166:169], v[198:201], v[84:87]
	v_mfma_f32_16x16x32_bf16 v[80:83], v[174:177], v[198:201], v[80:83]
	v_mfma_f32_16x16x32_bf16 v[68:71], v[166:169], v[206:209], v[68:71]
	v_mfma_f32_16x16x32_bf16 v[64:67], v[174:177], v[206:209], v[64:67]
	v_mfma_f32_16x16x32_bf16 v[116:119], v[170:173], v[186:189], v[116:119]
	v_mfma_f32_16x16x32_bf16 v[112:115], v[178:181], v[186:189], v[112:115]
	v_mfma_f32_16x16x32_bf16 v[100:103], v[170:173], v[194:197], v[100:103]
	v_mfma_f32_16x16x32_bf16 v[96:99], v[178:181], v[194:197], v[96:99]
	v_mfma_f32_16x16x32_bf16 v[84:87], v[170:173], v[202:205], v[84:87]
	v_mfma_f32_16x16x32_bf16 v[80:83], v[178:181], v[202:205], v[80:83]
	v_mfma_f32_16x16x32_bf16 v[68:71], v[170:173], v[210:213], v[68:71]
	v_mfma_f32_16x16x32_bf16 v[64:67], v[178:181], v[210:213], v[64:67]
	s_setprio 0
	s_barrier
; #define PG8_STAGE(bufoff, gbase, voff) do { _Pragma("unroll") for (int _i = 0; _i < 2; ++_i) \
;         __builtin_amdgcn_global_load_lds((const unsigned*)((const char*)(gbase) + (voff)[_i]), (LAS unsigned*)(lds + (bufoff) + ldsw + _i * 8192), 16, 0, 0); } while (0)
; #define PG8_LDA(dst, b, h) do { _Pragma("unroll") for (int m = 0; m < 4; ++m) _Pragma("unroll") for (int k = 0; k < 2; ++k) dst[m][k] = *(const LAS bf16x8*)(lds + PG8_SA(b, h) + aoff + m * 2048 + k * 1024); } while (0)
; #define PG8_MMA(ai, bj, At, Bt) do { __builtin_amdgcn_s_setprio(1); _Pragma("unroll") for (int m = 0; m < 4; ++m) _Pragma("unroll") for (int n = 0; n < 2; ++n) _Pragma("unroll") for (int k = 0; k < 2; ++k) \
;         acc[ai][bj][m][n] = __builtin_amdgcn_mfma_f32_16x16x32_bf16(Bt[n][k], At[m][k], acc[ai][bj][m][n], 0, 0, 0); __builtin_amdgcn_s_setprio(0); } while (0)
; #define PG8_WAIT_V(n) asm volatile("s_waitcnt vmcnt(" #n ")" ::: "memory")
; #define PG8_WAIT_L(n) asm volatile("s_waitcnt lgkmcnt(" #n ")" ::: "memory")
; #define PG8_BAR __builtin_amdgcn_s_barrier()
; #define PG8_SCHED __builtin_amdgcn_sched_barrier(0)
;     DI void pre(Pre& pr, const pg8::Unit& u, int wr, int fr) const { load_rows(pr, ssq, u, wr, fr); }
;     DI void pre(Pre& pr, const pg8::Unit& u, int wr, int fr) const { load_rows(pr, ssq, u, wr, fr); }
; template <class Epi, class Sched>
; DI void gemm_phase(LAS unsigned char* lds, const Gemm g, const Sched& S, const Epi& E) {
;     ...
;             PG8_LDA(At, 1, 1); PG8_STAGE(PG8_SB(1, 0), b3, voffB); PG8_STAGE(PG8_SB(1, 1), b3 + hstepB, voffB); PG8_STAGE(PG8_SA(1, 0), a3, voffA);
;             PG8_WAIT_V(8); PG8_WAIT_L(0); PG8_BAR; PG8_MMA(1, 0, At, B0); PG8_MMA(1, 1, At, B1); PG8_BAR; PG8_SCHED;
;         }
;         if (wr == 0) PG8_BAR;
;         E(acc, cur, wr, wc, fr, fq, pre);
;         if (!has_next) break;
	s_add_i32 s20, s48, s27
	v_lshl_add_u64 v[214:215], v[214:215], 0, s[10:11]
	s_mov_b32 m0, s20
	ds_read_b128 v[182:185], v153 offset:49152
	ds_read_b128 v[186:189], v153 offset:50176
	ds_read_b128 v[190:193], v153 offset:51200
	ds_read_b128 v[194:197], v153 offset:52224
	ds_read_b128 v[198:201], v153 offset:53248
	ds_read_b128 v[202:205], v153 offset:54272
	ds_read_b128 v[206:209], v153 offset:55296
	ds_read_b128 v[210:213], v153 offset:56320
	global_load_lds_dwordx4 v[214:215], off
	s_add_i32 m0, s20, 0x2000
	s_add_u32 s18, s18, 0xb0080
	v_lshl_add_u64 v[214:215], v[216:217], 0, s[10:11]
	s_addc_u32 s19, s19, 0
	s_add_i32 s20, s49, s27
	global_load_lds_dwordx4 v[214:215], off
	v_lshl_add_u64 v[214:215], s[18:19], 0, v[130:131]
	s_mov_b32 m0, s20
	s_nop 0
	global_load_lds_dwordx4 v[214:215], off
	v_lshl_add_u64 v[214:215], s[18:19], 0, v[134:135]
	s_add_i32 m0, s20, 0x2000
	s_nop 0
	global_load_lds_dwordx4 v[214:215], off
	v_lshl_add_u64 v[214:215], v[218:219], 0, s[10:11]
	s_mov_b32 m0, s36
	s_nop 0
	global_load_lds_dwordx4 v[214:215], off
	v_lshl_add_u64 v[214:215], v[220:221], 0, s[10:11]
	s_mov_b32 m0, s37
	s_nop 0
	global_load_lds_dwordx4 v[214:215], off
	s_waitcnt vmcnt(8)
	s_waitcnt lgkmcnt(0)
	s_nop 0
	s_barrier
	s_setprio 1
	v_mfma_f32_16x16x32_bf16 v[60:63], v[144:147], v[182:185], v[60:63]
	v_mfma_f32_16x16x32_bf16 v[56:59], v[158:161], v[182:185], v[56:59]
	v_mfma_f32_16x16x32_bf16 v[44:47], v[144:147], v[190:193], v[44:47]
	v_mfma_f32_16x16x32_bf16 v[40:43], v[158:161], v[190:193], v[40:43]
	v_mfma_f32_16x16x32_bf16 v[28:31], v[144:147], v[198:201], v[28:31]
	v_mfma_f32_16x16x32_bf16 v[24:27], v[158:161], v[198:201], v[24:27]
	v_mfma_f32_16x16x32_bf16 v[12:15], v[144:147], v[206:209], v[12:15]
	v_mfma_f32_16x16x32_bf16 v[8:11], v[158:161], v[206:209], v[8:11]
	v_mfma_f32_16x16x32_bf16 v[60:63], v[154:157], v[186:189], v[60:63]
	v_mfma_f32_16x16x32_bf16 v[56:59], v[162:165], v[186:189], v[56:59]
	v_mfma_f32_16x16x32_bf16 v[44:47], v[154:157], v[194:197], v[44:47]
	v_mfma_f32_16x16x32_bf16 v[40:43], v[162:165], v[194:197], v[40:43]
	v_mfma_f32_16x16x32_bf16 v[28:31], v[154:157], v[202:205], v[28:31]
	v_mfma_f32_16x16x32_bf16 v[24:27], v[162:165], v[202:205], v[24:27]
	v_mfma_f32_16x16x32_bf16 v[12:15], v[154:157], v[210:213], v[12:15]
	v_mfma_f32_16x16x32_bf16 v[8:11], v[162:165], v[210:213], v[8:11]
	v_mfma_f32_16x16x32_bf16 v[52:55], v[166:169], v[182:185], v[52:55]
	v_mfma_f32_16x16x32_bf16 v[48:51], v[174:177], v[182:185], v[48:51]
	v_mfma_f32_16x16x32_bf16 v[36:39], v[166:169], v[190:193], v[36:39]
	v_mfma_f32_16x16x32_bf16 v[32:35], v[174:177], v[190:193], v[32:35]
	v_mfma_f32_16x16x32_bf16 v[20:23], v[166:169], v[198:201], v[20:23]
	v_mfma_f32_16x16x32_bf16 v[16:19], v[174:177], v[198:201], v[16:19]
	v_mfma_f32_16x16x32_bf16 v[4:7], v[166:169], v[206:209], v[4:7]
	v_mfma_f32_16x16x32_bf16 v[0:3], v[174:177], v[206:209], v[0:3]
	v_mfma_f32_16x16x32_bf16 v[52:55], v[170:173], v[186:189], v[52:55]
	v_mfma_f32_16x16x32_bf16 v[48:51], v[178:181], v[186:189], v[48:51]
	v_mfma_f32_16x16x32_bf16 v[36:39], v[170:173], v[194:197], v[36:39]
	v_mfma_f32_16x16x32_bf16 v[32:35], v[178:181], v[194:197], v[32:35]
	v_mfma_f32_16x16x32_bf16 v[20:23], v[170:173], v[202:205], v[20:23]
	v_mfma_f32_16x16x32_bf16 v[16:19], v[178:181], v[202:205], v[16:19]
	v_mfma_f32_16x16x32_bf16 v[4:7], v[170:173], v[210:213], v[4:7]
	v_mfma_f32_16x16x32_bf16 v[0:3], v[178:181], v[210:213], v[0:3]
	s_setprio 0
	s_barrier
	s_add_i32 s47, s47, 2
	s_add_u32 s16, s16, 0x100
	s_addc_u32 s17, s17, 0
	s_add_u32 s45, s45, 0x100
	s_addc_u32 s46, s46, 0
	s_cmp_gt_u32 s47, 41
	s_cbranch_scc0 .LBB0_1331
	s_mov_b32 s99, 1
	s_and_b64 vcc, exec, s[12:13]
	s_cbranch_vccz .LBB0_1334
	s_barrier
